# priority: s_setprio 0/1 toggle after every 4th MFMA of each 16-MFMA cluster in the GEMM K-loops
# baseline (speedup 1.0000x reference)
; #define PG8_STAGE(bufoff, gbase, voff) do { _Pragma("unroll") for (int _i = 0; _i < 2; ++_i) \
;         __builtin_amdgcn_global_load_lds((const unsigned*)((const char*)(gbase) + (voff)[_i]), (PG8_LAS unsigned*)(lds + (bufoff) + ldsw + _i * 8192), 16, 0, 0); } while (0)
; #define PG8_LDA(dst, b, h) do { _Pragma("unroll") for (int m = 0; m < 4; ++m) _Pragma("unroll") for (int k = 0; k < 2; ++k) dst[m][k] = *(const PG8_LAS bf16x8*)(lds + PG8_SA(b, h) + aoff + m * 2048 + k * 1024); } while (0)
; #define PG8_LDB(dst, b, h) do { _Pragma("unroll") for (int n = 0; n < 2; ++n) _Pragma("unroll") for (int k = 0; k < 2; ++k) dst[n][k] = *(const PG8_LAS bf16x8*)(lds + PG8_SB(b, h) + boff + n * 2048 + k * 1024); } while (0)
; #define PG8_MMA(ai, bj, At, Bt) do { __builtin_amdgcn_s_setprio(1); _Pragma("unroll") for (int m = 0; m < 4; ++m) _Pragma("unroll") for (int n = 0; n < 2; ++n) _Pragma("unroll") for (int k = 0; k < 2; ++k) \
;         acc[ai][bj][m][n] = __builtin_amdgcn_mfma_f32_16x16x32_bf16(Bt[n][k], At[m][k], acc[ai][bj][m][n], 0, 0, 0); __builtin_amdgcn_s_setprio(0); } while (0)
; #define PG8_WAIT_V(n) asm volatile("s_waitcnt vmcnt(" #n ")" ::: "memory")
; #define PG8_WAIT_L(n) asm volatile("s_waitcnt lgkmcnt(" #n ")" ::: "memory")
; template <class Epi, class Sched, bool ALIGN_EPI, bool SP2, int KC>
; __device__ __forceinline__ void gemm_phase(PG8_LAS unsigned char* lds, const Gemm g, const Sched& S, const Epi& E, const int tid) {
;     ...
;             const bool last = (t == nt - 2);
;             const char* a1 = cA + (size_t)(t + 1) * kstep;
;             const char* a2 = last ? nA : cA + (size_t)(t + 2) * kstep; const char* b2 = last ? nB : cB + (size_t)(t + 2) * kstep;
;             const char* a3 = a2 + kstep; const char* b3 = b2 + kstep;
;             if (last && has_next) S.a_ready(nxt);
;             if constexpr (SP2) {
;             PG8_LDB(B0, 0, 0); PG8_LDB(B1, 0, 1); PG8_SCHED; PG8_LDA(At, 0, 0); PG8_STAGE(PG8_SA(1, 1), a1 + hstep, voffA);
;             PG8_WAIT_V(8); PG8_WAIT_L(0); PG8_BAR; PG8_MMA(0, 0, At, B0); PG8_MMA(0, 1, At, B1); PG8_BAR; PG8_SCHED;
;             PG8_LDA(At, 0, 1); PG8_STAGE(PG8_SB(0, 0), b2, voffB); PG8_STAGE(PG8_SB(0, 1), b2 + hstep, voffB); PG8_STAGE(PG8_SA(0, 0), a2, voffA);
;             PG8_WAIT_V(8); PG8_WAIT_L(0); PG8_BAR; PG8_MMA(1, 0, At, B0); PG8_MMA(1, 1, At, B1); PG8_BAR; PG8_SCHED;
.LBB0_44:
	s_add_u32 s24, s22, 0xfffc0080
	s_addc_u32 s25, s23, -1
	s_add_i32 s43, 0, 0x10000
	s_cmp_eq_u32 s42, 12
	s_cselect_b32 s27, s17, s25
	s_cselect_b32 s26, s38, s24
	v_add_u32_e32 v138, s43, v145
	s_cselect_b32 s25, s15, s41
	s_cselect_b32 s24, s39, s40
	s_add_i32 s46, 0, 0x14000
	ds_read_b128 v[148:151], v138
	ds_read_b128 v[152:155], v138 offset:1024
	ds_read_b128 v[156:159], v138 offset:2048
	ds_read_b128 v[160:163], v138 offset:3072
	v_add_u32_e32 v138, s46, v145
	ds_read_b128 v[174:177], v138
	ds_read_b128 v[178:181], v138 offset:1024
	ds_read_b128 v[182:185], v138 offset:2048
	ds_read_b128 v[186:189], v138 offset:3072
	v_lshl_add_u64 v[138:139], s[22:23], 0, v[134:135]
	s_add_i32 m0, s29, 0xc000
	ds_read_b128 v[190:193], v147
	ds_read_b128 v[194:197], v147 offset:1024
	ds_read_b128 v[198:201], v147 offset:2048
	ds_read_b128 v[202:205], v147 offset:3072
	ds_read_b128 v[206:209], v147 offset:4096
	ds_read_b128 v[210:213], v147 offset:5120
	ds_read_b128 v[214:217], v147 offset:6144
	ds_read_b128 v[218:221], v147 offset:7168
	global_load_lds_dwordx4 v[138:139], off
	v_lshl_add_u64 v[138:139], s[22:23], 0, v[136:137]
	s_add_i32 m0, s29, 0xe000
	s_nop 0
	global_load_lds_dwordx4 v[138:139], off
	s_waitcnt vmcnt(8)
	s_waitcnt lgkmcnt(0)
	s_barrier
	s_setprio 1
	s_waitcnt lgkmcnt(0)
	v_mfma_f32_16x16x32_bf16 v[124:127], v[148:151], v[190:193], v[124:127]
	v_mfma_f32_16x16x32_bf16 v[120:123], v[156:159], v[190:193], v[120:123]
	v_mfma_f32_16x16x32_bf16 v[116:119], v[148:151], v[198:201], v[116:119]
	v_mfma_f32_16x16x32_bf16 v[108:111], v[156:159], v[198:201], v[108:111]
	s_setprio 0
	s_setprio 1
	v_mfma_f32_16x16x32_bf16 v[100:103], v[148:151], v[206:209], v[100:103]
	v_mfma_f32_16x16x32_bf16 v[92:95], v[156:159], v[206:209], v[92:95]
	v_mfma_f32_16x16x32_bf16 v[80:83], v[148:151], v[214:217], v[80:83]
	v_mfma_f32_16x16x32_bf16 v[72:75], v[156:159], v[214:217], v[72:75]
	s_setprio 0
	s_setprio 1
	v_mfma_f32_16x16x32_bf16 v[124:127], v[152:155], v[194:197], v[124:127]
	v_mfma_f32_16x16x32_bf16 v[120:123], v[160:163], v[194:197], v[120:123]
	v_mfma_f32_16x16x32_bf16 v[116:119], v[152:155], v[202:205], v[116:119]
	v_mfma_f32_16x16x32_bf16 v[108:111], v[160:163], v[202:205], v[108:111]
	s_setprio 0
	s_setprio 1
	v_mfma_f32_16x16x32_bf16 v[100:103], v[152:155], v[210:213], v[100:103]
	v_mfma_f32_16x16x32_bf16 v[92:95], v[160:163], v[210:213], v[92:95]
	v_mfma_f32_16x16x32_bf16 v[80:83], v[152:155], v[218:221], v[80:83]
	v_mfma_f32_16x16x32_bf16 v[72:75], v[160:163], v[218:221], v[72:75]
	s_setprio 0
	s_setprio 1
	v_mfma_f32_16x16x32_bf16 v[112:115], v[174:177], v[190:193], v[112:115]
	v_mfma_f32_16x16x32_bf16 v[104:107], v[182:185], v[190:193], v[104:107]
	v_mfma_f32_16x16x32_bf16 v[96:99], v[174:177], v[198:201], v[96:99]
	v_mfma_f32_16x16x32_bf16 v[88:91], v[182:185], v[198:201], v[88:91]
	s_setprio 0
	s_setprio 1
	v_mfma_f32_16x16x32_bf16 v[84:87], v[174:177], v[206:209], v[84:87]
	v_mfma_f32_16x16x32_bf16 v[76:79], v[182:185], v[206:209], v[76:79]
	v_mfma_f32_16x16x32_bf16 v[68:71], v[174:177], v[214:217], v[68:71]
	v_mfma_f32_16x16x32_bf16 v[64:67], v[182:185], v[214:217], v[64:67]
	s_setprio 0
	s_setprio 1
	v_mfma_f32_16x16x32_bf16 v[112:115], v[178:181], v[194:197], v[112:115]
	v_mfma_f32_16x16x32_bf16 v[104:107], v[186:189], v[194:197], v[104:107]
	v_mfma_f32_16x16x32_bf16 v[96:99], v[178:181], v[202:205], v[96:99]
	v_mfma_f32_16x16x32_bf16 v[88:91], v[186:189], v[202:205], v[88:91]
	s_setprio 0
	s_setprio 1
	v_mfma_f32_16x16x32_bf16 v[84:87], v[178:181], v[210:213], v[84:87]
	v_mfma_f32_16x16x32_bf16 v[76:79], v[186:189], v[210:213], v[76:79]
	v_mfma_f32_16x16x32_bf16 v[68:71], v[178:181], v[218:221], v[68:71]
	v_mfma_f32_16x16x32_bf16 v[64:67], v[186:189], v[218:221], v[64:67]
	s_setprio 0
	s_barrier
	s_add_i32 s43, s43, s28
	v_lshl_add_u64 v[138:139], s[24:25], 0, v[164:165]
	s_mov_b32 m0, s43
	ds_read_b128 v[190:193], v147 offset:16384
	ds_read_b128 v[194:197], v147 offset:17408
	ds_read_b128 v[198:201], v147 offset:18432
	ds_read_b128 v[202:205], v147 offset:19456
	ds_read_b128 v[206:209], v147 offset:20480
	ds_read_b128 v[210:213], v147 offset:21504
	ds_read_b128 v[214:217], v147 offset:22528
	ds_read_b128 v[218:221], v147 offset:23552
	global_load_lds_dwordx4 v[138:139], off
	s_add_i32 m0, s43, 0x2000
	s_add_u32 s44, s24, 0x40000
	v_lshl_add_u64 v[222:223], s[24:25], 0, v[128:129]
	s_addc_u32 s45, s25, 0
	s_add_i32 s43, s46, s28
	global_load_lds_dwordx4 v[222:223], off
	v_lshl_add_u64 v[234:235], s[44:45], 0, v[164:165]
	s_mov_b32 m0, s43
	v_lshl_add_u64 v[236:237], s[26:27], 0, v[130:131]
	global_load_lds_dwordx4 v[234:235], off
	v_lshl_add_u64 v[234:235], s[44:45], 0, v[128:129]
	s_add_i32 m0, s43, 0x2000
	s_nop 0
	global_load_lds_dwordx4 v[234:235], off
	v_lshl_add_u64 v[234:235], s[26:27], 0, v[132:133]
	s_mov_b32 m0, s29
	s_nop 0
	global_load_lds_dwordx4 v[234:235], off
	s_mov_b32 m0, s30
	s_nop 0
	global_load_lds_dwordx4 v[236:237], off
	s_waitcnt vmcnt(8)
	s_waitcnt lgkmcnt(0)
	s_barrier
; #define PG8_STAGE(bufoff, gbase, voff) do { _Pragma("unroll") for (int _i = 0; _i < 2; ++_i) \
;         __builtin_amdgcn_global_load_lds((const unsigned*)((const char*)(gbase) + (voff)[_i]), (PG8_LAS unsigned*)(lds + (bufoff) + ldsw + _i * 8192), 16, 0, 0); } while (0)
; #define PG8_LDA(dst, b, h) do { _Pragma("unroll") for (int m = 0; m < 4; ++m) _Pragma("unroll") for (int k = 0; k < 2; ++k) dst[m][k] = *(const PG8_LAS bf16x8*)(lds + PG8_SA(b, h) + aoff + m * 2048 + k * 1024); } while (0)
; #define PG8_LDB(dst, b, h) do { _Pragma("unroll") for (int n = 0; n < 2; ++n) _Pragma("unroll") for (int k = 0; k < 2; ++k) dst[n][k] = *(const PG8_LAS bf16x8*)(lds + PG8_SB(b, h) + boff + n * 2048 + k * 1024); } while (0)
; #define PG8_MMA(ai, bj, At, Bt) do { __builtin_amdgcn_s_setprio(1); _Pragma("unroll") for (int m = 0; m < 4; ++m) _Pragma("unroll") for (int n = 0; n < 2; ++n) _Pragma("unroll") for (int k = 0; k < 2; ++k) \
;         acc[ai][bj][m][n] = __builtin_amdgcn_mfma_f32_16x16x32_bf16(Bt[n][k], At[m][k], acc[ai][bj][m][n], 0, 0, 0); __builtin_amdgcn_s_setprio(0); } while (0)
; #define PG8_WAIT_V(n) asm volatile("s_waitcnt vmcnt(" #n ")" ::: "memory")
; #define PG8_WAIT_L(n) asm volatile("s_waitcnt lgkmcnt(" #n ")" ::: "memory")
; #define PG8_BAR __builtin_amdgcn_s_barrier()
; #define PG8_SCHED __builtin_amdgcn_sched_barrier(0)
; template <class Epi, class Sched, bool ALIGN_EPI, bool SP2, int KC>
; __device__ __forceinline__ void gemm_phase(PG8_LAS unsigned char* lds, const Gemm g, const Sched& S, const Epi& E, const int tid) {
;     ...
;             PG8_WAIT_V(8); PG8_WAIT_L(0); PG8_BAR; PG8_MMA(1, 0, At, B0); PG8_MMA(1, 1, At, B1); PG8_BAR; PG8_SCHED;
;             PG8_LDB(B0, 1, 0); PG8_LDB(B1, 1, 1); PG8_SCHED; PG8_LDA(At, 1, 0); PG8_STAGE(PG8_SA(0, 1), a2 + hstep, voffA);
;             PG8_WAIT_V(8); PG8_WAIT_L(0); PG8_BAR; PG8_MMA(0, 0, At, B0); PG8_MMA(0, 1, At, B1); PG8_BAR; PG8_SCHED;
	s_setprio 1
	s_waitcnt lgkmcnt(0)
	v_mfma_f32_16x16x32_bf16 v[60:63], v[148:151], v[190:193], v[60:63]
	v_mfma_f32_16x16x32_bf16 v[56:59], v[156:159], v[190:193], v[56:59]
	v_mfma_f32_16x16x32_bf16 v[52:55], v[148:151], v[198:201], v[52:55]
	v_mfma_f32_16x16x32_bf16 v[44:47], v[156:159], v[198:201], v[44:47]
	s_setprio 0
	s_setprio 1
	v_mfma_f32_16x16x32_bf16 v[36:39], v[148:151], v[206:209], v[36:39]
	v_mfma_f32_16x16x32_bf16 v[28:31], v[156:159], v[206:209], v[28:31]
	v_mfma_f32_16x16x32_bf16 v[20:23], v[148:151], v[214:217], v[20:23]
	v_mfma_f32_16x16x32_bf16 v[12:15], v[156:159], v[214:217], v[12:15]
	s_setprio 0
	s_setprio 1
	v_mfma_f32_16x16x32_bf16 v[60:63], v[152:155], v[194:197], v[60:63]
	v_mfma_f32_16x16x32_bf16 v[56:59], v[160:163], v[194:197], v[56:59]
	v_mfma_f32_16x16x32_bf16 v[52:55], v[152:155], v[202:205], v[52:55]
	v_mfma_f32_16x16x32_bf16 v[44:47], v[160:163], v[202:205], v[44:47]
	s_setprio 0
	s_setprio 1
	v_mfma_f32_16x16x32_bf16 v[36:39], v[152:155], v[210:213], v[36:39]
	v_mfma_f32_16x16x32_bf16 v[28:31], v[160:163], v[210:213], v[28:31]
	v_mfma_f32_16x16x32_bf16 v[20:23], v[152:155], v[218:221], v[20:23]
	v_mfma_f32_16x16x32_bf16 v[12:15], v[160:163], v[218:221], v[12:15]
	s_setprio 0
	s_setprio 1
	v_mfma_f32_16x16x32_bf16 v[48:51], v[174:177], v[190:193], v[48:51]
	v_mfma_f32_16x16x32_bf16 v[40:43], v[182:185], v[190:193], v[40:43]
	v_mfma_f32_16x16x32_bf16 v[32:35], v[174:177], v[198:201], v[32:35]
	v_mfma_f32_16x16x32_bf16 v[24:27], v[182:185], v[198:201], v[24:27]
	s_setprio 0
	s_setprio 1
	v_mfma_f32_16x16x32_bf16 v[16:19], v[174:177], v[206:209], v[16:19]
	v_mfma_f32_16x16x32_bf16 v[8:11], v[182:185], v[206:209], v[8:11]
	v_mfma_f32_16x16x32_bf16 v[4:7], v[174:177], v[214:217], v[4:7]
	v_mfma_f32_16x16x32_bf16 v[0:3], v[182:185], v[214:217], v[0:3]
	s_setprio 0
	s_setprio 1
	v_mfma_f32_16x16x32_bf16 v[48:51], v[178:181], v[194:197], v[48:51]
	v_mfma_f32_16x16x32_bf16 v[40:43], v[186:189], v[194:197], v[40:43]
	v_mfma_f32_16x16x32_bf16 v[32:35], v[178:181], v[202:205], v[32:35]
	v_mfma_f32_16x16x32_bf16 v[24:27], v[186:189], v[202:205], v[24:27]
	s_setprio 0
	s_setprio 1
	v_mfma_f32_16x16x32_bf16 v[16:19], v[178:181], v[210:213], v[16:19]
	v_mfma_f32_16x16x32_bf16 v[8:11], v[186:189], v[210:213], v[8:11]
	v_mfma_f32_16x16x32_bf16 v[4:7], v[178:181], v[218:221], v[4:7]
	v_mfma_f32_16x16x32_bf16 v[0:3], v[186:189], v[218:221], v[0:3]
	s_setprio 0
	s_barrier
	s_add_i32 s43, 0, 0x18000
	s_add_i32 s44, 0, 0x1c000
	v_add_u32_e32 v160, s43, v145
	v_add_u32_e32 v171, s44, v145
	ds_read_b128 v[148:151], v160
	ds_read_b128 v[152:155], v160 offset:1024
	ds_read_b128 v[156:159], v160 offset:2048
	ds_read_b128 v[160:163], v160 offset:3072
	ds_read_b128 v[174:177], v171
	ds_read_b128 v[178:181], v171 offset:1024
	ds_read_b128 v[182:185], v171 offset:2048
	ds_read_b128 v[186:189], v171 offset:3072
	s_add_u32 s26, s26, 0x40000
	s_addc_u32 s27, s27, 0
	s_mov_b32 m0, s31
	v_lshl_add_u64 v[238:239], s[26:27], 0, v[132:133]
	ds_read_b128 v[190:193], v147 offset:32768
	ds_read_b128 v[194:197], v147 offset:33792
	ds_read_b128 v[198:201], v147 offset:34816
	ds_read_b128 v[202:205], v147 offset:35840
	ds_read_b128 v[206:209], v147 offset:36864
	ds_read_b128 v[210:213], v147 offset:37888
	ds_read_b128 v[214:217], v147 offset:38912
	ds_read_b128 v[218:221], v147 offset:39936
	global_load_lds_dwordx4 v[238:239], off
	v_lshl_add_u64 v[238:239], s[26:27], 0, v[130:131]
	s_mov_b32 m0, s34
	s_nop 0
	global_load_lds_dwordx4 v[238:239], off
	s_waitcnt vmcnt(8)
	s_waitcnt lgkmcnt(0)
	s_barrier
	s_setprio 1
	s_waitcnt lgkmcnt(0)
	v_mfma_f32_16x16x32_bf16 v[124:127], v[148:151], v[190:193], v[124:127]
	v_mfma_f32_16x16x32_bf16 v[120:123], v[156:159], v[190:193], v[120:123]
	v_mfma_f32_16x16x32_bf16 v[116:119], v[148:151], v[198:201], v[116:119]
	v_mfma_f32_16x16x32_bf16 v[108:111], v[156:159], v[198:201], v[108:111]
	s_setprio 0
	s_setprio 1
	v_mfma_f32_16x16x32_bf16 v[100:103], v[148:151], v[206:209], v[100:103]
	v_mfma_f32_16x16x32_bf16 v[92:95], v[156:159], v[206:209], v[92:95]
	v_mfma_f32_16x16x32_bf16 v[80:83], v[148:151], v[214:217], v[80:83]
	v_mfma_f32_16x16x32_bf16 v[72:75], v[156:159], v[214:217], v[72:75]
	s_setprio 0
	s_setprio 1
	v_mfma_f32_16x16x32_bf16 v[124:127], v[152:155], v[194:197], v[124:127]
	v_mfma_f32_16x16x32_bf16 v[120:123], v[160:163], v[194:197], v[120:123]
	v_mfma_f32_16x16x32_bf16 v[116:119], v[152:155], v[202:205], v[116:119]
	v_mfma_f32_16x16x32_bf16 v[108:111], v[160:163], v[202:205], v[108:111]
	s_setprio 0
	s_setprio 1
	v_mfma_f32_16x16x32_bf16 v[100:103], v[152:155], v[210:213], v[100:103]
	v_mfma_f32_16x16x32_bf16 v[92:95], v[160:163], v[210:213], v[92:95]
	v_mfma_f32_16x16x32_bf16 v[80:83], v[152:155], v[218:221], v[80:83]
	v_mfma_f32_16x16x32_bf16 v[72:75], v[160:163], v[218:221], v[72:75]
	s_setprio 0
	s_setprio 1
	v_mfma_f32_16x16x32_bf16 v[112:115], v[174:177], v[190:193], v[112:115]
	v_mfma_f32_16x16x32_bf16 v[104:107], v[182:185], v[190:193], v[104:107]
	v_mfma_f32_16x16x32_bf16 v[96:99], v[174:177], v[198:201], v[96:99]
	v_mfma_f32_16x16x32_bf16 v[88:91], v[182:185], v[198:201], v[88:91]
	s_setprio 0
	s_setprio 1
	v_mfma_f32_16x16x32_bf16 v[84:87], v[174:177], v[206:209], v[84:87]
	v_mfma_f32_16x16x32_bf16 v[76:79], v[182:185], v[206:209], v[76:79]
	v_mfma_f32_16x16x32_bf16 v[68:71], v[174:177], v[214:217], v[68:71]
	v_mfma_f32_16x16x32_bf16 v[64:67], v[182:185], v[214:217], v[64:67]
	s_setprio 0
	s_setprio 1
	v_mfma_f32_16x16x32_bf16 v[112:115], v[178:181], v[194:197], v[112:115]
	v_mfma_f32_16x16x32_bf16 v[104:107], v[186:189], v[194:197], v[104:107]
	v_mfma_f32_16x16x32_bf16 v[96:99], v[178:181], v[202:205], v[96:99]
	v_mfma_f32_16x16x32_bf16 v[88:91], v[186:189], v[202:205], v[88:91]
	s_setprio 0
	s_setprio 1
	v_mfma_f32_16x16x32_bf16 v[84:87], v[178:181], v[210:213], v[84:87]
	v_mfma_f32_16x16x32_bf16 v[76:79], v[186:189], v[210:213], v[76:79]
	v_mfma_f32_16x16x32_bf16 v[68:71], v[178:181], v[218:221], v[68:71]
	v_mfma_f32_16x16x32_bf16 v[64:67], v[186:189], v[218:221], v[64:67]
	s_setprio 0
	s_barrier
; #define PG8_STAGE(bufoff, gbase, voff) do { _Pragma("unroll") for (int _i = 0; _i < 2; ++_i) \
;         __builtin_amdgcn_global_load_lds((const unsigned*)((const char*)(gbase) + (voff)[_i]), (PG8_LAS unsigned*)(lds + (bufoff) + ldsw + _i * 8192), 16, 0, 0); } while (0)
; #define PG8_LDA(dst, b, h) do { _Pragma("unroll") for (int m = 0; m < 4; ++m) _Pragma("unroll") for (int k = 0; k < 2; ++k) dst[m][k] = *(const PG8_LAS bf16x8*)(lds + PG8_SA(b, h) + aoff + m * 2048 + k * 1024); } while (0)
; #define PG8_MMA(ai, bj, At, Bt) do { __builtin_amdgcn_s_setprio(1); _Pragma("unroll") for (int m = 0; m < 4; ++m) _Pragma("unroll") for (int n = 0; n < 2; ++n) _Pragma("unroll") for (int k = 0; k < 2; ++k) \
;         acc[ai][bj][m][n] = __builtin_amdgcn_mfma_f32_16x16x32_bf16(Bt[n][k], At[m][k], acc[ai][bj][m][n], 0, 0, 0); __builtin_amdgcn_s_setprio(0); } while (0)
; #define PG8_WAIT_V(n) asm volatile("s_waitcnt vmcnt(" #n ")" ::: "memory")
; #define PG8_WAIT_L(n) asm volatile("s_waitcnt lgkmcnt(" #n ")" ::: "memory")
; #define PG8_BAR __builtin_amdgcn_s_barrier()
; #define PG8_SCHED __builtin_amdgcn_sched_barrier(0)
; template <class Epi, class Sched, bool ALIGN_EPI, bool SP2, int KC>
; __device__ __forceinline__ void gemm_phase(PG8_LAS unsigned char* lds, const Gemm g, const Sched& S, const Epi& E, const int tid) {
;     ...
;             PG8_LDA(At, 1, 1); PG8_STAGE(PG8_SB(1, 0), b3, voffB); PG8_STAGE(PG8_SB(1, 1), b3 + hstep, voffB); PG8_STAGE(PG8_SA(1, 0), a3, voffA);
;             PG8_WAIT_V(8); PG8_WAIT_L(0); PG8_BAR; PG8_MMA(1, 0, At, B0); PG8_MMA(1, 1, At, B1); PG8_BAR; PG8_SCHED;
;     ...
;         if constexpr (ALIGN_EPI) { if (wr == 0) PG8_BAR; }
	s_add_i32 s26, s43, s28
	v_lshl_add_u64 v[138:139], v[138:139], 0, s[86:87]
	s_mov_b32 m0, s26
	ds_read_b128 v[190:193], v147 offset:49152
	ds_read_b128 v[194:197], v147 offset:50176
	ds_read_b128 v[198:201], v147 offset:51200
	ds_read_b128 v[202:205], v147 offset:52224
	ds_read_b128 v[206:209], v147 offset:53248
	ds_read_b128 v[210:213], v147 offset:54272
	ds_read_b128 v[214:217], v147 offset:55296
	ds_read_b128 v[218:221], v147 offset:56320
	global_load_lds_dwordx4 v[138:139], off
	s_add_i32 m0, s26, 0x2000
	s_add_u32 s24, s24, 0x40080
	v_lshl_add_u64 v[138:139], v[222:223], 0, s[86:87]
	s_addc_u32 s25, s25, 0
	s_add_i32 s26, s44, s28
	global_load_lds_dwordx4 v[138:139], off
	v_lshl_add_u64 v[138:139], s[24:25], 0, v[164:165]
	s_mov_b32 m0, s26
	s_nop 0
	global_load_lds_dwordx4 v[138:139], off
	v_lshl_add_u64 v[138:139], s[24:25], 0, v[128:129]
	s_add_i32 m0, s26, 0x2000
	s_nop 0
	global_load_lds_dwordx4 v[138:139], off
	v_lshl_add_u64 v[138:139], v[234:235], 0, s[86:87]
	s_mov_b32 m0, s35
	s_nop 0
	global_load_lds_dwordx4 v[138:139], off
	v_lshl_add_u64 v[138:139], v[236:237], 0, s[86:87]
	s_mov_b32 m0, s36
	s_nop 0
	global_load_lds_dwordx4 v[138:139], off
	s_waitcnt vmcnt(8)
	s_waitcnt lgkmcnt(0)
	s_barrier
	s_setprio 1
	s_waitcnt lgkmcnt(0)
	v_mfma_f32_16x16x32_bf16 v[60:63], v[148:151], v[190:193], v[60:63]
	v_mfma_f32_16x16x32_bf16 v[56:59], v[156:159], v[190:193], v[56:59]
	v_mfma_f32_16x16x32_bf16 v[52:55], v[148:151], v[198:201], v[52:55]
	v_mfma_f32_16x16x32_bf16 v[44:47], v[156:159], v[198:201], v[44:47]
	s_setprio 0
	s_setprio 1
	v_mfma_f32_16x16x32_bf16 v[36:39], v[148:151], v[206:209], v[36:39]
	v_mfma_f32_16x16x32_bf16 v[28:31], v[156:159], v[206:209], v[28:31]
	v_mfma_f32_16x16x32_bf16 v[20:23], v[148:151], v[214:217], v[20:23]
	v_mfma_f32_16x16x32_bf16 v[12:15], v[156:159], v[214:217], v[12:15]
	s_setprio 0
	s_setprio 1
	v_mfma_f32_16x16x32_bf16 v[60:63], v[152:155], v[194:197], v[60:63]
	v_mfma_f32_16x16x32_bf16 v[56:59], v[160:163], v[194:197], v[56:59]
	v_mfma_f32_16x16x32_bf16 v[52:55], v[152:155], v[202:205], v[52:55]
	v_mfma_f32_16x16x32_bf16 v[44:47], v[160:163], v[202:205], v[44:47]
	s_setprio 0
	s_setprio 1
	v_mfma_f32_16x16x32_bf16 v[36:39], v[152:155], v[210:213], v[36:39]
	v_mfma_f32_16x16x32_bf16 v[28:31], v[160:163], v[210:213], v[28:31]
	v_mfma_f32_16x16x32_bf16 v[20:23], v[152:155], v[218:221], v[20:23]
	v_mfma_f32_16x16x32_bf16 v[12:15], v[160:163], v[218:221], v[12:15]
	s_setprio 0
	s_setprio 1
	v_mfma_f32_16x16x32_bf16 v[48:51], v[174:177], v[190:193], v[48:51]
	v_mfma_f32_16x16x32_bf16 v[40:43], v[182:185], v[190:193], v[40:43]
	v_mfma_f32_16x16x32_bf16 v[32:35], v[174:177], v[198:201], v[32:35]
	v_mfma_f32_16x16x32_bf16 v[24:27], v[182:185], v[198:201], v[24:27]
	s_setprio 0
	s_setprio 1
	v_mfma_f32_16x16x32_bf16 v[16:19], v[174:177], v[206:209], v[16:19]
	v_mfma_f32_16x16x32_bf16 v[8:11], v[182:185], v[206:209], v[8:11]
	v_mfma_f32_16x16x32_bf16 v[4:7], v[174:177], v[214:217], v[4:7]
	v_mfma_f32_16x16x32_bf16 v[0:3], v[182:185], v[214:217], v[0:3]
	s_setprio 0
	s_setprio 1
	v_mfma_f32_16x16x32_bf16 v[48:51], v[178:181], v[194:197], v[48:51]
	v_mfma_f32_16x16x32_bf16 v[40:43], v[186:189], v[194:197], v[40:43]
	v_mfma_f32_16x16x32_bf16 v[32:35], v[178:181], v[202:205], v[32:35]
	v_mfma_f32_16x16x32_bf16 v[24:27], v[186:189], v[202:205], v[24:27]
	s_setprio 0
	s_setprio 1
	v_mfma_f32_16x16x32_bf16 v[16:19], v[178:181], v[210:213], v[16:19]
	v_mfma_f32_16x16x32_bf16 v[8:11], v[186:189], v[210:213], v[8:11]
	v_mfma_f32_16x16x32_bf16 v[4:7], v[178:181], v[218:221], v[4:7]
	v_mfma_f32_16x16x32_bf16 v[0:3], v[186:189], v[218:221], v[0:3]
	s_setprio 0
	s_barrier
	s_add_i32 s42, s42, 2
	s_add_u32 s22, s22, 0x100
	s_addc_u32 s23, s23, 0
	s_add_u32 s40, s40, 0x100
	s_addc_u32 s41, s41, 0
	s_cmp_gt_u32 s42, 13
	s_cbranch_scc0 .LBB0_44
	s_and_b64 vcc, exec, s[10:11]
	s_cbranch_vccz .LBB0_47
	s_barrier

; #define PG8_STAGE(bufoff, gbase, voff) do { _Pragma("unroll") for (int _i = 0; _i < 2; ++_i) \
;         __builtin_amdgcn_global_load_lds((const unsigned*)((const char*)(gbase) + (voff)[_i]), (PG8_LAS unsigned*)(lds + (bufoff) + ldsw + _i * 8192), 16, 0, 0); } while (0)
; #define PG8_LDA(dst, b, h) do { _Pragma("unroll") for (int m = 0; m < 4; ++m) _Pragma("unroll") for (int k = 0; k < 2; ++k) dst[m][k] = *(const PG8_LAS bf16x8*)(lds + PG8_SA(b, h) + aoff + m * 2048 + k * 1024); } while (0)
; #define PG8_LDB(dst, b, h) do { _Pragma("unroll") for (int n = 0; n < 2; ++n) _Pragma("unroll") for (int k = 0; k < 2; ++k) dst[n][k] = *(const PG8_LAS bf16x8*)(lds + PG8_SB(b, h) + boff + n * 2048 + k * 1024); } while (0)
; #define PG8_MMA(ai, bj, At, Bt) do { __builtin_amdgcn_s_setprio(1); _Pragma("unroll") for (int m = 0; m < 4; ++m) _Pragma("unroll") for (int n = 0; n < 2; ++n) _Pragma("unroll") for (int k = 0; k < 2; ++k) \
;         acc[ai][bj][m][n] = __builtin_amdgcn_mfma_f32_16x16x32_bf16(Bt[n][k], At[m][k], acc[ai][bj][m][n], 0, 0, 0); __builtin_amdgcn_s_setprio(0); } while (0)
; #define PG8_WAIT_V(n) asm volatile("s_waitcnt vmcnt(" #n ")" ::: "memory")
; #define PG8_WAIT_L(n) asm volatile("s_waitcnt lgkmcnt(" #n ")" ::: "memory")
; template <class Epi, class Sched, bool ALIGN_EPI, bool SP2, int KC>
; __device__ __forceinline__ void gemm_phase(PG8_LAS unsigned char* lds, const Gemm g, const Sched& S, const Epi& E, const int tid) {
;     ...
;             const bool last = (t == nt - 2);
;             const char* a1 = cA + (size_t)(t + 1) * kstep;
;             const char* a2 = last ? nA : cA + (size_t)(t + 2) * kstep; const char* b2 = last ? nB : cB + (size_t)(t + 2) * kstep;
;             const char* a3 = a2 + kstep; const char* b3 = b2 + kstep;
;             if (last && has_next) S.a_ready(nxt);
;             if constexpr (SP2) {
;             PG8_LDB(B0, 0, 0); PG8_LDB(B1, 0, 1); PG8_SCHED; PG8_LDA(At, 0, 0); PG8_STAGE(PG8_SA(1, 1), a1 + hstep, voffA);
;             PG8_WAIT_V(8); PG8_WAIT_L(0); PG8_BAR; PG8_MMA(0, 0, At, B0); PG8_MMA(0, 1, At, B1); PG8_BAR; PG8_SCHED;
;             PG8_LDA(At, 0, 1); PG8_STAGE(PG8_SB(0, 0), b2, voffB); PG8_STAGE(PG8_SB(0, 1), b2 + hstep, voffB); PG8_STAGE(PG8_SA(0, 0), a2, voffA);
;             PG8_WAIT_V(8); PG8_WAIT_L(0); PG8_BAR; PG8_MMA(1, 0, At, B0); PG8_MMA(1, 1, At, B1); PG8_BAR; PG8_SCHED;
.LBB0_66:
	s_add_u32 s24, s22, 0xfffc0080
	s_addc_u32 s25, s23, -1
	s_add_i32 s43, 0, 0x10000
	s_cmp_eq_u32 s42, 12
	s_cselect_b32 s27, s17, s25
	s_cselect_b32 s26, s38, s24
	v_add_u32_e32 v138, s43, v141
	s_cselect_b32 s25, s15, s41
	s_cselect_b32 s24, s39, s40
	s_add_i32 s46, 0, 0x14000
	ds_read_b128 v[146:149], v138
	ds_read_b128 v[150:153], v138 offset:1024
	ds_read_b128 v[154:157], v138 offset:2048
	ds_read_b128 v[158:161], v138 offset:3072
	v_add_u32_e32 v138, s46, v141
	ds_read_b128 v[174:177], v138
	ds_read_b128 v[178:181], v138 offset:1024
	ds_read_b128 v[182:185], v138 offset:2048
	ds_read_b128 v[186:189], v138 offset:3072
	v_lshl_add_u64 v[138:139], s[22:23], 0, v[134:135]
	s_add_i32 m0, s29, 0xc000
	ds_read_b128 v[190:193], v142
	ds_read_b128 v[194:197], v142 offset:1024
	ds_read_b128 v[198:201], v142 offset:2048
	ds_read_b128 v[202:205], v142 offset:3072
	ds_read_b128 v[206:209], v142 offset:4096
	ds_read_b128 v[210:213], v142 offset:5120
	ds_read_b128 v[214:217], v142 offset:6144
	ds_read_b128 v[218:221], v142 offset:7168
	global_load_lds_dwordx4 v[138:139], off
	v_lshl_add_u64 v[138:139], s[22:23], 0, v[136:137]
	s_add_i32 m0, s29, 0xe000
	s_nop 0
	global_load_lds_dwordx4 v[138:139], off
	s_waitcnt vmcnt(8)
	s_waitcnt lgkmcnt(0)
	s_barrier
	s_setprio 1
	s_waitcnt lgkmcnt(0)
	v_mfma_f32_16x16x32_bf16 v[124:127], v[146:149], v[190:193], v[124:127]
	v_mfma_f32_16x16x32_bf16 v[120:123], v[154:157], v[190:193], v[120:123]
	v_mfma_f32_16x16x32_bf16 v[116:119], v[146:149], v[198:201], v[116:119]
	v_mfma_f32_16x16x32_bf16 v[108:111], v[154:157], v[198:201], v[108:111]
	s_setprio 0
	s_setprio 1
	v_mfma_f32_16x16x32_bf16 v[100:103], v[146:149], v[206:209], v[100:103]
	v_mfma_f32_16x16x32_bf16 v[92:95], v[154:157], v[206:209], v[92:95]
	v_mfma_f32_16x16x32_bf16 v[80:83], v[146:149], v[214:217], v[80:83]
	v_mfma_f32_16x16x32_bf16 v[72:75], v[154:157], v[214:217], v[72:75]
	s_setprio 0
	s_setprio 1
	v_mfma_f32_16x16x32_bf16 v[124:127], v[150:153], v[194:197], v[124:127]
	v_mfma_f32_16x16x32_bf16 v[120:123], v[158:161], v[194:197], v[120:123]
	v_mfma_f32_16x16x32_bf16 v[116:119], v[150:153], v[202:205], v[116:119]
	v_mfma_f32_16x16x32_bf16 v[108:111], v[158:161], v[202:205], v[108:111]
	s_setprio 0
	s_setprio 1
	v_mfma_f32_16x16x32_bf16 v[100:103], v[150:153], v[210:213], v[100:103]
	v_mfma_f32_16x16x32_bf16 v[92:95], v[158:161], v[210:213], v[92:95]
	v_mfma_f32_16x16x32_bf16 v[80:83], v[150:153], v[218:221], v[80:83]
	v_mfma_f32_16x16x32_bf16 v[72:75], v[158:161], v[218:221], v[72:75]
	s_setprio 0
	s_setprio 1
	v_mfma_f32_16x16x32_bf16 v[112:115], v[174:177], v[190:193], v[112:115]
	v_mfma_f32_16x16x32_bf16 v[104:107], v[182:185], v[190:193], v[104:107]
	v_mfma_f32_16x16x32_bf16 v[96:99], v[174:177], v[198:201], v[96:99]
	v_mfma_f32_16x16x32_bf16 v[88:91], v[182:185], v[198:201], v[88:91]
	s_setprio 0
	s_setprio 1
	v_mfma_f32_16x16x32_bf16 v[84:87], v[174:177], v[206:209], v[84:87]
	v_mfma_f32_16x16x32_bf16 v[76:79], v[182:185], v[206:209], v[76:79]
	v_mfma_f32_16x16x32_bf16 v[68:71], v[174:177], v[214:217], v[68:71]
	v_mfma_f32_16x16x32_bf16 v[64:67], v[182:185], v[214:217], v[64:67]
	s_setprio 0
	s_setprio 1
	v_mfma_f32_16x16x32_bf16 v[112:115], v[178:181], v[194:197], v[112:115]
	v_mfma_f32_16x16x32_bf16 v[104:107], v[186:189], v[194:197], v[104:107]
	v_mfma_f32_16x16x32_bf16 v[96:99], v[178:181], v[202:205], v[96:99]
	v_mfma_f32_16x16x32_bf16 v[88:91], v[186:189], v[202:205], v[88:91]
	s_setprio 0
	s_setprio 1
	v_mfma_f32_16x16x32_bf16 v[84:87], v[178:181], v[210:213], v[84:87]
	v_mfma_f32_16x16x32_bf16 v[76:79], v[186:189], v[210:213], v[76:79]
	v_mfma_f32_16x16x32_bf16 v[68:71], v[178:181], v[218:221], v[68:71]
	v_mfma_f32_16x16x32_bf16 v[64:67], v[186:189], v[218:221], v[64:67]
	s_setprio 0
	s_barrier
	s_add_i32 s43, s43, s28
	v_lshl_add_u64 v[138:139], s[24:25], 0, v[164:165]
	s_mov_b32 m0, s43
	ds_read_b128 v[190:193], v142 offset:16384
	ds_read_b128 v[194:197], v142 offset:17408
	ds_read_b128 v[198:201], v142 offset:18432
	ds_read_b128 v[202:205], v142 offset:19456
	ds_read_b128 v[206:209], v142 offset:20480
	ds_read_b128 v[210:213], v142 offset:21504
	ds_read_b128 v[214:217], v142 offset:22528
	ds_read_b128 v[218:221], v142 offset:23552
	global_load_lds_dwordx4 v[138:139], off
	s_add_i32 m0, s43, 0x2000
	s_add_u32 s44, s24, 0x40000
	v_lshl_add_u64 v[162:163], s[24:25], 0, v[128:129]
	s_addc_u32 s45, s25, 0
	s_add_i32 s43, s46, s28
	global_load_lds_dwordx4 v[162:163], off
	v_lshl_add_u64 v[222:223], s[44:45], 0, v[164:165]
	s_mov_b32 m0, s43
	v_lshl_add_u64 v[234:235], s[26:27], 0, v[130:131]
	global_load_lds_dwordx4 v[222:223], off
	v_lshl_add_u64 v[222:223], s[44:45], 0, v[128:129]
	s_add_i32 m0, s43, 0x2000
	s_nop 0
	global_load_lds_dwordx4 v[222:223], off
	v_lshl_add_u64 v[222:223], s[26:27], 0, v[132:133]
	s_mov_b32 m0, s29
	s_nop 0
	global_load_lds_dwordx4 v[222:223], off
	s_mov_b32 m0, s30
	s_nop 0
	global_load_lds_dwordx4 v[234:235], off
	s_waitcnt vmcnt(8)
	s_waitcnt lgkmcnt(0)
	s_barrier
; #define PG8_STAGE(bufoff, gbase, voff) do { _Pragma("unroll") for (int _i = 0; _i < 2; ++_i) \
;         __builtin_amdgcn_global_load_lds((const unsigned*)((const char*)(gbase) + (voff)[_i]), (PG8_LAS unsigned*)(lds + (bufoff) + ldsw + _i * 8192), 16, 0, 0); } while (0)
; #define PG8_LDA(dst, b, h) do { _Pragma("unroll") for (int m = 0; m < 4; ++m) _Pragma("unroll") for (int k = 0; k < 2; ++k) dst[m][k] = *(const PG8_LAS bf16x8*)(lds + PG8_SA(b, h) + aoff + m * 2048 + k * 1024); } while (0)
; #define PG8_LDB(dst, b, h) do { _Pragma("unroll") for (int n = 0; n < 2; ++n) _Pragma("unroll") for (int k = 0; k < 2; ++k) dst[n][k] = *(const PG8_LAS bf16x8*)(lds + PG8_SB(b, h) + boff + n * 2048 + k * 1024); } while (0)
; #define PG8_MMA(ai, bj, At, Bt) do { __builtin_amdgcn_s_setprio(1); _Pragma("unroll") for (int m = 0; m < 4; ++m) _Pragma("unroll") for (int n = 0; n < 2; ++n) _Pragma("unroll") for (int k = 0; k < 2; ++k) \
;         acc[ai][bj][m][n] = __builtin_amdgcn_mfma_f32_16x16x32_bf16(Bt[n][k], At[m][k], acc[ai][bj][m][n], 0, 0, 0); __builtin_amdgcn_s_setprio(0); } while (0)
; #define PG8_WAIT_V(n) asm volatile("s_waitcnt vmcnt(" #n ")" ::: "memory")
; #define PG8_WAIT_L(n) asm volatile("s_waitcnt lgkmcnt(" #n ")" ::: "memory")
; #define PG8_BAR __builtin_amdgcn_s_barrier()
; #define PG8_SCHED __builtin_amdgcn_sched_barrier(0)
; template <class Epi, class Sched, bool ALIGN_EPI, bool SP2, int KC>
; __device__ __forceinline__ void gemm_phase(PG8_LAS unsigned char* lds, const Gemm g, const Sched& S, const Epi& E, const int tid) {
;     ...
;             PG8_WAIT_V(8); PG8_WAIT_L(0); PG8_BAR; PG8_MMA(1, 0, At, B0); PG8_MMA(1, 1, At, B1); PG8_BAR; PG8_SCHED;
;             PG8_LDB(B0, 1, 0); PG8_LDB(B1, 1, 1); PG8_SCHED; PG8_LDA(At, 1, 0); PG8_STAGE(PG8_SA(0, 1), a2 + hstep, voffA);
;             PG8_WAIT_V(8); PG8_WAIT_L(0); PG8_BAR; PG8_MMA(0, 0, At, B0); PG8_MMA(0, 1, At, B1); PG8_BAR; PG8_SCHED;
	s_setprio 1
	s_waitcnt lgkmcnt(0)
	v_mfma_f32_16x16x32_bf16 v[60:63], v[146:149], v[190:193], v[60:63]
	v_mfma_f32_16x16x32_bf16 v[56:59], v[154:157], v[190:193], v[56:59]
	v_mfma_f32_16x16x32_bf16 v[52:55], v[146:149], v[198:201], v[52:55]
	v_mfma_f32_16x16x32_bf16 v[44:47], v[154:157], v[198:201], v[44:47]
	s_setprio 0
	s_setprio 1
	v_mfma_f32_16x16x32_bf16 v[36:39], v[146:149], v[206:209], v[36:39]
	v_mfma_f32_16x16x32_bf16 v[28:31], v[154:157], v[206:209], v[28:31]
	v_mfma_f32_16x16x32_bf16 v[20:23], v[146:149], v[214:217], v[20:23]
	v_mfma_f32_16x16x32_bf16 v[12:15], v[154:157], v[214:217], v[12:15]
	s_setprio 0
	s_setprio 1
	v_mfma_f32_16x16x32_bf16 v[60:63], v[150:153], v[194:197], v[60:63]
	v_mfma_f32_16x16x32_bf16 v[56:59], v[158:161], v[194:197], v[56:59]
	v_mfma_f32_16x16x32_bf16 v[52:55], v[150:153], v[202:205], v[52:55]
	v_mfma_f32_16x16x32_bf16 v[44:47], v[158:161], v[202:205], v[44:47]
	s_setprio 0
	s_setprio 1
	v_mfma_f32_16x16x32_bf16 v[36:39], v[150:153], v[210:213], v[36:39]
	v_mfma_f32_16x16x32_bf16 v[28:31], v[158:161], v[210:213], v[28:31]
	v_mfma_f32_16x16x32_bf16 v[20:23], v[150:153], v[218:221], v[20:23]
	v_mfma_f32_16x16x32_bf16 v[12:15], v[158:161], v[218:221], v[12:15]
	s_setprio 0
	s_setprio 1
	v_mfma_f32_16x16x32_bf16 v[48:51], v[174:177], v[190:193], v[48:51]
	v_mfma_f32_16x16x32_bf16 v[40:43], v[182:185], v[190:193], v[40:43]
	v_mfma_f32_16x16x32_bf16 v[32:35], v[174:177], v[198:201], v[32:35]
	v_mfma_f32_16x16x32_bf16 v[24:27], v[182:185], v[198:201], v[24:27]
	s_setprio 0
	s_setprio 1
	v_mfma_f32_16x16x32_bf16 v[16:19], v[174:177], v[206:209], v[16:19]
	v_mfma_f32_16x16x32_bf16 v[8:11], v[182:185], v[206:209], v[8:11]
	v_mfma_f32_16x16x32_bf16 v[4:7], v[174:177], v[214:217], v[4:7]
	v_mfma_f32_16x16x32_bf16 v[0:3], v[182:185], v[214:217], v[0:3]
	s_setprio 0
	s_setprio 1
	v_mfma_f32_16x16x32_bf16 v[48:51], v[178:181], v[194:197], v[48:51]
	v_mfma_f32_16x16x32_bf16 v[40:43], v[186:189], v[194:197], v[40:43]
	v_mfma_f32_16x16x32_bf16 v[32:35], v[178:181], v[202:205], v[32:35]
	v_mfma_f32_16x16x32_bf16 v[24:27], v[186:189], v[202:205], v[24:27]
	s_setprio 0
	s_setprio 1
	v_mfma_f32_16x16x32_bf16 v[16:19], v[178:181], v[210:213], v[16:19]
	v_mfma_f32_16x16x32_bf16 v[8:11], v[186:189], v[210:213], v[8:11]
	v_mfma_f32_16x16x32_bf16 v[4:7], v[178:181], v[218:221], v[4:7]
	v_mfma_f32_16x16x32_bf16 v[0:3], v[186:189], v[218:221], v[0:3]
	s_setprio 0
	s_barrier
	s_add_i32 s43, 0, 0x18000
	v_add_u32_e32 v143, s43, v141
	s_add_i32 s44, 0, 0x1c000
	ds_read_b128 v[146:149], v143
	ds_read_b128 v[150:153], v143 offset:1024
	ds_read_b128 v[154:157], v143 offset:2048
	ds_read_b128 v[158:161], v143 offset:3072
	v_add_u32_e32 v143, s44, v141
	ds_read_b128 v[174:177], v143
	ds_read_b128 v[178:181], v143 offset:1024
	ds_read_b128 v[182:185], v143 offset:2048
	ds_read_b128 v[186:189], v143 offset:3072
	s_add_u32 s26, s26, 0x40000
	s_addc_u32 s27, s27, 0
	s_mov_b32 m0, s31
	v_lshl_add_u64 v[236:237], s[26:27], 0, v[132:133]
	ds_read_b128 v[190:193], v142 offset:32768
	ds_read_b128 v[194:197], v142 offset:33792
	ds_read_b128 v[198:201], v142 offset:34816
	ds_read_b128 v[202:205], v142 offset:35840
	ds_read_b128 v[206:209], v142 offset:36864
	ds_read_b128 v[210:213], v142 offset:37888
	ds_read_b128 v[214:217], v142 offset:38912
	ds_read_b128 v[218:221], v142 offset:39936
	global_load_lds_dwordx4 v[236:237], off
	v_lshl_add_u64 v[236:237], s[26:27], 0, v[130:131]
	s_mov_b32 m0, s34
	s_nop 0
	global_load_lds_dwordx4 v[236:237], off
	s_waitcnt vmcnt(8)
	s_waitcnt lgkmcnt(0)
	s_barrier
	s_setprio 1
	s_waitcnt lgkmcnt(0)
	v_mfma_f32_16x16x32_bf16 v[124:127], v[146:149], v[190:193], v[124:127]
	v_mfma_f32_16x16x32_bf16 v[120:123], v[154:157], v[190:193], v[120:123]
	v_mfma_f32_16x16x32_bf16 v[116:119], v[146:149], v[198:201], v[116:119]
	v_mfma_f32_16x16x32_bf16 v[108:111], v[154:157], v[198:201], v[108:111]
	s_setprio 0
	s_setprio 1
	v_mfma_f32_16x16x32_bf16 v[100:103], v[146:149], v[206:209], v[100:103]
	v_mfma_f32_16x16x32_bf16 v[92:95], v[154:157], v[206:209], v[92:95]
	v_mfma_f32_16x16x32_bf16 v[80:83], v[146:149], v[214:217], v[80:83]
	v_mfma_f32_16x16x32_bf16 v[72:75], v[154:157], v[214:217], v[72:75]
	s_setprio 0
	s_setprio 1
	v_mfma_f32_16x16x32_bf16 v[124:127], v[150:153], v[194:197], v[124:127]
	v_mfma_f32_16x16x32_bf16 v[120:123], v[158:161], v[194:197], v[120:123]
	v_mfma_f32_16x16x32_bf16 v[116:119], v[150:153], v[202:205], v[116:119]
	v_mfma_f32_16x16x32_bf16 v[108:111], v[158:161], v[202:205], v[108:111]
	s_setprio 0
	s_setprio 1
	v_mfma_f32_16x16x32_bf16 v[100:103], v[150:153], v[210:213], v[100:103]
	v_mfma_f32_16x16x32_bf16 v[92:95], v[158:161], v[210:213], v[92:95]
	v_mfma_f32_16x16x32_bf16 v[80:83], v[150:153], v[218:221], v[80:83]
	v_mfma_f32_16x16x32_bf16 v[72:75], v[158:161], v[218:221], v[72:75]
	s_setprio 0
	s_setprio 1
	v_mfma_f32_16x16x32_bf16 v[112:115], v[174:177], v[190:193], v[112:115]
	v_mfma_f32_16x16x32_bf16 v[104:107], v[182:185], v[190:193], v[104:107]
	v_mfma_f32_16x16x32_bf16 v[96:99], v[174:177], v[198:201], v[96:99]
	v_mfma_f32_16x16x32_bf16 v[88:91], v[182:185], v[198:201], v[88:91]
	s_setprio 0
	s_setprio 1
	v_mfma_f32_16x16x32_bf16 v[84:87], v[174:177], v[206:209], v[84:87]
	v_mfma_f32_16x16x32_bf16 v[76:79], v[182:185], v[206:209], v[76:79]
	v_mfma_f32_16x16x32_bf16 v[68:71], v[174:177], v[214:217], v[68:71]
	v_mfma_f32_16x16x32_bf16 v[64:67], v[182:185], v[214:217], v[64:67]
	s_setprio 0
	s_setprio 1
	v_mfma_f32_16x16x32_bf16 v[112:115], v[178:181], v[194:197], v[112:115]
	v_mfma_f32_16x16x32_bf16 v[104:107], v[186:189], v[194:197], v[104:107]
	v_mfma_f32_16x16x32_bf16 v[96:99], v[178:181], v[202:205], v[96:99]
	v_mfma_f32_16x16x32_bf16 v[88:91], v[186:189], v[202:205], v[88:91]
	s_setprio 0
	s_setprio 1
	v_mfma_f32_16x16x32_bf16 v[84:87], v[178:181], v[210:213], v[84:87]
	v_mfma_f32_16x16x32_bf16 v[76:79], v[186:189], v[210:213], v[76:79]
	v_mfma_f32_16x16x32_bf16 v[68:71], v[178:181], v[218:221], v[68:71]
	v_mfma_f32_16x16x32_bf16 v[64:67], v[186:189], v[218:221], v[64:67]
	s_setprio 0
	s_barrier
; #define PG8_STAGE(bufoff, gbase, voff) do { _Pragma("unroll") for (int _i = 0; _i < 2; ++_i) \
;         __builtin_amdgcn_global_load_lds((const unsigned*)((const char*)(gbase) + (voff)[_i]), (PG8_LAS unsigned*)(lds + (bufoff) + ldsw + _i * 8192), 16, 0, 0); } while (0)
; #define PG8_LDA(dst, b, h) do { _Pragma("unroll") for (int m = 0; m < 4; ++m) _Pragma("unroll") for (int k = 0; k < 2; ++k) dst[m][k] = *(const PG8_LAS bf16x8*)(lds + PG8_SA(b, h) + aoff + m * 2048 + k * 1024); } while (0)
; #define PG8_MMA(ai, bj, At, Bt) do { __builtin_amdgcn_s_setprio(1); _Pragma("unroll") for (int m = 0; m < 4; ++m) _Pragma("unroll") for (int n = 0; n < 2; ++n) _Pragma("unroll") for (int k = 0; k < 2; ++k) \
;         acc[ai][bj][m][n] = __builtin_amdgcn_mfma_f32_16x16x32_bf16(Bt[n][k], At[m][k], acc[ai][bj][m][n], 0, 0, 0); __builtin_amdgcn_s_setprio(0); } while (0)
; #define PG8_WAIT_V(n) asm volatile("s_waitcnt vmcnt(" #n ")" ::: "memory")
; #define PG8_WAIT_L(n) asm volatile("s_waitcnt lgkmcnt(" #n ")" ::: "memory")
; #define PG8_BAR __builtin_amdgcn_s_barrier()
; #define PG8_SCHED __builtin_amdgcn_sched_barrier(0)
; template <class Epi, class Sched, bool ALIGN_EPI, bool SP2, int KC>
; __device__ __forceinline__ void gemm_phase(PG8_LAS unsigned char* lds, const Gemm g, const Sched& S, const Epi& E, const int tid) {
;     ...
;             PG8_LDA(At, 1, 1); PG8_STAGE(PG8_SB(1, 0), b3, voffB); PG8_STAGE(PG8_SB(1, 1), b3 + hstep, voffB); PG8_STAGE(PG8_SA(1, 0), a3, voffA);
;             PG8_WAIT_V(8); PG8_WAIT_L(0); PG8_BAR; PG8_MMA(1, 0, At, B0); PG8_MMA(1, 1, At, B1); PG8_BAR; PG8_SCHED;
;     ...
;         if constexpr (ALIGN_EPI) { if (wr == 0) PG8_BAR; }
	s_add_i32 s26, s43, s28
	v_lshl_add_u64 v[138:139], v[138:139], 0, s[86:87]
	s_mov_b32 m0, s26
	ds_read_b128 v[190:193], v142 offset:49152
	ds_read_b128 v[194:197], v142 offset:50176
	ds_read_b128 v[198:201], v142 offset:51200
	ds_read_b128 v[202:205], v142 offset:52224
	ds_read_b128 v[206:209], v142 offset:53248
	ds_read_b128 v[210:213], v142 offset:54272
	ds_read_b128 v[214:217], v142 offset:55296
	ds_read_b128 v[218:221], v142 offset:56320
	global_load_lds_dwordx4 v[138:139], off
	s_add_i32 m0, s26, 0x2000
	s_add_u32 s24, s24, 0x40080
	v_lshl_add_u64 v[138:139], v[162:163], 0, s[86:87]
	s_addc_u32 s25, s25, 0
	s_add_i32 s26, s44, s28
	global_load_lds_dwordx4 v[138:139], off
	v_lshl_add_u64 v[138:139], s[24:25], 0, v[164:165]
	s_mov_b32 m0, s26
	s_nop 0
	global_load_lds_dwordx4 v[138:139], off
	v_lshl_add_u64 v[138:139], s[24:25], 0, v[128:129]
	s_add_i32 m0, s26, 0x2000
	s_nop 0
	global_load_lds_dwordx4 v[138:139], off
	v_lshl_add_u64 v[138:139], v[222:223], 0, s[86:87]
	s_mov_b32 m0, s35
	s_nop 0
	global_load_lds_dwordx4 v[138:139], off
	v_lshl_add_u64 v[138:139], v[234:235], 0, s[86:87]
	s_mov_b32 m0, s36
	s_nop 0
	global_load_lds_dwordx4 v[138:139], off
	s_waitcnt vmcnt(8)
	s_waitcnt lgkmcnt(0)
	s_barrier
	s_setprio 1
	s_waitcnt lgkmcnt(0)
	v_mfma_f32_16x16x32_bf16 v[60:63], v[146:149], v[190:193], v[60:63]
	v_mfma_f32_16x16x32_bf16 v[56:59], v[154:157], v[190:193], v[56:59]
	v_mfma_f32_16x16x32_bf16 v[52:55], v[146:149], v[198:201], v[52:55]
	v_mfma_f32_16x16x32_bf16 v[44:47], v[154:157], v[198:201], v[44:47]
	s_setprio 0
	s_setprio 1
	v_mfma_f32_16x16x32_bf16 v[36:39], v[146:149], v[206:209], v[36:39]
	v_mfma_f32_16x16x32_bf16 v[28:31], v[154:157], v[206:209], v[28:31]
	v_mfma_f32_16x16x32_bf16 v[20:23], v[146:149], v[214:217], v[20:23]
	v_mfma_f32_16x16x32_bf16 v[12:15], v[154:157], v[214:217], v[12:15]
	s_setprio 0
	s_setprio 1
	v_mfma_f32_16x16x32_bf16 v[60:63], v[150:153], v[194:197], v[60:63]
	v_mfma_f32_16x16x32_bf16 v[56:59], v[158:161], v[194:197], v[56:59]
	v_mfma_f32_16x16x32_bf16 v[52:55], v[150:153], v[202:205], v[52:55]
	v_mfma_f32_16x16x32_bf16 v[44:47], v[158:161], v[202:205], v[44:47]
	s_setprio 0
	s_setprio 1
	v_mfma_f32_16x16x32_bf16 v[36:39], v[150:153], v[210:213], v[36:39]
	v_mfma_f32_16x16x32_bf16 v[28:31], v[158:161], v[210:213], v[28:31]
	v_mfma_f32_16x16x32_bf16 v[20:23], v[150:153], v[218:221], v[20:23]
	v_mfma_f32_16x16x32_bf16 v[12:15], v[158:161], v[218:221], v[12:15]
	s_setprio 0
	s_setprio 1
	v_mfma_f32_16x16x32_bf16 v[48:51], v[174:177], v[190:193], v[48:51]
	v_mfma_f32_16x16x32_bf16 v[40:43], v[182:185], v[190:193], v[40:43]
	v_mfma_f32_16x16x32_bf16 v[32:35], v[174:177], v[198:201], v[32:35]
	v_mfma_f32_16x16x32_bf16 v[24:27], v[182:185], v[198:201], v[24:27]
	s_setprio 0
	s_setprio 1
	v_mfma_f32_16x16x32_bf16 v[16:19], v[174:177], v[206:209], v[16:19]
	v_mfma_f32_16x16x32_bf16 v[8:11], v[182:185], v[206:209], v[8:11]
	v_mfma_f32_16x16x32_bf16 v[4:7], v[174:177], v[214:217], v[4:7]
	v_mfma_f32_16x16x32_bf16 v[0:3], v[182:185], v[214:217], v[0:3]
	s_setprio 0
	s_setprio 1
	v_mfma_f32_16x16x32_bf16 v[48:51], v[178:181], v[194:197], v[48:51]
	v_mfma_f32_16x16x32_bf16 v[40:43], v[186:189], v[194:197], v[40:43]
	v_mfma_f32_16x16x32_bf16 v[32:35], v[178:181], v[202:205], v[32:35]
	v_mfma_f32_16x16x32_bf16 v[24:27], v[186:189], v[202:205], v[24:27]
	s_setprio 0
	s_setprio 1
	v_mfma_f32_16x16x32_bf16 v[16:19], v[178:181], v[210:213], v[16:19]
	v_mfma_f32_16x16x32_bf16 v[8:11], v[186:189], v[210:213], v[8:11]
	v_mfma_f32_16x16x32_bf16 v[4:7], v[178:181], v[218:221], v[4:7]
	v_mfma_f32_16x16x32_bf16 v[0:3], v[186:189], v[218:221], v[0:3]
	s_setprio 0
	s_barrier
	s_add_i32 s42, s42, 2
	s_add_u32 s22, s22, 0x100
	s_addc_u32 s23, s23, 0
	s_add_u32 s40, s40, 0x100
	s_addc_u32 s41, s41, 0
	s_cmp_gt_u32 s42, 13
	s_cbranch_scc0 .LBB0_66
	s_and_b64 vcc, exec, s[10:11]
	s_cbranch_vccz .LBB0_69
	s_barrier

; #define PG8_STAGE(bufoff, gbase, voff) do { _Pragma("unroll") for (int _i = 0; _i < 2; ++_i) \
;         __builtin_amdgcn_global_load_lds((const unsigned*)((const char*)(gbase) + (voff)[_i]), (PG8_LAS unsigned*)(lds + (bufoff) + ldsw + _i * 8192), 16, 0, 0); } while (0)
; #define PG8_LDA(dst, b, h) do { _Pragma("unroll") for (int m = 0; m < 4; ++m) _Pragma("unroll") for (int k = 0; k < 2; ++k) dst[m][k] = *(const PG8_LAS bf16x8*)(lds + PG8_SA(b, h) + aoff + m * 2048 + k * 1024); } while (0)
; #define PG8_LDB(dst, b, h) do { _Pragma("unroll") for (int n = 0; n < 2; ++n) _Pragma("unroll") for (int k = 0; k < 2; ++k) dst[n][k] = *(const PG8_LAS bf16x8*)(lds + PG8_SB(b, h) + boff + n * 2048 + k * 1024); } while (0)
; #define PG8_MMA(ai, bj, At, Bt) do { __builtin_amdgcn_s_setprio(1); _Pragma("unroll") for (int m = 0; m < 4; ++m) _Pragma("unroll") for (int n = 0; n < 2; ++n) _Pragma("unroll") for (int k = 0; k < 2; ++k) \
;         acc[ai][bj][m][n] = __builtin_amdgcn_mfma_f32_16x16x32_bf16(Bt[n][k], At[m][k], acc[ai][bj][m][n], 0, 0, 0); __builtin_amdgcn_s_setprio(0); } while (0)
; #define PG8_WAIT_V(n) asm volatile("s_waitcnt vmcnt(" #n ")" ::: "memory")
; #define PG8_WAIT_L(n) asm volatile("s_waitcnt lgkmcnt(" #n ")" ::: "memory")
; template <class Epi, class Sched, bool ALIGN_EPI, bool SP2, int KC>
; __device__ __forceinline__ void gemm_phase(PG8_LAS unsigned char* lds, const Gemm g, const Sched& S, const Epi& E, const int tid) {
;     ...
;             const bool last = (t == nt - 2);
;             const char* a1 = cA + (size_t)(t + 1) * kstep;
;             const char* a2 = last ? nA : cA + (size_t)(t + 2) * kstep; const char* b2 = last ? nB : cB + (size_t)(t + 2) * kstep;
;             const char* a3 = a2 + kstep; const char* b3 = b2 + kstep;
;             if (last && has_next) S.a_ready(nxt);
;             if constexpr (SP2) {
;             PG8_LDB(B0, 0, 0); PG8_LDB(B1, 0, 1); PG8_SCHED; PG8_LDA(At, 0, 0); PG8_STAGE(PG8_SA(1, 1), a1 + hstep, voffA);
;             PG8_WAIT_V(8); PG8_WAIT_L(0); PG8_BAR; PG8_MMA(0, 0, At, B0); PG8_MMA(0, 1, At, B1); PG8_BAR; PG8_SCHED;
;             PG8_LDA(At, 0, 1); PG8_STAGE(PG8_SB(0, 0), b2, voffB); PG8_STAGE(PG8_SB(0, 1), b2 + hstep, voffB); PG8_STAGE(PG8_SA(0, 0), a2, voffA);
;             PG8_WAIT_V(8); PG8_WAIT_L(0); PG8_BAR; PG8_MMA(1, 0, At, B0); PG8_MMA(1, 1, At, B1); PG8_BAR; PG8_SCHED;
.LBB0_92:
	s_add_u32 s26, s4, 0xfffc0080
	s_addc_u32 s27, s5, -1
	s_add_i32 s45, 0, 0x10000
	s_cmp_eq_u32 s44, 12
	s_cselect_b32 s29, s19, s27
	s_cselect_b32 s28, s40, s26
	s_cselect_b32 s27, s17, s43
	s_cselect_b32 s26, s41, s42
	s_add_i32 s48, 0, 0x14000
	v_add_u32_e32 v76, s45, v222
	v_add_u32_e32 v156, s48, v222
	ds_read_b128 v[64:67], v76
	ds_read_b128 v[68:71], v76 offset:1024
	ds_read_b128 v[72:75], v76 offset:2048
	ds_read_b128 v[76:79], v76 offset:3072
	ds_read_b128 v[144:147], v156
	ds_read_b128 v[148:151], v156 offset:1024
	ds_read_b128 v[152:155], v156 offset:2048
	ds_read_b128 v[156:159], v156 offset:3072
	v_lshl_add_u64 v[212:213], s[4:5], 0, v[176:177]
	s_add_i32 m0, s7, 0xc000
	ds_read_b128 v[180:183], v233
	ds_read_b128 v[184:187], v233 offset:1024
	ds_read_b128 v[188:191], v233 offset:2048
	ds_read_b128 v[192:195], v233 offset:3072
	ds_read_b128 v[196:199], v233 offset:4096
	ds_read_b128 v[200:203], v233 offset:5120
	ds_read_b128 v[204:207], v233 offset:6144
	ds_read_b128 v[208:211], v233 offset:7168
	global_load_lds_dwordx4 v[212:213], off
	v_lshl_add_u64 v[212:213], s[4:5], 0, v[178:179]
	s_add_i32 m0, s7, 0xe000
	s_nop 0
	global_load_lds_dwordx4 v[212:213], off
	s_waitcnt vmcnt(8)
	s_waitcnt lgkmcnt(0)
	s_barrier
	s_setprio 1
	s_waitcnt lgkmcnt(0)
	v_mfma_f32_16x16x32_bf16 v[140:143], v[64:67], v[180:183], v[140:143]
	v_mfma_f32_16x16x32_bf16 v[132:135], v[72:75], v[180:183], v[132:135]
	v_mfma_f32_16x16x32_bf16 v[124:127], v[64:67], v[188:191], v[124:127]
	v_mfma_f32_16x16x32_bf16 v[116:119], v[72:75], v[188:191], v[116:119]
	s_setprio 0
	s_setprio 1
	v_mfma_f32_16x16x32_bf16 v[108:111], v[64:67], v[196:199], v[108:111]
	v_mfma_f32_16x16x32_bf16 v[100:103], v[72:75], v[196:199], v[100:103]
	v_mfma_f32_16x16x32_bf16 v[92:95], v[64:67], v[204:207], v[92:95]
	v_mfma_f32_16x16x32_bf16 v[84:87], v[72:75], v[204:207], v[84:87]
	s_setprio 0
	s_setprio 1
	v_mfma_f32_16x16x32_bf16 v[140:143], v[68:71], v[184:187], v[140:143]
	v_mfma_f32_16x16x32_bf16 v[132:135], v[76:79], v[184:187], v[132:135]
	v_mfma_f32_16x16x32_bf16 v[124:127], v[68:71], v[192:195], v[124:127]
	v_mfma_f32_16x16x32_bf16 v[116:119], v[76:79], v[192:195], v[116:119]
	s_setprio 0
	s_setprio 1
	v_mfma_f32_16x16x32_bf16 v[108:111], v[68:71], v[200:203], v[108:111]
	v_mfma_f32_16x16x32_bf16 v[100:103], v[76:79], v[200:203], v[100:103]
	v_mfma_f32_16x16x32_bf16 v[92:95], v[68:71], v[208:211], v[92:95]
	v_mfma_f32_16x16x32_bf16 v[84:87], v[76:79], v[208:211], v[84:87]
	s_setprio 0
	s_setprio 1
	v_mfma_f32_16x16x32_bf16 v[136:139], v[144:147], v[180:183], v[136:139]
	v_mfma_f32_16x16x32_bf16 v[128:131], v[152:155], v[180:183], v[128:131]
	v_mfma_f32_16x16x32_bf16 v[120:123], v[144:147], v[188:191], v[120:123]
	v_mfma_f32_16x16x32_bf16 v[112:115], v[152:155], v[188:191], v[112:115]
	s_setprio 0
	s_setprio 1
	v_mfma_f32_16x16x32_bf16 v[104:107], v[144:147], v[196:199], v[104:107]
	v_mfma_f32_16x16x32_bf16 v[96:99], v[152:155], v[196:199], v[96:99]
	v_mfma_f32_16x16x32_bf16 v[88:91], v[144:147], v[204:207], v[88:91]
	v_mfma_f32_16x16x32_bf16 v[80:83], v[152:155], v[204:207], v[80:83]
	s_setprio 0
	s_setprio 1
	v_mfma_f32_16x16x32_bf16 v[136:139], v[148:151], v[184:187], v[136:139]
	v_mfma_f32_16x16x32_bf16 v[128:131], v[156:159], v[184:187], v[128:131]
	v_mfma_f32_16x16x32_bf16 v[120:123], v[148:151], v[192:195], v[120:123]
	v_mfma_f32_16x16x32_bf16 v[112:115], v[156:159], v[192:195], v[112:115]
	s_setprio 0
	s_setprio 1
	v_mfma_f32_16x16x32_bf16 v[104:107], v[148:151], v[200:203], v[104:107]
	v_mfma_f32_16x16x32_bf16 v[96:99], v[156:159], v[200:203], v[96:99]
	v_mfma_f32_16x16x32_bf16 v[88:91], v[148:151], v[208:211], v[88:91]
	v_mfma_f32_16x16x32_bf16 v[80:83], v[156:159], v[208:211], v[80:83]
	s_setprio 0
	s_barrier
	s_add_i32 s45, s45, s6
	v_lshl_add_u64 v[212:213], s[26:27], 0, v[164:165]
	s_mov_b32 m0, s45
	ds_read_b128 v[180:183], v233 offset:16384
	ds_read_b128 v[184:187], v233 offset:17408
	ds_read_b128 v[188:191], v233 offset:18432
	ds_read_b128 v[192:195], v233 offset:19456
	ds_read_b128 v[196:199], v233 offset:20480
	ds_read_b128 v[200:203], v233 offset:21504
	ds_read_b128 v[204:207], v233 offset:22528
	ds_read_b128 v[208:211], v233 offset:23552
	global_load_lds_dwordx4 v[212:213], off
	s_add_i32 m0, s45, 0x2000
	s_add_u32 s46, s26, 0x40000
	v_lshl_add_u64 v[214:215], s[26:27], 0, v[160:161]
	s_addc_u32 s47, s27, 0
	s_add_i32 s45, s48, s6
	global_load_lds_dwordx4 v[214:215], off
	v_lshl_add_u64 v[216:217], s[46:47], 0, v[164:165]
	s_mov_b32 m0, s45
	v_lshl_add_u64 v[218:219], s[28:29], 0, v[162:163]
	global_load_lds_dwordx4 v[216:217], off
	v_lshl_add_u64 v[216:217], s[46:47], 0, v[160:161]
	s_add_i32 m0, s45, 0x2000
	s_nop 0
	global_load_lds_dwordx4 v[216:217], off
	v_lshl_add_u64 v[216:217], s[28:29], 0, v[174:175]
	s_mov_b32 m0, s7
	s_nop 0
	global_load_lds_dwordx4 v[216:217], off
	s_mov_b32 m0, s30
	s_nop 0
	global_load_lds_dwordx4 v[218:219], off
	s_waitcnt vmcnt(8)
	s_waitcnt lgkmcnt(0)
	s_barrier
; #define PG8_STAGE(bufoff, gbase, voff) do { _Pragma("unroll") for (int _i = 0; _i < 2; ++_i) \
;         __builtin_amdgcn_global_load_lds((const unsigned*)((const char*)(gbase) + (voff)[_i]), (PG8_LAS unsigned*)(lds + (bufoff) + ldsw + _i * 8192), 16, 0, 0); } while (0)
; #define PG8_LDA(dst, b, h) do { _Pragma("unroll") for (int m = 0; m < 4; ++m) _Pragma("unroll") for (int k = 0; k < 2; ++k) dst[m][k] = *(const PG8_LAS bf16x8*)(lds + PG8_SA(b, h) + aoff + m * 2048 + k * 1024); } while (0)
; #define PG8_LDB(dst, b, h) do { _Pragma("unroll") for (int n = 0; n < 2; ++n) _Pragma("unroll") for (int k = 0; k < 2; ++k) dst[n][k] = *(const PG8_LAS bf16x8*)(lds + PG8_SB(b, h) + boff + n * 2048 + k * 1024); } while (0)
; #define PG8_MMA(ai, bj, At, Bt) do { __builtin_amdgcn_s_setprio(1); _Pragma("unroll") for (int m = 0; m < 4; ++m) _Pragma("unroll") for (int n = 0; n < 2; ++n) _Pragma("unroll") for (int k = 0; k < 2; ++k) \
;         acc[ai][bj][m][n] = __builtin_amdgcn_mfma_f32_16x16x32_bf16(Bt[n][k], At[m][k], acc[ai][bj][m][n], 0, 0, 0); __builtin_amdgcn_s_setprio(0); } while (0)
; #define PG8_WAIT_V(n) asm volatile("s_waitcnt vmcnt(" #n ")" ::: "memory")
; #define PG8_WAIT_L(n) asm volatile("s_waitcnt lgkmcnt(" #n ")" ::: "memory")
; #define PG8_BAR __builtin_amdgcn_s_barrier()
; #define PG8_SCHED __builtin_amdgcn_sched_barrier(0)
; template <class Epi, class Sched, bool ALIGN_EPI, bool SP2, int KC>
; __device__ __forceinline__ void gemm_phase(PG8_LAS unsigned char* lds, const Gemm g, const Sched& S, const Epi& E, const int tid) {
;     ...
;             PG8_WAIT_V(8); PG8_WAIT_L(0); PG8_BAR; PG8_MMA(1, 0, At, B0); PG8_MMA(1, 1, At, B1); PG8_BAR; PG8_SCHED;
;             PG8_LDB(B0, 1, 0); PG8_LDB(B1, 1, 1); PG8_SCHED; PG8_LDA(At, 1, 0); PG8_STAGE(PG8_SA(0, 1), a2 + hstep, voffA);
;             PG8_WAIT_V(8); PG8_WAIT_L(0); PG8_BAR; PG8_MMA(0, 0, At, B0); PG8_MMA(0, 1, At, B1); PG8_BAR; PG8_SCHED;
	s_setprio 1
	s_waitcnt lgkmcnt(0)
	v_mfma_f32_16x16x32_bf16 v[60:63], v[64:67], v[180:183], v[60:63]
	v_mfma_f32_16x16x32_bf16 v[52:55], v[72:75], v[180:183], v[52:55]
	v_mfma_f32_16x16x32_bf16 v[44:47], v[64:67], v[188:191], v[44:47]
	v_mfma_f32_16x16x32_bf16 v[36:39], v[72:75], v[188:191], v[36:39]
	s_setprio 0
	s_setprio 1
	v_mfma_f32_16x16x32_bf16 v[28:31], v[64:67], v[196:199], v[28:31]
	v_mfma_f32_16x16x32_bf16 v[20:23], v[72:75], v[196:199], v[20:23]
	v_mfma_f32_16x16x32_bf16 v[12:15], v[64:67], v[204:207], v[12:15]
	v_mfma_f32_16x16x32_bf16 v[4:7], v[72:75], v[204:207], v[4:7]
	s_setprio 0
	s_setprio 1
	v_mfma_f32_16x16x32_bf16 v[60:63], v[68:71], v[184:187], v[60:63]
	v_mfma_f32_16x16x32_bf16 v[52:55], v[76:79], v[184:187], v[52:55]
	v_mfma_f32_16x16x32_bf16 v[44:47], v[68:71], v[192:195], v[44:47]
	v_mfma_f32_16x16x32_bf16 v[36:39], v[76:79], v[192:195], v[36:39]
	s_setprio 0
	s_setprio 1
	v_mfma_f32_16x16x32_bf16 v[28:31], v[68:71], v[200:203], v[28:31]
	v_mfma_f32_16x16x32_bf16 v[20:23], v[76:79], v[200:203], v[20:23]
	v_mfma_f32_16x16x32_bf16 v[12:15], v[68:71], v[208:211], v[12:15]
	v_mfma_f32_16x16x32_bf16 v[4:7], v[76:79], v[208:211], v[4:7]
	s_setprio 0
	s_setprio 1
	v_mfma_f32_16x16x32_bf16 v[56:59], v[144:147], v[180:183], v[56:59]
	v_mfma_f32_16x16x32_bf16 v[48:51], v[152:155], v[180:183], v[48:51]
	v_mfma_f32_16x16x32_bf16 v[40:43], v[144:147], v[188:191], v[40:43]
	v_mfma_f32_16x16x32_bf16 v[32:35], v[152:155], v[188:191], v[32:35]
	s_setprio 0
	s_setprio 1
	v_mfma_f32_16x16x32_bf16 v[24:27], v[144:147], v[196:199], v[24:27]
	v_mfma_f32_16x16x32_bf16 v[16:19], v[152:155], v[196:199], v[16:19]
	v_mfma_f32_16x16x32_bf16 v[8:11], v[144:147], v[204:207], v[8:11]
	v_mfma_f32_16x16x32_bf16 v[0:3], v[152:155], v[204:207], v[0:3]
	s_setprio 0
	s_setprio 1
	v_mfma_f32_16x16x32_bf16 v[56:59], v[148:151], v[184:187], v[56:59]
	v_mfma_f32_16x16x32_bf16 v[48:51], v[156:159], v[184:187], v[48:51]
	v_mfma_f32_16x16x32_bf16 v[40:43], v[148:151], v[192:195], v[40:43]
	v_mfma_f32_16x16x32_bf16 v[32:35], v[156:159], v[192:195], v[32:35]
	s_setprio 0
	s_setprio 1
	v_mfma_f32_16x16x32_bf16 v[24:27], v[148:151], v[200:203], v[24:27]
	v_mfma_f32_16x16x32_bf16 v[16:19], v[156:159], v[200:203], v[16:19]
	v_mfma_f32_16x16x32_bf16 v[8:11], v[148:151], v[208:211], v[8:11]
	v_mfma_f32_16x16x32_bf16 v[0:3], v[156:159], v[208:211], v[0:3]
	s_setprio 0
	s_barrier
	s_add_i32 s45, 0, 0x18000
	s_add_i32 s46, 0, 0x1c000
	v_add_u32_e32 v76, s45, v222
	v_add_u32_e32 v156, s46, v222
	ds_read_b128 v[64:67], v76
	ds_read_b128 v[68:71], v76 offset:1024
	ds_read_b128 v[72:75], v76 offset:2048
	ds_read_b128 v[76:79], v76 offset:3072
	ds_read_b128 v[144:147], v156
	ds_read_b128 v[148:151], v156 offset:1024
	ds_read_b128 v[152:155], v156 offset:2048
	ds_read_b128 v[156:159], v156 offset:3072
	s_add_u32 s28, s28, 0x40000
	s_addc_u32 s29, s29, 0
	s_mov_b32 m0, s31
	v_lshl_add_u64 v[220:221], s[28:29], 0, v[174:175]
	ds_read_b128 v[180:183], v233 offset:32768
	ds_read_b128 v[184:187], v233 offset:33792
	ds_read_b128 v[188:191], v233 offset:34816
	ds_read_b128 v[192:195], v233 offset:35840
	ds_read_b128 v[196:199], v233 offset:36864
	ds_read_b128 v[200:203], v233 offset:37888
	ds_read_b128 v[204:207], v233 offset:38912
	ds_read_b128 v[208:211], v233 offset:39936
	global_load_lds_dwordx4 v[220:221], off
	v_lshl_add_u64 v[220:221], s[28:29], 0, v[162:163]
	s_mov_b32 m0, s34
	s_nop 0
	global_load_lds_dwordx4 v[220:221], off
	s_waitcnt vmcnt(8)
	s_waitcnt lgkmcnt(0)
	s_barrier
	s_setprio 1
	s_waitcnt lgkmcnt(0)
	v_mfma_f32_16x16x32_bf16 v[140:143], v[64:67], v[180:183], v[140:143]
	v_mfma_f32_16x16x32_bf16 v[132:135], v[72:75], v[180:183], v[132:135]
	v_mfma_f32_16x16x32_bf16 v[124:127], v[64:67], v[188:191], v[124:127]
	v_mfma_f32_16x16x32_bf16 v[116:119], v[72:75], v[188:191], v[116:119]
	s_setprio 0
	s_setprio 1
	v_mfma_f32_16x16x32_bf16 v[108:111], v[64:67], v[196:199], v[108:111]
	v_mfma_f32_16x16x32_bf16 v[100:103], v[72:75], v[196:199], v[100:103]
	v_mfma_f32_16x16x32_bf16 v[92:95], v[64:67], v[204:207], v[92:95]
	v_mfma_f32_16x16x32_bf16 v[84:87], v[72:75], v[204:207], v[84:87]
	s_setprio 0
	s_setprio 1
	v_mfma_f32_16x16x32_bf16 v[140:143], v[68:71], v[184:187], v[140:143]
	v_mfma_f32_16x16x32_bf16 v[132:135], v[76:79], v[184:187], v[132:135]
	v_mfma_f32_16x16x32_bf16 v[124:127], v[68:71], v[192:195], v[124:127]
	v_mfma_f32_16x16x32_bf16 v[116:119], v[76:79], v[192:195], v[116:119]
	s_setprio 0
	s_setprio 1
	v_mfma_f32_16x16x32_bf16 v[108:111], v[68:71], v[200:203], v[108:111]
	v_mfma_f32_16x16x32_bf16 v[100:103], v[76:79], v[200:203], v[100:103]
	v_mfma_f32_16x16x32_bf16 v[92:95], v[68:71], v[208:211], v[92:95]
	v_mfma_f32_16x16x32_bf16 v[84:87], v[76:79], v[208:211], v[84:87]
	s_setprio 0
	s_setprio 1
	v_mfma_f32_16x16x32_bf16 v[136:139], v[144:147], v[180:183], v[136:139]
	v_mfma_f32_16x16x32_bf16 v[128:131], v[152:155], v[180:183], v[128:131]
	v_mfma_f32_16x16x32_bf16 v[120:123], v[144:147], v[188:191], v[120:123]
	v_mfma_f32_16x16x32_bf16 v[112:115], v[152:155], v[188:191], v[112:115]
	s_setprio 0
	s_setprio 1
	v_mfma_f32_16x16x32_bf16 v[104:107], v[144:147], v[196:199], v[104:107]
	v_mfma_f32_16x16x32_bf16 v[96:99], v[152:155], v[196:199], v[96:99]
	v_mfma_f32_16x16x32_bf16 v[88:91], v[144:147], v[204:207], v[88:91]
	v_mfma_f32_16x16x32_bf16 v[80:83], v[152:155], v[204:207], v[80:83]
	s_setprio 0
	s_setprio 1
	v_mfma_f32_16x16x32_bf16 v[136:139], v[148:151], v[184:187], v[136:139]
	v_mfma_f32_16x16x32_bf16 v[128:131], v[156:159], v[184:187], v[128:131]
	v_mfma_f32_16x16x32_bf16 v[120:123], v[148:151], v[192:195], v[120:123]
	v_mfma_f32_16x16x32_bf16 v[112:115], v[156:159], v[192:195], v[112:115]
	s_setprio 0
	s_setprio 1
	v_mfma_f32_16x16x32_bf16 v[104:107], v[148:151], v[200:203], v[104:107]
	v_mfma_f32_16x16x32_bf16 v[96:99], v[156:159], v[200:203], v[96:99]
	v_mfma_f32_16x16x32_bf16 v[88:91], v[148:151], v[208:211], v[88:91]
	v_mfma_f32_16x16x32_bf16 v[80:83], v[156:159], v[208:211], v[80:83]
	s_setprio 0
	s_barrier
; #define PG8_STAGE(bufoff, gbase, voff) do { _Pragma("unroll") for (int _i = 0; _i < 2; ++_i) \
;         __builtin_amdgcn_global_load_lds((const unsigned*)((const char*)(gbase) + (voff)[_i]), (PG8_LAS unsigned*)(lds + (bufoff) + ldsw + _i * 8192), 16, 0, 0); } while (0)
; #define PG8_LDA(dst, b, h) do { _Pragma("unroll") for (int m = 0; m < 4; ++m) _Pragma("unroll") for (int k = 0; k < 2; ++k) dst[m][k] = *(const PG8_LAS bf16x8*)(lds + PG8_SA(b, h) + aoff + m * 2048 + k * 1024); } while (0)
; #define PG8_MMA(ai, bj, At, Bt) do { __builtin_amdgcn_s_setprio(1); _Pragma("unroll") for (int m = 0; m < 4; ++m) _Pragma("unroll") for (int n = 0; n < 2; ++n) _Pragma("unroll") for (int k = 0; k < 2; ++k) \
;         acc[ai][bj][m][n] = __builtin_amdgcn_mfma_f32_16x16x32_bf16(Bt[n][k], At[m][k], acc[ai][bj][m][n], 0, 0, 0); __builtin_amdgcn_s_setprio(0); } while (0)
; #define PG8_WAIT_V(n) asm volatile("s_waitcnt vmcnt(" #n ")" ::: "memory")
; #define PG8_WAIT_L(n) asm volatile("s_waitcnt lgkmcnt(" #n ")" ::: "memory")
; #define PG8_BAR __builtin_amdgcn_s_barrier()
; #define PG8_SCHED __builtin_amdgcn_sched_barrier(0)
; template <class Epi, class Sched, bool ALIGN_EPI, bool SP2, int KC>
; __device__ __forceinline__ void gemm_phase(PG8_LAS unsigned char* lds, const Gemm g, const Sched& S, const Epi& E, const int tid) {
;     ...
;             PG8_LDA(At, 1, 1); PG8_STAGE(PG8_SB(1, 0), b3, voffB); PG8_STAGE(PG8_SB(1, 1), b3 + hstep, voffB); PG8_STAGE(PG8_SA(1, 0), a3, voffA);
;             PG8_WAIT_V(8); PG8_WAIT_L(0); PG8_BAR; PG8_MMA(1, 0, At, B0); PG8_MMA(1, 1, At, B1); PG8_BAR; PG8_SCHED;
;     ...
;         if constexpr (ALIGN_EPI) { if (wr == 0) PG8_BAR; }
	s_add_i32 s28, s45, s6
	v_lshl_add_u64 v[212:213], v[212:213], 0, s[86:87]
	s_mov_b32 m0, s28
	ds_read_b128 v[180:183], v233 offset:49152
	ds_read_b128 v[184:187], v233 offset:50176
	ds_read_b128 v[188:191], v233 offset:51200
	ds_read_b128 v[192:195], v233 offset:52224
	ds_read_b128 v[196:199], v233 offset:53248
	ds_read_b128 v[200:203], v233 offset:54272
	ds_read_b128 v[204:207], v233 offset:55296
	ds_read_b128 v[208:211], v233 offset:56320
	global_load_lds_dwordx4 v[212:213], off
	s_add_i32 m0, s28, 0x2000
	s_add_u32 s26, s26, 0x40080
	v_lshl_add_u64 v[212:213], v[214:215], 0, s[86:87]
	s_addc_u32 s27, s27, 0
	s_add_i32 s28, s46, s6
	global_load_lds_dwordx4 v[212:213], off
	v_lshl_add_u64 v[212:213], s[26:27], 0, v[164:165]
	s_mov_b32 m0, s28
	s_nop 0
	global_load_lds_dwordx4 v[212:213], off
	v_lshl_add_u64 v[212:213], s[26:27], 0, v[160:161]
	s_add_i32 m0, s28, 0x2000
	s_nop 0
	global_load_lds_dwordx4 v[212:213], off
	v_lshl_add_u64 v[212:213], v[216:217], 0, s[86:87]
	s_mov_b32 m0, s35
	s_nop 0
	global_load_lds_dwordx4 v[212:213], off
	v_lshl_add_u64 v[212:213], v[218:219], 0, s[86:87]
	s_mov_b32 m0, s36
	s_nop 0
	global_load_lds_dwordx4 v[212:213], off
	s_waitcnt vmcnt(8)
	s_waitcnt lgkmcnt(0)
	s_barrier
	s_setprio 1
	s_waitcnt lgkmcnt(0)
	v_mfma_f32_16x16x32_bf16 v[60:63], v[64:67], v[180:183], v[60:63]
	v_mfma_f32_16x16x32_bf16 v[52:55], v[72:75], v[180:183], v[52:55]
	v_mfma_f32_16x16x32_bf16 v[44:47], v[64:67], v[188:191], v[44:47]
	v_mfma_f32_16x16x32_bf16 v[36:39], v[72:75], v[188:191], v[36:39]
	s_setprio 0
	s_setprio 1
	v_mfma_f32_16x16x32_bf16 v[28:31], v[64:67], v[196:199], v[28:31]
	v_mfma_f32_16x16x32_bf16 v[20:23], v[72:75], v[196:199], v[20:23]
	v_mfma_f32_16x16x32_bf16 v[12:15], v[64:67], v[204:207], v[12:15]
	v_mfma_f32_16x16x32_bf16 v[4:7], v[72:75], v[204:207], v[4:7]
	s_setprio 0
	s_setprio 1
	v_mfma_f32_16x16x32_bf16 v[60:63], v[68:71], v[184:187], v[60:63]
	v_mfma_f32_16x16x32_bf16 v[52:55], v[76:79], v[184:187], v[52:55]
	v_mfma_f32_16x16x32_bf16 v[44:47], v[68:71], v[192:195], v[44:47]
	v_mfma_f32_16x16x32_bf16 v[36:39], v[76:79], v[192:195], v[36:39]
	s_setprio 0
	s_setprio 1
	v_mfma_f32_16x16x32_bf16 v[28:31], v[68:71], v[200:203], v[28:31]
	v_mfma_f32_16x16x32_bf16 v[20:23], v[76:79], v[200:203], v[20:23]
	v_mfma_f32_16x16x32_bf16 v[12:15], v[68:71], v[208:211], v[12:15]
	v_mfma_f32_16x16x32_bf16 v[4:7], v[76:79], v[208:211], v[4:7]
	s_setprio 0
	s_setprio 1
	v_mfma_f32_16x16x32_bf16 v[56:59], v[144:147], v[180:183], v[56:59]
	v_mfma_f32_16x16x32_bf16 v[48:51], v[152:155], v[180:183], v[48:51]
	v_mfma_f32_16x16x32_bf16 v[40:43], v[144:147], v[188:191], v[40:43]
	v_mfma_f32_16x16x32_bf16 v[32:35], v[152:155], v[188:191], v[32:35]
	s_setprio 0
	s_setprio 1
	v_mfma_f32_16x16x32_bf16 v[24:27], v[144:147], v[196:199], v[24:27]
	v_mfma_f32_16x16x32_bf16 v[16:19], v[152:155], v[196:199], v[16:19]
	v_mfma_f32_16x16x32_bf16 v[8:11], v[144:147], v[204:207], v[8:11]
	v_mfma_f32_16x16x32_bf16 v[0:3], v[152:155], v[204:207], v[0:3]
	s_setprio 0
	s_setprio 1
	v_mfma_f32_16x16x32_bf16 v[56:59], v[148:151], v[184:187], v[56:59]
	v_mfma_f32_16x16x32_bf16 v[48:51], v[156:159], v[184:187], v[48:51]
	v_mfma_f32_16x16x32_bf16 v[40:43], v[148:151], v[192:195], v[40:43]
	v_mfma_f32_16x16x32_bf16 v[32:35], v[156:159], v[192:195], v[32:35]
	s_setprio 0
	s_setprio 1
	v_mfma_f32_16x16x32_bf16 v[24:27], v[148:151], v[200:203], v[24:27]
	v_mfma_f32_16x16x32_bf16 v[16:19], v[156:159], v[200:203], v[16:19]
	v_mfma_f32_16x16x32_bf16 v[8:11], v[148:151], v[208:211], v[8:11]
	v_mfma_f32_16x16x32_bf16 v[0:3], v[156:159], v[208:211], v[0:3]
	s_setprio 0
	s_barrier
	s_add_i32 s44, s44, 2
	s_add_u32 s4, s4, 0x100
	s_addc_u32 s5, s5, 0
	s_add_u32 s42, s42, 0x100
	s_addc_u32 s43, s43, 0
	s_cmp_gt_u32 s44, 13
	s_cbranch_scc0 .LBB0_92
	s_and_b64 vcc, exec, s[14:15]
	s_cbranch_vccz .LBB0_95
	s_barrier

; #define PG8_STAGE(bufoff, gbase, voff) do { _Pragma("unroll") for (int _i = 0; _i < 2; ++_i) \
;         __builtin_amdgcn_global_load_lds((const unsigned*)((const char*)(gbase) + (voff)[_i]), (PG8_LAS unsigned*)(lds + (bufoff) + ldsw + _i * 8192), 16, 0, 0); } while (0)
; #define PG8_LDA(dst, b, h) do { _Pragma("unroll") for (int m = 0; m < 4; ++m) _Pragma("unroll") for (int k = 0; k < 2; ++k) dst[m][k] = *(const PG8_LAS bf16x8*)(lds + PG8_SA(b, h) + aoff + m * 2048 + k * 1024); } while (0)
; #define PG8_LDB(dst, b, h) do { _Pragma("unroll") for (int n = 0; n < 2; ++n) _Pragma("unroll") for (int k = 0; k < 2; ++k) dst[n][k] = *(const PG8_LAS bf16x8*)(lds + PG8_SB(b, h) + boff + n * 2048 + k * 1024); } while (0)
; #define PG8_MMA(ai, bj, At, Bt) do { __builtin_amdgcn_s_setprio(1); _Pragma("unroll") for (int m = 0; m < 4; ++m) _Pragma("unroll") for (int n = 0; n < 2; ++n) _Pragma("unroll") for (int k = 0; k < 2; ++k) \
;         acc[ai][bj][m][n] = __builtin_amdgcn_mfma_f32_16x16x32_bf16(Bt[n][k], At[m][k], acc[ai][bj][m][n], 0, 0, 0); __builtin_amdgcn_s_setprio(0); } while (0)
; #define PG8_WAIT_V(n) asm volatile("s_waitcnt vmcnt(" #n ")" ::: "memory")
; #define PG8_WAIT_L(n) asm volatile("s_waitcnt lgkmcnt(" #n ")" ::: "memory")
; #define PG8_BAR __builtin_amdgcn_s_barrier()
; template <class Epi, class Sched, bool ALIGN_EPI, bool SP2, int KC>
; __device__ __forceinline__ void gemm_phase(PG8_LAS unsigned char* lds, const Gemm g, const Sched& S, const Epi& E, const int tid) {
;     ...
;             const char* a1 = cA + (size_t)(t + 1) * kstep;
;             const char* a2 = last ? nA : cA + (size_t)(t + 2) * kstep; const char* b2 = last ? nB : cB + (size_t)(t + 2) * kstep;
;             const char* a3 = a2 + kstep; const char* b3 = b2 + kstep;
;             if (last && has_next) S.a_ready(nxt);
;             if constexpr (SP2) {
;             PG8_LDB(B0, 0, 0); PG8_LDB(B1, 0, 1); PG8_SCHED; PG8_LDA(At, 0, 0); PG8_STAGE(PG8_SA(1, 1), a1 + hstep, voffA);
;             PG8_WAIT_V(8); PG8_WAIT_L(0); PG8_BAR; PG8_MMA(0, 0, At, B0); PG8_MMA(0, 1, At, B1); PG8_BAR; PG8_SCHED;
;             PG8_LDA(At, 0, 1); PG8_STAGE(PG8_SB(0, 0), b2, voffB); PG8_STAGE(PG8_SB(0, 1), b2 + hstep, voffB); PG8_STAGE(PG8_SA(0, 0), a2, voffA);
;             PG8_WAIT_V(8); PG8_WAIT_L(0); PG8_BAR; PG8_MMA(1, 0, At, B0); PG8_MMA(1, 1, At, B1); PG8_BAR; PG8_SCHED;
.LBB0_116:
	s_add_u32 s24, s22, 0xfffc0080
	s_addc_u32 s25, s23, -1
	s_add_i32 s43, 0, 0x10000
	s_cmp_eq_u32 s42, 12
	s_cselect_b32 s27, s15, s25
	s_cselect_b32 s26, s38, s24
	s_cselect_b32 s25, s13, s41
	s_cselect_b32 s24, s39, s40
	s_add_i32 s46, 0, 0x14000
	v_add_u32_e32 v140, s43, v196
	v_add_u32_e32 v162, s46, v196
	ds_read_b128 v[128:131], v140
	ds_read_b128 v[132:135], v140 offset:1024
	ds_read_b128 v[136:139], v140 offset:2048
	ds_read_b128 v[140:143], v140 offset:3072
	ds_read_b128 v[154:157], v162
	ds_read_b128 v[158:161], v162 offset:1024
	ds_read_b128 v[174:177], v162 offset:2048
	ds_read_b128 v[178:181], v162 offset:3072
	v_lshl_add_u64 v[162:163], s[22:23], 0, v[150:151]
	s_add_i32 m0, s29, 0xc000
	ds_read_b128 v[182:185], v198
	ds_read_b128 v[186:189], v198 offset:1024
	ds_read_b128 v[190:193], v198 offset:2048
	ds_read_b128 v[200:203], v198 offset:3072
	ds_read_b128 v[204:207], v198 offset:4096
	ds_read_b128 v[208:211], v198 offset:5120
	ds_read_b128 v[212:215], v198 offset:6144
	ds_read_b128 v[216:219], v198 offset:7168
	global_load_lds_dwordx4 v[162:163], off
	v_lshl_add_u64 v[162:163], s[22:23], 0, v[152:153]
	s_add_i32 m0, s29, 0xe000
	s_nop 0
	global_load_lds_dwordx4 v[162:163], off
	s_waitcnt vmcnt(8)
	s_waitcnt lgkmcnt(0)
	s_barrier
	s_setprio 1
	s_waitcnt lgkmcnt(0)
	v_mfma_f32_16x16x32_bf16 v[124:127], v[128:131], v[182:185], v[124:127]
	v_mfma_f32_16x16x32_bf16 v[120:123], v[136:139], v[182:185], v[120:123]
	v_mfma_f32_16x16x32_bf16 v[116:119], v[128:131], v[190:193], v[116:119]
	v_mfma_f32_16x16x32_bf16 v[112:115], v[136:139], v[190:193], v[112:115]
	s_setprio 0
	s_setprio 1
	v_mfma_f32_16x16x32_bf16 v[108:111], v[128:131], v[204:207], v[108:111]
	v_mfma_f32_16x16x32_bf16 v[104:107], v[136:139], v[204:207], v[104:107]
	v_mfma_f32_16x16x32_bf16 v[100:103], v[128:131], v[212:215], v[100:103]
	v_mfma_f32_16x16x32_bf16 v[96:99], v[136:139], v[212:215], v[96:99]
	s_setprio 0
	s_setprio 1
	v_mfma_f32_16x16x32_bf16 v[124:127], v[132:135], v[186:189], v[124:127]
	v_mfma_f32_16x16x32_bf16 v[120:123], v[140:143], v[186:189], v[120:123]
	v_mfma_f32_16x16x32_bf16 v[116:119], v[132:135], v[200:203], v[116:119]
	v_mfma_f32_16x16x32_bf16 v[112:115], v[140:143], v[200:203], v[112:115]
	s_setprio 0
	s_setprio 1
	v_mfma_f32_16x16x32_bf16 v[108:111], v[132:135], v[208:211], v[108:111]
	v_mfma_f32_16x16x32_bf16 v[104:107], v[140:143], v[208:211], v[104:107]
	v_mfma_f32_16x16x32_bf16 v[100:103], v[132:135], v[216:219], v[100:103]
	v_mfma_f32_16x16x32_bf16 v[96:99], v[140:143], v[216:219], v[96:99]
	s_setprio 0
	s_setprio 1
	v_mfma_f32_16x16x32_bf16 v[68:71], v[154:157], v[182:185], v[68:71]
	v_mfma_f32_16x16x32_bf16 v[64:67], v[174:177], v[182:185], v[64:67]
	v_mfma_f32_16x16x32_bf16 v[52:55], v[154:157], v[190:193], v[52:55]
	v_mfma_f32_16x16x32_bf16 v[48:51], v[174:177], v[190:193], v[48:51]
	s_setprio 0
	s_setprio 1
	v_mfma_f32_16x16x32_bf16 v[44:47], v[154:157], v[204:207], v[44:47]
	v_mfma_f32_16x16x32_bf16 v[40:43], v[174:177], v[204:207], v[40:43]
	v_mfma_f32_16x16x32_bf16 v[36:39], v[154:157], v[212:215], v[36:39]
	v_mfma_f32_16x16x32_bf16 v[32:35], v[174:177], v[212:215], v[32:35]
	s_setprio 0
	s_setprio 1
	v_mfma_f32_16x16x32_bf16 v[68:71], v[158:161], v[186:189], v[68:71]
	v_mfma_f32_16x16x32_bf16 v[64:67], v[178:181], v[186:189], v[64:67]
	v_mfma_f32_16x16x32_bf16 v[52:55], v[158:161], v[200:203], v[52:55]
	v_mfma_f32_16x16x32_bf16 v[48:51], v[178:181], v[200:203], v[48:51]
	s_setprio 0
	s_setprio 1
	v_mfma_f32_16x16x32_bf16 v[44:47], v[158:161], v[208:211], v[44:47]
	v_mfma_f32_16x16x32_bf16 v[40:43], v[178:181], v[208:211], v[40:43]
	v_mfma_f32_16x16x32_bf16 v[36:39], v[158:161], v[216:219], v[36:39]
	v_mfma_f32_16x16x32_bf16 v[32:35], v[178:181], v[216:219], v[32:35]
	s_setprio 0
	s_barrier
	s_add_i32 s43, s43, s28
	v_lshl_add_u64 v[162:163], s[24:25], 0, v[164:165]
	s_mov_b32 m0, s43
	ds_read_b128 v[182:185], v198 offset:16384
	ds_read_b128 v[186:189], v198 offset:17408
	ds_read_b128 v[190:193], v198 offset:18432
	ds_read_b128 v[200:203], v198 offset:19456
	ds_read_b128 v[204:207], v198 offset:20480
	ds_read_b128 v[208:211], v198 offset:21504
	ds_read_b128 v[212:215], v198 offset:22528
	ds_read_b128 v[216:219], v198 offset:23552
	global_load_lds_dwordx4 v[162:163], off
	s_add_i32 m0, s43, 0x2000
	s_add_u32 s44, s24, 0x40000
	v_lshl_add_u64 v[194:195], s[24:25], 0, v[144:145]
	s_addc_u32 s45, s25, 0
	s_add_i32 s43, s46, s28
	global_load_lds_dwordx4 v[194:195], off
	v_lshl_add_u64 v[220:221], s[44:45], 0, v[164:165]
	s_mov_b32 m0, s43
	v_lshl_add_u64 v[222:223], s[26:27], 0, v[146:147]
	global_load_lds_dwordx4 v[220:221], off
	v_lshl_add_u64 v[220:221], s[44:45], 0, v[144:145]
	s_add_i32 m0, s43, 0x2000
	s_nop 0
	global_load_lds_dwordx4 v[220:221], off
	v_lshl_add_u64 v[220:221], s[26:27], 0, v[148:149]
	s_mov_b32 m0, s29
	s_nop 0
	global_load_lds_dwordx4 v[220:221], off
	s_mov_b32 m0, s30
	s_nop 0
	global_load_lds_dwordx4 v[222:223], off
	s_waitcnt vmcnt(8)
	s_waitcnt lgkmcnt(0)
	s_barrier
; #define PG8_STAGE(bufoff, gbase, voff) do { _Pragma("unroll") for (int _i = 0; _i < 2; ++_i) \
;         __builtin_amdgcn_global_load_lds((const unsigned*)((const char*)(gbase) + (voff)[_i]), (PG8_LAS unsigned*)(lds + (bufoff) + ldsw + _i * 8192), 16, 0, 0); } while (0)
; #define PG8_LDA(dst, b, h) do { _Pragma("unroll") for (int m = 0; m < 4; ++m) _Pragma("unroll") for (int k = 0; k < 2; ++k) dst[m][k] = *(const PG8_LAS bf16x8*)(lds + PG8_SA(b, h) + aoff + m * 2048 + k * 1024); } while (0)
; #define PG8_LDB(dst, b, h) do { _Pragma("unroll") for (int n = 0; n < 2; ++n) _Pragma("unroll") for (int k = 0; k < 2; ++k) dst[n][k] = *(const PG8_LAS bf16x8*)(lds + PG8_SB(b, h) + boff + n * 2048 + k * 1024); } while (0)
; #define PG8_MMA(ai, bj, At, Bt) do { __builtin_amdgcn_s_setprio(1); _Pragma("unroll") for (int m = 0; m < 4; ++m) _Pragma("unroll") for (int n = 0; n < 2; ++n) _Pragma("unroll") for (int k = 0; k < 2; ++k) \
;         acc[ai][bj][m][n] = __builtin_amdgcn_mfma_f32_16x16x32_bf16(Bt[n][k], At[m][k], acc[ai][bj][m][n], 0, 0, 0); __builtin_amdgcn_s_setprio(0); } while (0)
; #define PG8_WAIT_V(n) asm volatile("s_waitcnt vmcnt(" #n ")" ::: "memory")
; #define PG8_WAIT_L(n) asm volatile("s_waitcnt lgkmcnt(" #n ")" ::: "memory")
; #define PG8_BAR __builtin_amdgcn_s_barrier()
; #define PG8_SCHED __builtin_amdgcn_sched_barrier(0)
; template <class Epi, class Sched, bool ALIGN_EPI, bool SP2, int KC>
; __device__ __forceinline__ void gemm_phase(PG8_LAS unsigned char* lds, const Gemm g, const Sched& S, const Epi& E, const int tid) {
;     ...
;             PG8_WAIT_V(8); PG8_WAIT_L(0); PG8_BAR; PG8_MMA(1, 0, At, B0); PG8_MMA(1, 1, At, B1); PG8_BAR; PG8_SCHED;
;             PG8_LDB(B0, 1, 0); PG8_LDB(B1, 1, 1); PG8_SCHED; PG8_LDA(At, 1, 0); PG8_STAGE(PG8_SA(0, 1), a2 + hstep, voffA);
;             PG8_WAIT_V(8); PG8_WAIT_L(0); PG8_BAR; PG8_MMA(0, 0, At, B0); PG8_MMA(0, 1, At, B1); PG8_BAR; PG8_SCHED;
	s_setprio 1
	s_waitcnt lgkmcnt(0)
	v_mfma_f32_16x16x32_bf16 v[92:95], v[128:131], v[182:185], v[92:95]
	v_mfma_f32_16x16x32_bf16 v[88:91], v[136:139], v[182:185], v[88:91]
	v_mfma_f32_16x16x32_bf16 v[84:87], v[128:131], v[190:193], v[84:87]
	v_mfma_f32_16x16x32_bf16 v[80:83], v[136:139], v[190:193], v[80:83]
	s_setprio 0
	s_setprio 1
	v_mfma_f32_16x16x32_bf16 v[76:79], v[128:131], v[204:207], v[76:79]
	v_mfma_f32_16x16x32_bf16 v[72:75], v[136:139], v[204:207], v[72:75]
	v_mfma_f32_16x16x32_bf16 v[60:63], v[128:131], v[212:215], v[60:63]
	v_mfma_f32_16x16x32_bf16 v[56:59], v[136:139], v[212:215], v[56:59]
	s_setprio 0
	s_setprio 1
	v_mfma_f32_16x16x32_bf16 v[92:95], v[132:135], v[186:189], v[92:95]
	v_mfma_f32_16x16x32_bf16 v[88:91], v[140:143], v[186:189], v[88:91]
	v_mfma_f32_16x16x32_bf16 v[84:87], v[132:135], v[200:203], v[84:87]
	v_mfma_f32_16x16x32_bf16 v[80:83], v[140:143], v[200:203], v[80:83]
	s_setprio 0
	s_setprio 1
	v_mfma_f32_16x16x32_bf16 v[76:79], v[132:135], v[208:211], v[76:79]
	v_mfma_f32_16x16x32_bf16 v[72:75], v[140:143], v[208:211], v[72:75]
	v_mfma_f32_16x16x32_bf16 v[60:63], v[132:135], v[216:219], v[60:63]
	v_mfma_f32_16x16x32_bf16 v[56:59], v[140:143], v[216:219], v[56:59]
	s_setprio 0
	s_setprio 1
	v_mfma_f32_16x16x32_bf16 v[28:31], v[154:157], v[182:185], v[28:31]
	v_mfma_f32_16x16x32_bf16 v[24:27], v[174:177], v[182:185], v[24:27]
	v_mfma_f32_16x16x32_bf16 v[20:23], v[154:157], v[190:193], v[20:23]
	v_mfma_f32_16x16x32_bf16 v[16:19], v[174:177], v[190:193], v[16:19]
	s_setprio 0
	s_setprio 1
	v_mfma_f32_16x16x32_bf16 v[12:15], v[154:157], v[204:207], v[12:15]
	v_mfma_f32_16x16x32_bf16 v[8:11], v[174:177], v[204:207], v[8:11]
	v_mfma_f32_16x16x32_bf16 v[4:7], v[154:157], v[212:215], v[4:7]
	v_mfma_f32_16x16x32_bf16 v[0:3], v[174:177], v[212:215], v[0:3]
	s_setprio 0
	s_setprio 1
	v_mfma_f32_16x16x32_bf16 v[28:31], v[158:161], v[186:189], v[28:31]
	v_mfma_f32_16x16x32_bf16 v[24:27], v[178:181], v[186:189], v[24:27]
	v_mfma_f32_16x16x32_bf16 v[20:23], v[158:161], v[200:203], v[20:23]
	v_mfma_f32_16x16x32_bf16 v[16:19], v[178:181], v[200:203], v[16:19]
	s_setprio 0
	s_setprio 1
	v_mfma_f32_16x16x32_bf16 v[12:15], v[158:161], v[208:211], v[12:15]
	v_mfma_f32_16x16x32_bf16 v[8:11], v[178:181], v[208:211], v[8:11]
	v_mfma_f32_16x16x32_bf16 v[4:7], v[158:161], v[216:219], v[4:7]
	v_mfma_f32_16x16x32_bf16 v[0:3], v[178:181], v[216:219], v[0:3]
	s_setprio 0
	s_barrier
	s_add_i32 s43, 0, 0x18000
	s_add_i32 s44, 0, 0x1c000
	v_add_u32_e32 v140, s43, v196
	v_add_u32_e32 v178, s44, v196
	ds_read_b128 v[128:131], v140
	ds_read_b128 v[132:135], v140 offset:1024
	ds_read_b128 v[136:139], v140 offset:2048
	ds_read_b128 v[140:143], v140 offset:3072
	ds_read_b128 v[154:157], v178
	ds_read_b128 v[158:161], v178 offset:1024
	ds_read_b128 v[174:177], v178 offset:2048
	ds_read_b128 v[178:181], v178 offset:3072
	s_add_u32 s26, s26, 0x40000
	s_addc_u32 s27, s27, 0
	s_mov_b32 m0, s31
	v_lshl_add_u64 v[234:235], s[26:27], 0, v[148:149]
	ds_read_b128 v[182:185], v198 offset:32768
	ds_read_b128 v[186:189], v198 offset:33792
	ds_read_b128 v[190:193], v198 offset:34816
	ds_read_b128 v[200:203], v198 offset:35840
	ds_read_b128 v[204:207], v198 offset:36864
	ds_read_b128 v[208:211], v198 offset:37888
	ds_read_b128 v[212:215], v198 offset:38912
	ds_read_b128 v[216:219], v198 offset:39936
	global_load_lds_dwordx4 v[234:235], off
	v_lshl_add_u64 v[234:235], s[26:27], 0, v[146:147]
	s_mov_b32 m0, s34
	s_nop 0
	global_load_lds_dwordx4 v[234:235], off
	s_waitcnt vmcnt(8)
	s_waitcnt lgkmcnt(0)
	s_barrier
	s_setprio 1
	s_waitcnt lgkmcnt(0)
	v_mfma_f32_16x16x32_bf16 v[124:127], v[128:131], v[182:185], v[124:127]
	v_mfma_f32_16x16x32_bf16 v[120:123], v[136:139], v[182:185], v[120:123]
	v_mfma_f32_16x16x32_bf16 v[116:119], v[128:131], v[190:193], v[116:119]
	v_mfma_f32_16x16x32_bf16 v[112:115], v[136:139], v[190:193], v[112:115]
	s_setprio 0
	s_setprio 1
	v_mfma_f32_16x16x32_bf16 v[108:111], v[128:131], v[204:207], v[108:111]
	v_mfma_f32_16x16x32_bf16 v[104:107], v[136:139], v[204:207], v[104:107]
	v_mfma_f32_16x16x32_bf16 v[100:103], v[128:131], v[212:215], v[100:103]
	v_mfma_f32_16x16x32_bf16 v[96:99], v[136:139], v[212:215], v[96:99]
	s_setprio 0
	s_setprio 1
	v_mfma_f32_16x16x32_bf16 v[124:127], v[132:135], v[186:189], v[124:127]
	v_mfma_f32_16x16x32_bf16 v[120:123], v[140:143], v[186:189], v[120:123]
	v_mfma_f32_16x16x32_bf16 v[116:119], v[132:135], v[200:203], v[116:119]
	v_mfma_f32_16x16x32_bf16 v[112:115], v[140:143], v[200:203], v[112:115]
	s_setprio 0
	s_setprio 1
	v_mfma_f32_16x16x32_bf16 v[108:111], v[132:135], v[208:211], v[108:111]
	v_mfma_f32_16x16x32_bf16 v[104:107], v[140:143], v[208:211], v[104:107]
	v_mfma_f32_16x16x32_bf16 v[100:103], v[132:135], v[216:219], v[100:103]
	v_mfma_f32_16x16x32_bf16 v[96:99], v[140:143], v[216:219], v[96:99]
	s_setprio 0
	s_setprio 1
	v_mfma_f32_16x16x32_bf16 v[68:71], v[154:157], v[182:185], v[68:71]
	v_mfma_f32_16x16x32_bf16 v[64:67], v[174:177], v[182:185], v[64:67]
	v_mfma_f32_16x16x32_bf16 v[52:55], v[154:157], v[190:193], v[52:55]
	v_mfma_f32_16x16x32_bf16 v[48:51], v[174:177], v[190:193], v[48:51]
	s_setprio 0
	s_setprio 1
	v_mfma_f32_16x16x32_bf16 v[44:47], v[154:157], v[204:207], v[44:47]
	v_mfma_f32_16x16x32_bf16 v[40:43], v[174:177], v[204:207], v[40:43]
	v_mfma_f32_16x16x32_bf16 v[36:39], v[154:157], v[212:215], v[36:39]
	v_mfma_f32_16x16x32_bf16 v[32:35], v[174:177], v[212:215], v[32:35]
	s_setprio 0
	s_setprio 1
	v_mfma_f32_16x16x32_bf16 v[68:71], v[158:161], v[186:189], v[68:71]
	v_mfma_f32_16x16x32_bf16 v[64:67], v[178:181], v[186:189], v[64:67]
	v_mfma_f32_16x16x32_bf16 v[52:55], v[158:161], v[200:203], v[52:55]
	v_mfma_f32_16x16x32_bf16 v[48:51], v[178:181], v[200:203], v[48:51]
	s_setprio 0
	s_setprio 1
	v_mfma_f32_16x16x32_bf16 v[44:47], v[158:161], v[208:211], v[44:47]
	v_mfma_f32_16x16x32_bf16 v[40:43], v[178:181], v[208:211], v[40:43]
	v_mfma_f32_16x16x32_bf16 v[36:39], v[158:161], v[216:219], v[36:39]
	v_mfma_f32_16x16x32_bf16 v[32:35], v[178:181], v[216:219], v[32:35]
	s_setprio 0
	s_barrier
; #define PG8_STAGE(bufoff, gbase, voff) do { _Pragma("unroll") for (int _i = 0; _i < 2; ++_i) \
;         __builtin_amdgcn_global_load_lds((const unsigned*)((const char*)(gbase) + (voff)[_i]), (PG8_LAS unsigned*)(lds + (bufoff) + ldsw + _i * 8192), 16, 0, 0); } while (0)
; #define PG8_LDA(dst, b, h) do { _Pragma("unroll") for (int m = 0; m < 4; ++m) _Pragma("unroll") for (int k = 0; k < 2; ++k) dst[m][k] = *(const PG8_LAS bf16x8*)(lds + PG8_SA(b, h) + aoff + m * 2048 + k * 1024); } while (0)
; #define PG8_MMA(ai, bj, At, Bt) do { __builtin_amdgcn_s_setprio(1); _Pragma("unroll") for (int m = 0; m < 4; ++m) _Pragma("unroll") for (int n = 0; n < 2; ++n) _Pragma("unroll") for (int k = 0; k < 2; ++k) \
;         acc[ai][bj][m][n] = __builtin_amdgcn_mfma_f32_16x16x32_bf16(Bt[n][k], At[m][k], acc[ai][bj][m][n], 0, 0, 0); __builtin_amdgcn_s_setprio(0); } while (0)
; #define PG8_WAIT_V(n) asm volatile("s_waitcnt vmcnt(" #n ")" ::: "memory")
; #define PG8_WAIT_L(n) asm volatile("s_waitcnt lgkmcnt(" #n ")" ::: "memory")
; #define PG8_BAR __builtin_amdgcn_s_barrier()
; #define PG8_SCHED __builtin_amdgcn_sched_barrier(0)
; template <class Epi, class Sched, bool ALIGN_EPI, bool SP2, int KC>
; __device__ __forceinline__ void gemm_phase(PG8_LAS unsigned char* lds, const Gemm g, const Sched& S, const Epi& E, const int tid) {
;     ...
;             PG8_LDA(At, 1, 1); PG8_STAGE(PG8_SB(1, 0), b3, voffB); PG8_STAGE(PG8_SB(1, 1), b3 + hstep, voffB); PG8_STAGE(PG8_SA(1, 0), a3, voffA);
;             PG8_WAIT_V(8); PG8_WAIT_L(0); PG8_BAR; PG8_MMA(1, 0, At, B0); PG8_MMA(1, 1, At, B1); PG8_BAR; PG8_SCHED;
	s_add_i32 s26, s43, s28
	v_lshl_add_u64 v[162:163], v[162:163], 0, s[86:87]
	s_mov_b32 m0, s26
	ds_read_b128 v[182:185], v198 offset:49152
	ds_read_b128 v[186:189], v198 offset:50176
	ds_read_b128 v[190:193], v198 offset:51200
	ds_read_b128 v[200:203], v198 offset:52224
	ds_read_b128 v[204:207], v198 offset:53248
	ds_read_b128 v[208:211], v198 offset:54272
	ds_read_b128 v[212:215], v198 offset:55296
	ds_read_b128 v[216:219], v198 offset:56320
	global_load_lds_dwordx4 v[162:163], off
	s_add_i32 m0, s26, 0x2000
	s_add_u32 s24, s24, 0x40080
	v_lshl_add_u64 v[162:163], v[194:195], 0, s[86:87]
	s_addc_u32 s25, s25, 0
	s_add_i32 s26, s44, s28
	global_load_lds_dwordx4 v[162:163], off
	v_lshl_add_u64 v[162:163], s[24:25], 0, v[164:165]
	s_mov_b32 m0, s26
	s_nop 0
	global_load_lds_dwordx4 v[162:163], off
	v_lshl_add_u64 v[162:163], s[24:25], 0, v[144:145]
	s_add_i32 m0, s26, 0x2000
	s_nop 0
	global_load_lds_dwordx4 v[162:163], off
	v_lshl_add_u64 v[162:163], v[220:221], 0, s[86:87]
	s_mov_b32 m0, s35
	s_nop 0
	global_load_lds_dwordx4 v[162:163], off
	v_lshl_add_u64 v[162:163], v[222:223], 0, s[86:87]
	s_mov_b32 m0, s36
	s_nop 0
	global_load_lds_dwordx4 v[162:163], off
	s_waitcnt vmcnt(8)
	s_waitcnt lgkmcnt(0)
	s_barrier
	s_setprio 1
	s_waitcnt lgkmcnt(0)
	v_mfma_f32_16x16x32_bf16 v[92:95], v[128:131], v[182:185], v[92:95]
	v_mfma_f32_16x16x32_bf16 v[88:91], v[136:139], v[182:185], v[88:91]
	v_mfma_f32_16x16x32_bf16 v[84:87], v[128:131], v[190:193], v[84:87]
	v_mfma_f32_16x16x32_bf16 v[80:83], v[136:139], v[190:193], v[80:83]
	s_setprio 0
	s_setprio 1
	v_mfma_f32_16x16x32_bf16 v[76:79], v[128:131], v[204:207], v[76:79]
	v_mfma_f32_16x16x32_bf16 v[72:75], v[136:139], v[204:207], v[72:75]
	v_mfma_f32_16x16x32_bf16 v[60:63], v[128:131], v[212:215], v[60:63]
	v_mfma_f32_16x16x32_bf16 v[56:59], v[136:139], v[212:215], v[56:59]
	s_setprio 0
	s_setprio 1
	v_mfma_f32_16x16x32_bf16 v[92:95], v[132:135], v[186:189], v[92:95]
	v_mfma_f32_16x16x32_bf16 v[88:91], v[140:143], v[186:189], v[88:91]
	v_mfma_f32_16x16x32_bf16 v[84:87], v[132:135], v[200:203], v[84:87]
	v_mfma_f32_16x16x32_bf16 v[80:83], v[140:143], v[200:203], v[80:83]
	s_setprio 0
	s_setprio 1
	v_mfma_f32_16x16x32_bf16 v[76:79], v[132:135], v[208:211], v[76:79]
	v_mfma_f32_16x16x32_bf16 v[72:75], v[140:143], v[208:211], v[72:75]
	v_mfma_f32_16x16x32_bf16 v[60:63], v[132:135], v[216:219], v[60:63]
	v_mfma_f32_16x16x32_bf16 v[56:59], v[140:143], v[216:219], v[56:59]
	s_setprio 0
	s_setprio 1
	v_mfma_f32_16x16x32_bf16 v[28:31], v[154:157], v[182:185], v[28:31]
	v_mfma_f32_16x16x32_bf16 v[24:27], v[174:177], v[182:185], v[24:27]
	v_mfma_f32_16x16x32_bf16 v[20:23], v[154:157], v[190:193], v[20:23]
	v_mfma_f32_16x16x32_bf16 v[16:19], v[174:177], v[190:193], v[16:19]
	s_setprio 0
	s_setprio 1
	v_mfma_f32_16x16x32_bf16 v[12:15], v[154:157], v[204:207], v[12:15]
	v_mfma_f32_16x16x32_bf16 v[8:11], v[174:177], v[204:207], v[8:11]
	v_mfma_f32_16x16x32_bf16 v[4:7], v[154:157], v[212:215], v[4:7]
	v_mfma_f32_16x16x32_bf16 v[0:3], v[174:177], v[212:215], v[0:3]
	s_setprio 0
	s_setprio 1
	v_mfma_f32_16x16x32_bf16 v[28:31], v[158:161], v[186:189], v[28:31]
	v_mfma_f32_16x16x32_bf16 v[24:27], v[178:181], v[186:189], v[24:27]
	v_mfma_f32_16x16x32_bf16 v[20:23], v[158:161], v[200:203], v[20:23]
	v_mfma_f32_16x16x32_bf16 v[16:19], v[178:181], v[200:203], v[16:19]
	s_setprio 0
	s_setprio 1
	v_mfma_f32_16x16x32_bf16 v[12:15], v[158:161], v[208:211], v[12:15]
	v_mfma_f32_16x16x32_bf16 v[8:11], v[178:181], v[208:211], v[8:11]
	v_mfma_f32_16x16x32_bf16 v[4:7], v[158:161], v[216:219], v[4:7]
	v_mfma_f32_16x16x32_bf16 v[0:3], v[178:181], v[216:219], v[0:3]
	s_setprio 0
	s_barrier
	s_add_i32 s42, s42, 2
	s_add_u32 s22, s22, 0x100
	s_addc_u32 s23, s23, 0
	s_add_u32 s40, s40, 0x100
	s_addc_u32 s41, s41, 0
	s_cmp_gt_u32 s42, 13
	s_cbranch_scc0 .LBB0_116
	s_and_b64 vcc, exec, s[10:11]
	s_cbranch_vccz .LBB0_119
	s_barrier

; #define PG8_STAGE(bufoff, gbase, voff) do { _Pragma("unroll") for (int _i = 0; _i < 2; ++_i) \
;         __builtin_amdgcn_global_load_lds((const unsigned*)((const char*)(gbase) + (voff)[_i]), (PG8_LAS unsigned*)(lds + (bufoff) + ldsw + _i * 8192), 16, 0, 0); } while (0)
; #define PG8_LDA(dst, b, h) do { _Pragma("unroll") for (int m = 0; m < 4; ++m) _Pragma("unroll") for (int k = 0; k < 2; ++k) dst[m][k] = *(const PG8_LAS bf16x8*)(lds + PG8_SA(b, h) + aoff + m * 2048 + k * 1024); } while (0)
; #define PG8_LDB(dst, b, h) do { _Pragma("unroll") for (int n = 0; n < 2; ++n) _Pragma("unroll") for (int k = 0; k < 2; ++k) dst[n][k] = *(const PG8_LAS bf16x8*)(lds + PG8_SB(b, h) + boff + n * 2048 + k * 1024); } while (0)
; #define PG8_MMA(ai, bj, At, Bt) do { __builtin_amdgcn_s_setprio(1); _Pragma("unroll") for (int m = 0; m < 4; ++m) _Pragma("unroll") for (int n = 0; n < 2; ++n) _Pragma("unroll") for (int k = 0; k < 2; ++k) \
;         acc[ai][bj][m][n] = __builtin_amdgcn_mfma_f32_16x16x32_bf16(Bt[n][k], At[m][k], acc[ai][bj][m][n], 0, 0, 0); __builtin_amdgcn_s_setprio(0); } while (0)
; #define PG8_WAIT_V(n) asm volatile("s_waitcnt vmcnt(" #n ")" ::: "memory")
; #define PG8_WAIT_L(n) asm volatile("s_waitcnt lgkmcnt(" #n ")" ::: "memory")
; #define PG8_BAR __builtin_amdgcn_s_barrier()
; template <class Epi, class Sched, bool ALIGN_EPI, bool SP2, int KC>
; __device__ __forceinline__ void gemm_phase(PG8_LAS unsigned char* lds, const Gemm g, const Sched& S, const Epi& E, const int tid) {
;     ...
;             const char* a1 = cA + (size_t)(t + 1) * kstep;
;             const char* a2 = last ? nA : cA + (size_t)(t + 2) * kstep; const char* b2 = last ? nB : cB + (size_t)(t + 2) * kstep;
;             const char* a3 = a2 + kstep; const char* b3 = b2 + kstep;
;             if (last && has_next) S.a_ready(nxt);
;             if constexpr (SP2) {
;             PG8_LDB(B0, 0, 0); PG8_LDB(B1, 0, 1); PG8_SCHED; PG8_LDA(At, 0, 0); PG8_STAGE(PG8_SA(1, 1), a1 + hstep, voffA);
;             PG8_WAIT_V(8); PG8_WAIT_L(0); PG8_BAR; PG8_MMA(0, 0, At, B0); PG8_MMA(0, 1, At, B1); PG8_BAR; PG8_SCHED;
;             PG8_LDA(At, 0, 1); PG8_STAGE(PG8_SB(0, 0), b2, voffB); PG8_STAGE(PG8_SB(0, 1), b2 + hstep, voffB); PG8_STAGE(PG8_SA(0, 0), a2, voffA);
;             PG8_WAIT_V(8); PG8_WAIT_L(0); PG8_BAR; PG8_MMA(1, 0, At, B0); PG8_MMA(1, 1, At, B1); PG8_BAR; PG8_SCHED;
.LBB0_162:
	s_add_u32 s16, s4, 0xfffc0080
	s_addc_u32 s17, s5, -1
	s_add_i32 s71, 0, 0x10000
	s_cmp_eq_u32 s70, 12
	s_cselect_b32 s19, s41, s17
	s_cselect_b32 s18, s47, s16
	s_cselect_b32 s17, s39, s65
	s_cselect_b32 s16, s49, s64
	s_add_i32 s79, 0, 0x14000
	v_add_u32_e32 v146, s71, v245
	v_add_u32_e32 v162, s79, v245
	ds_read_b128 v[128:131], v146
	ds_read_b128 v[132:135], v146 offset:1024
	ds_read_b128 v[136:139], v146 offset:2048
	ds_read_b128 v[146:149], v146 offset:3072
	ds_read_b128 v[150:153], v162
	ds_read_b128 v[154:157], v162 offset:1024
	ds_read_b128 v[158:161], v162 offset:2048
	ds_read_b128 v[174:177], v162 offset:3072
	v_lshl_add_u64 v[162:163], s[4:5], 0, v[142:143]
	s_add_i32 m0, s7, 0xc000
	ds_read_b128 v[178:181], v249
	ds_read_b128 v[182:185], v249 offset:1024
	ds_read_b128 v[186:189], v249 offset:2048
	ds_read_b128 v[190:193], v249 offset:3072
	ds_read_b128 v[194:197], v249 offset:4096
	ds_read_b128 v[198:201], v249 offset:5120
	ds_read_b128 v[202:205], v249 offset:6144
	ds_read_b128 v[206:209], v249 offset:7168
	global_load_lds_dwordx4 v[162:163], off
	v_lshl_add_u64 v[162:163], s[4:5], 0, v[144:145]
	s_add_i32 m0, s7, 0xe000
	s_nop 0
	global_load_lds_dwordx4 v[162:163], off
	s_waitcnt vmcnt(8)
	s_waitcnt lgkmcnt(0)
	s_barrier
	s_setprio 1
	s_waitcnt lgkmcnt(0)
	v_mfma_f32_16x16x32_bf16 v[124:127], v[128:131], v[178:181], v[124:127]
	v_mfma_f32_16x16x32_bf16 v[108:111], v[136:139], v[178:181], v[108:111]
	v_mfma_f32_16x16x32_bf16 v[120:123], v[128:131], v[186:189], v[120:123]
	v_mfma_f32_16x16x32_bf16 v[104:107], v[136:139], v[186:189], v[104:107]
	s_setprio 0
	s_setprio 1
	v_mfma_f32_16x16x32_bf16 v[116:119], v[128:131], v[194:197], v[116:119]
	v_mfma_f32_16x16x32_bf16 v[100:103], v[136:139], v[194:197], v[100:103]
	v_mfma_f32_16x16x32_bf16 v[112:115], v[128:131], v[202:205], v[112:115]
	v_mfma_f32_16x16x32_bf16 v[96:99], v[136:139], v[202:205], v[96:99]
	s_setprio 0
	s_setprio 1
	v_mfma_f32_16x16x32_bf16 v[124:127], v[132:135], v[182:185], v[124:127]
	v_mfma_f32_16x16x32_bf16 v[108:111], v[146:149], v[182:185], v[108:111]
	v_mfma_f32_16x16x32_bf16 v[120:123], v[132:135], v[190:193], v[120:123]
	v_mfma_f32_16x16x32_bf16 v[104:107], v[146:149], v[190:193], v[104:107]
	s_setprio 0
	s_setprio 1
	v_mfma_f32_16x16x32_bf16 v[116:119], v[132:135], v[198:201], v[116:119]
	v_mfma_f32_16x16x32_bf16 v[100:103], v[146:149], v[198:201], v[100:103]
	v_mfma_f32_16x16x32_bf16 v[112:115], v[132:135], v[206:209], v[112:115]
	v_mfma_f32_16x16x32_bf16 v[96:99], v[146:149], v[206:209], v[96:99]
	s_setprio 0
	s_setprio 1
	v_mfma_f32_16x16x32_bf16 v[92:95], v[150:153], v[178:181], v[92:95]
	v_mfma_f32_16x16x32_bf16 v[76:79], v[158:161], v[178:181], v[76:79]
	v_mfma_f32_16x16x32_bf16 v[88:91], v[150:153], v[186:189], v[88:91]
	v_mfma_f32_16x16x32_bf16 v[72:75], v[158:161], v[186:189], v[72:75]
	s_setprio 0
	s_setprio 1
	v_mfma_f32_16x16x32_bf16 v[84:87], v[150:153], v[194:197], v[84:87]
	v_mfma_f32_16x16x32_bf16 v[68:71], v[158:161], v[194:197], v[68:71]
	v_mfma_f32_16x16x32_bf16 v[80:83], v[150:153], v[202:205], v[80:83]
	v_mfma_f32_16x16x32_bf16 v[64:67], v[158:161], v[202:205], v[64:67]
	s_setprio 0
	s_setprio 1
	v_mfma_f32_16x16x32_bf16 v[92:95], v[154:157], v[182:185], v[92:95]
	v_mfma_f32_16x16x32_bf16 v[76:79], v[174:177], v[182:185], v[76:79]
	v_mfma_f32_16x16x32_bf16 v[88:91], v[154:157], v[190:193], v[88:91]
	v_mfma_f32_16x16x32_bf16 v[72:75], v[174:177], v[190:193], v[72:75]
	s_setprio 0
	s_setprio 1
	v_mfma_f32_16x16x32_bf16 v[84:87], v[154:157], v[198:201], v[84:87]
	v_mfma_f32_16x16x32_bf16 v[68:71], v[174:177], v[198:201], v[68:71]
	v_mfma_f32_16x16x32_bf16 v[80:83], v[154:157], v[206:209], v[80:83]
	v_mfma_f32_16x16x32_bf16 v[64:67], v[174:177], v[206:209], v[64:67]
	s_setprio 0
	s_barrier
	s_add_i32 s71, s71, s6
	v_lshl_add_u64 v[162:163], s[16:17], 0, v[164:165]
	s_mov_b32 m0, s71
	ds_read_b128 v[178:181], v249 offset:16384
	ds_read_b128 v[182:185], v249 offset:17408
	ds_read_b128 v[186:189], v249 offset:18432
	ds_read_b128 v[190:193], v249 offset:19456
	ds_read_b128 v[194:197], v249 offset:20480
	ds_read_b128 v[198:201], v249 offset:21504
	ds_read_b128 v[202:205], v249 offset:22528
	ds_read_b128 v[206:209], v249 offset:23552
	global_load_lds_dwordx4 v[162:163], off
	s_add_i32 m0, s71, 0x2000
	s_add_u32 s92, s16, 0x40000
	v_lshl_add_u64 v[210:211], s[16:17], 0, v[140:141]
	s_addc_u32 s93, s17, 0
	s_add_i32 s71, s79, s6
	global_load_lds_dwordx4 v[210:211], off
	v_lshl_add_u64 v[212:213], s[92:93], 0, v[164:165]
	s_mov_b32 m0, s71
	v_lshl_add_u64 v[214:215], s[18:19], 0, v[140:141]
	global_load_lds_dwordx4 v[212:213], off
	v_lshl_add_u64 v[212:213], s[92:93], 0, v[140:141]
	s_add_i32 m0, s71, 0x2000
	s_nop 0
	global_load_lds_dwordx4 v[212:213], off
	v_lshl_add_u64 v[212:213], s[18:19], 0, v[164:165]
	s_mov_b32 m0, s7
	s_nop 0
	global_load_lds_dwordx4 v[212:213], off
	s_mov_b32 m0, s58
	s_nop 0
	global_load_lds_dwordx4 v[214:215], off
	s_waitcnt vmcnt(8)
	s_waitcnt lgkmcnt(0)
	s_barrier
; #define PG8_STAGE(bufoff, gbase, voff) do { _Pragma("unroll") for (int _i = 0; _i < 2; ++_i) \
;         __builtin_amdgcn_global_load_lds((const unsigned*)((const char*)(gbase) + (voff)[_i]), (PG8_LAS unsigned*)(lds + (bufoff) + ldsw + _i * 8192), 16, 0, 0); } while (0)
; #define PG8_LDA(dst, b, h) do { _Pragma("unroll") for (int m = 0; m < 4; ++m) _Pragma("unroll") for (int k = 0; k < 2; ++k) dst[m][k] = *(const PG8_LAS bf16x8*)(lds + PG8_SA(b, h) + aoff + m * 2048 + k * 1024); } while (0)
; #define PG8_LDB(dst, b, h) do { _Pragma("unroll") for (int n = 0; n < 2; ++n) _Pragma("unroll") for (int k = 0; k < 2; ++k) dst[n][k] = *(const PG8_LAS bf16x8*)(lds + PG8_SB(b, h) + boff + n * 2048 + k * 1024); } while (0)
; #define PG8_MMA(ai, bj, At, Bt) do { __builtin_amdgcn_s_setprio(1); _Pragma("unroll") for (int m = 0; m < 4; ++m) _Pragma("unroll") for (int n = 0; n < 2; ++n) _Pragma("unroll") for (int k = 0; k < 2; ++k) \
;         acc[ai][bj][m][n] = __builtin_amdgcn_mfma_f32_16x16x32_bf16(Bt[n][k], At[m][k], acc[ai][bj][m][n], 0, 0, 0); __builtin_amdgcn_s_setprio(0); } while (0)
; #define PG8_WAIT_V(n) asm volatile("s_waitcnt vmcnt(" #n ")" ::: "memory")
; #define PG8_WAIT_L(n) asm volatile("s_waitcnt lgkmcnt(" #n ")" ::: "memory")
; #define PG8_BAR __builtin_amdgcn_s_barrier()
; #define PG8_SCHED __builtin_amdgcn_sched_barrier(0)
; template <class Epi, class Sched, bool ALIGN_EPI, bool SP2, int KC>
; __device__ __forceinline__ void gemm_phase(PG8_LAS unsigned char* lds, const Gemm g, const Sched& S, const Epi& E, const int tid) {
;     ...
;             PG8_WAIT_V(8); PG8_WAIT_L(0); PG8_BAR; PG8_MMA(1, 0, At, B0); PG8_MMA(1, 1, At, B1); PG8_BAR; PG8_SCHED;
;             PG8_LDB(B0, 1, 0); PG8_LDB(B1, 1, 1); PG8_SCHED; PG8_LDA(At, 1, 0); PG8_STAGE(PG8_SA(0, 1), a2 + hstep, voffA);
;             PG8_WAIT_V(8); PG8_WAIT_L(0); PG8_BAR; PG8_MMA(0, 0, At, B0); PG8_MMA(0, 1, At, B1); PG8_BAR; PG8_SCHED;
	s_setprio 1
	s_waitcnt lgkmcnt(0)
	v_mfma_f32_16x16x32_bf16 v[60:63], v[128:131], v[178:181], v[60:63]
	v_mfma_f32_16x16x32_bf16 v[44:47], v[136:139], v[178:181], v[44:47]
	v_mfma_f32_16x16x32_bf16 v[56:59], v[128:131], v[186:189], v[56:59]
	v_mfma_f32_16x16x32_bf16 v[40:43], v[136:139], v[186:189], v[40:43]
	s_setprio 0
	s_setprio 1
	v_mfma_f32_16x16x32_bf16 v[52:55], v[128:131], v[194:197], v[52:55]
	v_mfma_f32_16x16x32_bf16 v[36:39], v[136:139], v[194:197], v[36:39]
	v_mfma_f32_16x16x32_bf16 v[48:51], v[128:131], v[202:205], v[48:51]
	v_mfma_f32_16x16x32_bf16 v[32:35], v[136:139], v[202:205], v[32:35]
	s_setprio 0
	s_setprio 1
	v_mfma_f32_16x16x32_bf16 v[60:63], v[132:135], v[182:185], v[60:63]
	v_mfma_f32_16x16x32_bf16 v[44:47], v[146:149], v[182:185], v[44:47]
	v_mfma_f32_16x16x32_bf16 v[56:59], v[132:135], v[190:193], v[56:59]
	v_mfma_f32_16x16x32_bf16 v[40:43], v[146:149], v[190:193], v[40:43]
	s_setprio 0
	s_setprio 1
	v_mfma_f32_16x16x32_bf16 v[52:55], v[132:135], v[198:201], v[52:55]
	v_mfma_f32_16x16x32_bf16 v[36:39], v[146:149], v[198:201], v[36:39]
	v_mfma_f32_16x16x32_bf16 v[48:51], v[132:135], v[206:209], v[48:51]
	v_mfma_f32_16x16x32_bf16 v[32:35], v[146:149], v[206:209], v[32:35]
	s_setprio 0
	s_setprio 1
	v_mfma_f32_16x16x32_bf16 v[28:31], v[150:153], v[178:181], v[28:31]
	v_mfma_f32_16x16x32_bf16 v[12:15], v[158:161], v[178:181], v[12:15]
	v_mfma_f32_16x16x32_bf16 v[24:27], v[150:153], v[186:189], v[24:27]
	v_mfma_f32_16x16x32_bf16 v[8:11], v[158:161], v[186:189], v[8:11]
	s_setprio 0
	s_setprio 1
	v_mfma_f32_16x16x32_bf16 v[20:23], v[150:153], v[194:197], v[20:23]
	v_mfma_f32_16x16x32_bf16 v[4:7], v[158:161], v[194:197], v[4:7]
	v_mfma_f32_16x16x32_bf16 v[16:19], v[150:153], v[202:205], v[16:19]
	v_mfma_f32_16x16x32_bf16 v[0:3], v[158:161], v[202:205], v[0:3]
	s_setprio 0
	s_setprio 1
	v_mfma_f32_16x16x32_bf16 v[28:31], v[154:157], v[182:185], v[28:31]
	v_mfma_f32_16x16x32_bf16 v[12:15], v[174:177], v[182:185], v[12:15]
	v_mfma_f32_16x16x32_bf16 v[24:27], v[154:157], v[190:193], v[24:27]
	v_mfma_f32_16x16x32_bf16 v[8:11], v[174:177], v[190:193], v[8:11]
	s_setprio 0
	s_setprio 1
	v_mfma_f32_16x16x32_bf16 v[20:23], v[154:157], v[198:201], v[20:23]
	v_mfma_f32_16x16x32_bf16 v[4:7], v[174:177], v[198:201], v[4:7]
	v_mfma_f32_16x16x32_bf16 v[16:19], v[154:157], v[206:209], v[16:19]
	v_mfma_f32_16x16x32_bf16 v[0:3], v[174:177], v[206:209], v[0:3]
	s_setprio 0
	s_barrier
	s_add_i32 s71, 0, 0x18000
	s_add_i32 s79, 0, 0x1c000
	v_add_u32_e32 v146, s71, v245
	v_add_u32_e32 v174, s79, v245
	ds_read_b128 v[128:131], v146
	ds_read_b128 v[132:135], v146 offset:1024
	ds_read_b128 v[136:139], v146 offset:2048
	ds_read_b128 v[146:149], v146 offset:3072
	ds_read_b128 v[150:153], v174
	ds_read_b128 v[154:157], v174 offset:1024
	ds_read_b128 v[158:161], v174 offset:2048
	ds_read_b128 v[174:177], v174 offset:3072
	s_add_u32 s18, s18, 0x40000
	s_addc_u32 s19, s19, 0
	s_mov_b32 m0, s59
	v_lshl_add_u64 v[216:217], s[18:19], 0, v[164:165]
	ds_read_b128 v[178:181], v249 offset:32768
	ds_read_b128 v[182:185], v249 offset:33792
	ds_read_b128 v[186:189], v249 offset:34816
	ds_read_b128 v[190:193], v249 offset:35840
	ds_read_b128 v[194:197], v249 offset:36864
	ds_read_b128 v[198:201], v249 offset:37888
	ds_read_b128 v[202:205], v249 offset:38912
	ds_read_b128 v[206:209], v249 offset:39936
	global_load_lds_dwordx4 v[216:217], off
	v_lshl_add_u64 v[216:217], s[18:19], 0, v[140:141]
	s_mov_b32 m0, s74
	s_nop 0
	global_load_lds_dwordx4 v[216:217], off
	s_waitcnt vmcnt(8)
	s_waitcnt lgkmcnt(0)
	s_barrier
	s_setprio 1
	s_waitcnt lgkmcnt(0)
	v_mfma_f32_16x16x32_bf16 v[124:127], v[128:131], v[178:181], v[124:127]
	v_mfma_f32_16x16x32_bf16 v[108:111], v[136:139], v[178:181], v[108:111]
	v_mfma_f32_16x16x32_bf16 v[120:123], v[128:131], v[186:189], v[120:123]
	v_mfma_f32_16x16x32_bf16 v[104:107], v[136:139], v[186:189], v[104:107]
	s_setprio 0
	s_setprio 1
	v_mfma_f32_16x16x32_bf16 v[116:119], v[128:131], v[194:197], v[116:119]
	v_mfma_f32_16x16x32_bf16 v[100:103], v[136:139], v[194:197], v[100:103]
	v_mfma_f32_16x16x32_bf16 v[112:115], v[128:131], v[202:205], v[112:115]
	v_mfma_f32_16x16x32_bf16 v[96:99], v[136:139], v[202:205], v[96:99]
	s_setprio 0
	s_setprio 1
	v_mfma_f32_16x16x32_bf16 v[124:127], v[132:135], v[182:185], v[124:127]
	v_mfma_f32_16x16x32_bf16 v[108:111], v[146:149], v[182:185], v[108:111]
	v_mfma_f32_16x16x32_bf16 v[120:123], v[132:135], v[190:193], v[120:123]
	v_mfma_f32_16x16x32_bf16 v[104:107], v[146:149], v[190:193], v[104:107]
	s_setprio 0
	s_setprio 1
	v_mfma_f32_16x16x32_bf16 v[116:119], v[132:135], v[198:201], v[116:119]
	v_mfma_f32_16x16x32_bf16 v[100:103], v[146:149], v[198:201], v[100:103]
	v_mfma_f32_16x16x32_bf16 v[112:115], v[132:135], v[206:209], v[112:115]
	v_mfma_f32_16x16x32_bf16 v[96:99], v[146:149], v[206:209], v[96:99]
	s_setprio 0
	s_setprio 1
	v_mfma_f32_16x16x32_bf16 v[92:95], v[150:153], v[178:181], v[92:95]
	v_mfma_f32_16x16x32_bf16 v[76:79], v[158:161], v[178:181], v[76:79]
	v_mfma_f32_16x16x32_bf16 v[88:91], v[150:153], v[186:189], v[88:91]
	v_mfma_f32_16x16x32_bf16 v[72:75], v[158:161], v[186:189], v[72:75]
	s_setprio 0
	s_setprio 1
	v_mfma_f32_16x16x32_bf16 v[84:87], v[150:153], v[194:197], v[84:87]
	v_mfma_f32_16x16x32_bf16 v[68:71], v[158:161], v[194:197], v[68:71]
	v_mfma_f32_16x16x32_bf16 v[80:83], v[150:153], v[202:205], v[80:83]
	v_mfma_f32_16x16x32_bf16 v[64:67], v[158:161], v[202:205], v[64:67]
	s_setprio 0
	s_setprio 1
	v_mfma_f32_16x16x32_bf16 v[92:95], v[154:157], v[182:185], v[92:95]
	v_mfma_f32_16x16x32_bf16 v[76:79], v[174:177], v[182:185], v[76:79]
	v_mfma_f32_16x16x32_bf16 v[88:91], v[154:157], v[190:193], v[88:91]
	v_mfma_f32_16x16x32_bf16 v[72:75], v[174:177], v[190:193], v[72:75]
	s_setprio 0
	s_setprio 1
	v_mfma_f32_16x16x32_bf16 v[84:87], v[154:157], v[198:201], v[84:87]
	v_mfma_f32_16x16x32_bf16 v[68:71], v[174:177], v[198:201], v[68:71]
	v_mfma_f32_16x16x32_bf16 v[80:83], v[154:157], v[206:209], v[80:83]
	v_mfma_f32_16x16x32_bf16 v[64:67], v[174:177], v[206:209], v[64:67]
	s_setprio 0
	s_barrier
; #define PG8_STAGE(bufoff, gbase, voff) do { _Pragma("unroll") for (int _i = 0; _i < 2; ++_i) \
;         __builtin_amdgcn_global_load_lds((const unsigned*)((const char*)(gbase) + (voff)[_i]), (PG8_LAS unsigned*)(lds + (bufoff) + ldsw + _i * 8192), 16, 0, 0); } while (0)
; #define PG8_LDA(dst, b, h) do { _Pragma("unroll") for (int m = 0; m < 4; ++m) _Pragma("unroll") for (int k = 0; k < 2; ++k) dst[m][k] = *(const PG8_LAS bf16x8*)(lds + PG8_SA(b, h) + aoff + m * 2048 + k * 1024); } while (0)
; #define PG8_MMA(ai, bj, At, Bt) do { __builtin_amdgcn_s_setprio(1); _Pragma("unroll") for (int m = 0; m < 4; ++m) _Pragma("unroll") for (int n = 0; n < 2; ++n) _Pragma("unroll") for (int k = 0; k < 2; ++k) \
;         acc[ai][bj][m][n] = __builtin_amdgcn_mfma_f32_16x16x32_bf16(Bt[n][k], At[m][k], acc[ai][bj][m][n], 0, 0, 0); __builtin_amdgcn_s_setprio(0); } while (0)
; #define PG8_WAIT_V(n) asm volatile("s_waitcnt vmcnt(" #n ")" ::: "memory")
; #define PG8_WAIT_L(n) asm volatile("s_waitcnt lgkmcnt(" #n ")" ::: "memory")
; #define PG8_BAR __builtin_amdgcn_s_barrier()
; #define PG8_SCHED __builtin_amdgcn_sched_barrier(0)
; template <class Epi, class Sched, bool ALIGN_EPI, bool SP2, int KC>
; __device__ __forceinline__ void gemm_phase(PG8_LAS unsigned char* lds, const Gemm g, const Sched& S, const Epi& E, const int tid) {
;     ...
;             PG8_LDA(At, 1, 1); PG8_STAGE(PG8_SB(1, 0), b3, voffB); PG8_STAGE(PG8_SB(1, 1), b3 + hstep, voffB); PG8_STAGE(PG8_SA(1, 0), a3, voffA);
;             PG8_WAIT_V(8); PG8_WAIT_L(0); PG8_BAR; PG8_MMA(1, 0, At, B0); PG8_MMA(1, 1, At, B1); PG8_BAR; PG8_SCHED;
	s_add_i32 s18, s71, s6
	v_lshl_add_u64 v[162:163], v[162:163], 0, s[86:87]
	s_mov_b32 m0, s18
	ds_read_b128 v[178:181], v249 offset:49152
	ds_read_b128 v[182:185], v249 offset:50176
	ds_read_b128 v[186:189], v249 offset:51200
	ds_read_b128 v[190:193], v249 offset:52224
	ds_read_b128 v[194:197], v249 offset:53248
	ds_read_b128 v[198:201], v249 offset:54272
	ds_read_b128 v[202:205], v249 offset:55296
	ds_read_b128 v[206:209], v249 offset:56320
	global_load_lds_dwordx4 v[162:163], off
	s_add_i32 m0, s18, 0x2000
	s_add_u32 s16, s16, 0x40080
	v_lshl_add_u64 v[162:163], v[210:211], 0, s[86:87]
	s_addc_u32 s17, s17, 0
	s_add_i32 s18, s79, s6
	global_load_lds_dwordx4 v[162:163], off
	v_lshl_add_u64 v[162:163], s[16:17], 0, v[164:165]
	s_mov_b32 m0, s18
	s_nop 0
	global_load_lds_dwordx4 v[162:163], off
	v_lshl_add_u64 v[162:163], s[16:17], 0, v[140:141]
	s_add_i32 m0, s18, 0x2000
	s_nop 0
	global_load_lds_dwordx4 v[162:163], off
	v_lshl_add_u64 v[162:163], v[212:213], 0, s[86:87]
	s_mov_b32 m0, s76
	s_nop 0
	global_load_lds_dwordx4 v[162:163], off
	v_lshl_add_u64 v[162:163], v[214:215], 0, s[86:87]
	s_mov_b32 m0, s77
	s_nop 0
	global_load_lds_dwordx4 v[162:163], off
	s_waitcnt vmcnt(8)
	s_waitcnt lgkmcnt(0)
	s_barrier
	s_setprio 1
	s_waitcnt lgkmcnt(0)
	v_mfma_f32_16x16x32_bf16 v[60:63], v[128:131], v[178:181], v[60:63]
	v_mfma_f32_16x16x32_bf16 v[44:47], v[136:139], v[178:181], v[44:47]
	v_mfma_f32_16x16x32_bf16 v[56:59], v[128:131], v[186:189], v[56:59]
	v_mfma_f32_16x16x32_bf16 v[40:43], v[136:139], v[186:189], v[40:43]
	s_setprio 0
	s_setprio 1
	v_mfma_f32_16x16x32_bf16 v[52:55], v[128:131], v[194:197], v[52:55]
	v_mfma_f32_16x16x32_bf16 v[36:39], v[136:139], v[194:197], v[36:39]
	v_mfma_f32_16x16x32_bf16 v[48:51], v[128:131], v[202:205], v[48:51]
	v_mfma_f32_16x16x32_bf16 v[32:35], v[136:139], v[202:205], v[32:35]
	s_setprio 0
	s_setprio 1
	v_mfma_f32_16x16x32_bf16 v[60:63], v[132:135], v[182:185], v[60:63]
	v_mfma_f32_16x16x32_bf16 v[44:47], v[146:149], v[182:185], v[44:47]
	v_mfma_f32_16x16x32_bf16 v[56:59], v[132:135], v[190:193], v[56:59]
	v_mfma_f32_16x16x32_bf16 v[40:43], v[146:149], v[190:193], v[40:43]
	s_setprio 0
	s_setprio 1
	v_mfma_f32_16x16x32_bf16 v[52:55], v[132:135], v[198:201], v[52:55]
	v_mfma_f32_16x16x32_bf16 v[36:39], v[146:149], v[198:201], v[36:39]
	v_mfma_f32_16x16x32_bf16 v[48:51], v[132:135], v[206:209], v[48:51]
	v_mfma_f32_16x16x32_bf16 v[32:35], v[146:149], v[206:209], v[32:35]
	s_setprio 0
	s_setprio 1
	v_mfma_f32_16x16x32_bf16 v[28:31], v[150:153], v[178:181], v[28:31]
	v_mfma_f32_16x16x32_bf16 v[12:15], v[158:161], v[178:181], v[12:15]
	v_mfma_f32_16x16x32_bf16 v[24:27], v[150:153], v[186:189], v[24:27]
	v_mfma_f32_16x16x32_bf16 v[8:11], v[158:161], v[186:189], v[8:11]
	s_setprio 0
	s_setprio 1
	v_mfma_f32_16x16x32_bf16 v[20:23], v[150:153], v[194:197], v[20:23]
	v_mfma_f32_16x16x32_bf16 v[4:7], v[158:161], v[194:197], v[4:7]
	v_mfma_f32_16x16x32_bf16 v[16:19], v[150:153], v[202:205], v[16:19]
	v_mfma_f32_16x16x32_bf16 v[0:3], v[158:161], v[202:205], v[0:3]
	s_setprio 0
	s_setprio 1
	v_mfma_f32_16x16x32_bf16 v[28:31], v[154:157], v[182:185], v[28:31]
	v_mfma_f32_16x16x32_bf16 v[12:15], v[174:177], v[182:185], v[12:15]
	v_mfma_f32_16x16x32_bf16 v[24:27], v[154:157], v[190:193], v[24:27]
	v_mfma_f32_16x16x32_bf16 v[8:11], v[174:177], v[190:193], v[8:11]
	s_setprio 0
	s_setprio 1
	v_mfma_f32_16x16x32_bf16 v[20:23], v[154:157], v[198:201], v[20:23]
	v_mfma_f32_16x16x32_bf16 v[4:7], v[174:177], v[198:201], v[4:7]
	v_mfma_f32_16x16x32_bf16 v[16:19], v[154:157], v[206:209], v[16:19]
	v_mfma_f32_16x16x32_bf16 v[0:3], v[174:177], v[206:209], v[0:3]
	s_setprio 0
	s_barrier
	s_add_i32 s70, s70, 2
	s_add_u32 s4, s4, 0x100
	s_addc_u32 s5, s5, 0
	s_add_u32 s64, s64, 0x100
	s_addc_u32 s65, s65, 0
	s_cmp_gt_u32 s70, 13
	s_cbranch_scc0 .LBB0_162
	s_and_b64 vcc, exec, s[30:31]
	s_cbranch_vccz .LBB0_165
	s_barrier

; #define PG8_STAGE(bufoff, gbase, voff) do { _Pragma("unroll") for (int _i = 0; _i < 2; ++_i) \
;         __builtin_amdgcn_global_load_lds((const unsigned*)((const char*)(gbase) + (voff)[_i]), (PG8_LAS unsigned*)(lds + (bufoff) + ldsw + _i * 8192), 16, 0, 0); } while (0)
; #define PG8_LDA(dst, b, h) do { _Pragma("unroll") for (int m = 0; m < 4; ++m) _Pragma("unroll") for (int k = 0; k < 2; ++k) dst[m][k] = *(const PG8_LAS bf16x8*)(lds + PG8_SA(b, h) + aoff + m * 2048 + k * 1024); } while (0)
; #define PG8_LDB(dst, b, h) do { _Pragma("unroll") for (int n = 0; n < 2; ++n) _Pragma("unroll") for (int k = 0; k < 2; ++k) dst[n][k] = *(const PG8_LAS bf16x8*)(lds + PG8_SB(b, h) + boff + n * 2048 + k * 1024); } while (0)
; #define PG8_MMA(ai, bj, At, Bt) do { __builtin_amdgcn_s_setprio(1); _Pragma("unroll") for (int m = 0; m < 4; ++m) _Pragma("unroll") for (int n = 0; n < 2; ++n) _Pragma("unroll") for (int k = 0; k < 2; ++k) \
;         acc[ai][bj][m][n] = __builtin_amdgcn_mfma_f32_16x16x32_bf16(Bt[n][k], At[m][k], acc[ai][bj][m][n], 0, 0, 0); __builtin_amdgcn_s_setprio(0); } while (0)
; #define PG8_WAIT_V(n) asm volatile("s_waitcnt vmcnt(" #n ")" ::: "memory")
; #define PG8_WAIT_L(n) asm volatile("s_waitcnt lgkmcnt(" #n ")" ::: "memory")
; #define PG8_BAR __builtin_amdgcn_s_barrier()
; template <class Epi, class Sched, bool ALIGN_EPI, bool SP2, int KC>
; __device__ __forceinline__ void gemm_phase(PG8_LAS unsigned char* lds, const Gemm g, const Sched& S, const Epi& E, const int tid) {
;     ...
;             const char* a1 = cA + (size_t)(t + 1) * kstep;
;             const char* a2 = last ? nA : cA + (size_t)(t + 2) * kstep; const char* b2 = last ? nB : cB + (size_t)(t + 2) * kstep;
;             const char* a3 = a2 + kstep; const char* b3 = b2 + kstep;
;             if (last && has_next) S.a_ready(nxt);
;             if constexpr (SP2) {
;             PG8_LDB(B0, 0, 0); PG8_LDB(B1, 0, 1); PG8_SCHED; PG8_LDA(At, 0, 0); PG8_STAGE(PG8_SA(1, 1), a1 + hstep, voffA);
;             PG8_WAIT_V(8); PG8_WAIT_L(0); PG8_BAR; PG8_MMA(0, 0, At, B0); PG8_MMA(0, 1, At, B1); PG8_BAR; PG8_SCHED;
;             PG8_LDA(At, 0, 1); PG8_STAGE(PG8_SB(0, 0), b2, voffB); PG8_STAGE(PG8_SB(0, 1), b2 + hstep, voffB); PG8_STAGE(PG8_SA(0, 0), a2, voffA);
;             PG8_WAIT_V(8); PG8_WAIT_L(0); PG8_BAR; PG8_MMA(1, 0, At, B0); PG8_MMA(1, 1, At, B1); PG8_BAR; PG8_SCHED;
.LBB0_560:
	s_add_u32 s16, s4, 0x100
	s_addc_u32 s17, s5, 0
	s_add_i32 s49, 0, 0x10000
	s_cmp_eq_u32 s48, 40
	s_cselect_b32 s39, s27, s17
	s_cselect_b32 s38, s26, s16
	s_cselect_b32 s37, s29, s35
	s_cselect_b32 s36, s28, s31
	s_add_i32 s58, 0, 0x14000
	v_add_u32_e32 v146, s49, v212
	v_add_u32_e32 v162, s58, v212
	ds_read_b128 v[128:131], v146
	ds_read_b128 v[132:135], v146 offset:1024
	ds_read_b128 v[142:145], v146 offset:2048
	ds_read_b128 v[146:149], v146 offset:3072
	ds_read_b128 v[150:153], v162
	ds_read_b128 v[154:157], v162 offset:1024
	ds_read_b128 v[158:161], v162 offset:2048
	ds_read_b128 v[174:177], v162 offset:3072
	v_lshl_add_u64 v[162:163], s[4:5], 0, v[138:139]
	s_add_i32 m0, s7, 0xc000
	ds_read_b128 v[178:181], v216
	ds_read_b128 v[182:185], v216 offset:1024
	ds_read_b128 v[186:189], v216 offset:2048
	ds_read_b128 v[190:193], v216 offset:3072
	ds_read_b128 v[194:197], v216 offset:4096
	ds_read_b128 v[198:201], v216 offset:5120
	ds_read_b128 v[202:205], v216 offset:6144
	ds_read_b128 v[206:209], v216 offset:7168
	global_load_lds_dwordx4 v[162:163], off
	v_lshl_add_u64 v[162:163], s[4:5], 0, v[140:141]
	s_add_i32 m0, s7, 0xe000
	s_nop 0
	global_load_lds_dwordx4 v[162:163], off
	s_waitcnt vmcnt(8)
	s_waitcnt lgkmcnt(0)
	s_barrier
	s_setprio 1
	s_waitcnt lgkmcnt(0)
	v_mfma_f32_16x16x32_bf16 v[60:63], v[128:131], v[178:181], v[60:63]
	v_mfma_f32_16x16x32_bf16 v[92:95], v[142:145], v[178:181], v[92:95]
	v_mfma_f32_16x16x32_bf16 v[56:59], v[128:131], v[186:189], v[56:59]
	v_mfma_f32_16x16x32_bf16 v[84:87], v[142:145], v[186:189], v[84:87]
	s_setprio 0
	s_setprio 1
	v_mfma_f32_16x16x32_bf16 v[48:51], v[128:131], v[194:197], v[48:51]
	v_mfma_f32_16x16x32_bf16 v[80:83], v[142:145], v[194:197], v[80:83]
	v_mfma_f32_16x16x32_bf16 v[40:43], v[128:131], v[202:205], v[40:43]
	v_mfma_f32_16x16x32_bf16 v[72:75], v[142:145], v[202:205], v[72:75]
	s_setprio 0
	s_setprio 1
	v_mfma_f32_16x16x32_bf16 v[60:63], v[132:135], v[182:185], v[60:63]
	v_mfma_f32_16x16x32_bf16 v[92:95], v[146:149], v[182:185], v[92:95]
	v_mfma_f32_16x16x32_bf16 v[56:59], v[132:135], v[190:193], v[56:59]
	v_mfma_f32_16x16x32_bf16 v[84:87], v[146:149], v[190:193], v[84:87]
	s_setprio 0
	s_setprio 1
	v_mfma_f32_16x16x32_bf16 v[48:51], v[132:135], v[198:201], v[48:51]
	v_mfma_f32_16x16x32_bf16 v[80:83], v[146:149], v[198:201], v[80:83]
	v_mfma_f32_16x16x32_bf16 v[40:43], v[132:135], v[206:209], v[40:43]
	v_mfma_f32_16x16x32_bf16 v[72:75], v[146:149], v[206:209], v[72:75]
	s_setprio 0
	s_setprio 1
	v_mfma_f32_16x16x32_bf16 v[120:123], v[150:153], v[178:181], v[120:123]
	v_mfma_f32_16x16x32_bf16 v[124:127], v[158:161], v[178:181], v[124:127]
	v_mfma_f32_16x16x32_bf16 v[112:115], v[150:153], v[186:189], v[112:115]
	v_mfma_f32_16x16x32_bf16 v[116:119], v[158:161], v[186:189], v[116:119]
	s_setprio 0
	s_setprio 1
	v_mfma_f32_16x16x32_bf16 v[108:111], v[150:153], v[194:197], v[108:111]
	v_mfma_f32_16x16x32_bf16 v[104:107], v[158:161], v[194:197], v[104:107]
	v_mfma_f32_16x16x32_bf16 v[100:103], v[150:153], v[202:205], v[100:103]
	v_mfma_f32_16x16x32_bf16 v[96:99], v[158:161], v[202:205], v[96:99]
	s_setprio 0
	s_setprio 1
	v_mfma_f32_16x16x32_bf16 v[120:123], v[154:157], v[182:185], v[120:123]
	v_mfma_f32_16x16x32_bf16 v[124:127], v[174:177], v[182:185], v[124:127]
	v_mfma_f32_16x16x32_bf16 v[112:115], v[154:157], v[190:193], v[112:115]
	v_mfma_f32_16x16x32_bf16 v[116:119], v[174:177], v[190:193], v[116:119]
	s_setprio 0
	s_setprio 1
	v_mfma_f32_16x16x32_bf16 v[108:111], v[154:157], v[198:201], v[108:111]
	v_mfma_f32_16x16x32_bf16 v[104:107], v[174:177], v[198:201], v[104:107]
	v_mfma_f32_16x16x32_bf16 v[100:103], v[154:157], v[206:209], v[100:103]
	v_mfma_f32_16x16x32_bf16 v[96:99], v[174:177], v[206:209], v[96:99]
	s_setprio 0
	s_barrier
	s_add_i32 s4, s49, s6
	v_lshl_add_u64 v[162:163], s[36:37], 0, v[164:165]
	s_mov_b32 m0, s4
	ds_read_b128 v[178:181], v216 offset:16384
	ds_read_b128 v[182:185], v216 offset:17408
	ds_read_b128 v[186:189], v216 offset:18432
	ds_read_b128 v[190:193], v216 offset:19456
	ds_read_b128 v[194:197], v216 offset:20480
	ds_read_b128 v[198:201], v216 offset:21504
	ds_read_b128 v[202:205], v216 offset:22528
	ds_read_b128 v[206:209], v216 offset:23552
	global_load_lds_dwordx4 v[162:163], off
	s_add_i32 m0, s4, 0x2000
	s_add_u32 s4, s36, 0xb0000
	v_lshl_add_u64 v[210:211], s[36:37], 0, v[136:137]
	s_addc_u32 s5, s37, 0
	s_add_i32 s49, s58, s6
	global_load_lds_dwordx4 v[210:211], off
	v_lshl_add_u64 v[220:221], s[4:5], 0, v[164:165]
	s_mov_b32 m0, s49
	v_lshl_add_u64 v[222:223], s[38:39], 0, v[136:137]
	global_load_lds_dwordx4 v[220:221], off
	v_lshl_add_u64 v[220:221], s[4:5], 0, v[136:137]
	s_add_i32 m0, s49, 0x2000
	s_nop 0
	global_load_lds_dwordx4 v[220:221], off
	v_lshl_add_u64 v[220:221], s[38:39], 0, v[164:165]
	s_mov_b32 m0, s7
	s_nop 0
	global_load_lds_dwordx4 v[220:221], off
	s_mov_b32 m0, s40
	s_nop 0
	global_load_lds_dwordx4 v[222:223], off
	s_waitcnt vmcnt(8)
	s_waitcnt lgkmcnt(0)
	s_barrier
; #define PG8_STAGE(bufoff, gbase, voff) do { _Pragma("unroll") for (int _i = 0; _i < 2; ++_i) \
;         __builtin_amdgcn_global_load_lds((const unsigned*)((const char*)(gbase) + (voff)[_i]), (PG8_LAS unsigned*)(lds + (bufoff) + ldsw + _i * 8192), 16, 0, 0); } while (0)
; #define PG8_LDA(dst, b, h) do { _Pragma("unroll") for (int m = 0; m < 4; ++m) _Pragma("unroll") for (int k = 0; k < 2; ++k) dst[m][k] = *(const PG8_LAS bf16x8*)(lds + PG8_SA(b, h) + aoff + m * 2048 + k * 1024); } while (0)
; #define PG8_LDB(dst, b, h) do { _Pragma("unroll") for (int n = 0; n < 2; ++n) _Pragma("unroll") for (int k = 0; k < 2; ++k) dst[n][k] = *(const PG8_LAS bf16x8*)(lds + PG8_SB(b, h) + boff + n * 2048 + k * 1024); } while (0)
; #define PG8_MMA(ai, bj, At, Bt) do { __builtin_amdgcn_s_setprio(1); _Pragma("unroll") for (int m = 0; m < 4; ++m) _Pragma("unroll") for (int n = 0; n < 2; ++n) _Pragma("unroll") for (int k = 0; k < 2; ++k) \
;         acc[ai][bj][m][n] = __builtin_amdgcn_mfma_f32_16x16x32_bf16(Bt[n][k], At[m][k], acc[ai][bj][m][n], 0, 0, 0); __builtin_amdgcn_s_setprio(0); } while (0)
; #define PG8_WAIT_V(n) asm volatile("s_waitcnt vmcnt(" #n ")" ::: "memory")
; #define PG8_WAIT_L(n) asm volatile("s_waitcnt lgkmcnt(" #n ")" ::: "memory")
; #define PG8_BAR __builtin_amdgcn_s_barrier()
; #define PG8_SCHED __builtin_amdgcn_sched_barrier(0)
; template <class Epi, class Sched, bool ALIGN_EPI, bool SP2, int KC>
; __device__ __forceinline__ void gemm_phase(PG8_LAS unsigned char* lds, const Gemm g, const Sched& S, const Epi& E, const int tid) {
;     ...
;             PG8_WAIT_V(8); PG8_WAIT_L(0); PG8_BAR; PG8_MMA(1, 0, At, B0); PG8_MMA(1, 1, At, B1); PG8_BAR; PG8_SCHED;
;             PG8_LDB(B0, 1, 0); PG8_LDB(B1, 1, 1); PG8_SCHED; PG8_LDA(At, 1, 0); PG8_STAGE(PG8_SA(0, 1), a2 + hstep, voffA);
;             PG8_WAIT_V(8); PG8_WAIT_L(0); PG8_BAR; PG8_MMA(0, 0, At, B0); PG8_MMA(0, 1, At, B1); PG8_BAR; PG8_SCHED;
	s_setprio 1
	s_waitcnt lgkmcnt(0)
	v_mfma_f32_16x16x32_bf16 v[88:91], v[128:131], v[178:181], v[88:91]
	v_mfma_f32_16x16x32_bf16 v[52:55], v[142:145], v[178:181], v[52:55]
	v_mfma_f32_16x16x32_bf16 v[76:79], v[128:131], v[186:189], v[76:79]
	v_mfma_f32_16x16x32_bf16 v[44:47], v[142:145], v[186:189], v[44:47]
	s_setprio 0
	s_setprio 1
	v_mfma_f32_16x16x32_bf16 v[68:71], v[128:131], v[194:197], v[68:71]
	v_mfma_f32_16x16x32_bf16 v[36:39], v[142:145], v[194:197], v[36:39]
	v_mfma_f32_16x16x32_bf16 v[64:67], v[128:131], v[202:205], v[64:67]
	v_mfma_f32_16x16x32_bf16 v[32:35], v[142:145], v[202:205], v[32:35]
	s_setprio 0
	s_setprio 1
	v_mfma_f32_16x16x32_bf16 v[88:91], v[132:135], v[182:185], v[88:91]
	v_mfma_f32_16x16x32_bf16 v[52:55], v[146:149], v[182:185], v[52:55]
	v_mfma_f32_16x16x32_bf16 v[76:79], v[132:135], v[190:193], v[76:79]
	v_mfma_f32_16x16x32_bf16 v[44:47], v[146:149], v[190:193], v[44:47]
	s_setprio 0
	s_setprio 1
	v_mfma_f32_16x16x32_bf16 v[68:71], v[132:135], v[198:201], v[68:71]
	v_mfma_f32_16x16x32_bf16 v[36:39], v[146:149], v[198:201], v[36:39]
	v_mfma_f32_16x16x32_bf16 v[64:67], v[132:135], v[206:209], v[64:67]
	v_mfma_f32_16x16x32_bf16 v[32:35], v[146:149], v[206:209], v[32:35]
	s_setprio 0
	s_setprio 1
	v_mfma_f32_16x16x32_bf16 v[28:31], v[150:153], v[178:181], v[28:31]
	v_mfma_f32_16x16x32_bf16 v[12:15], v[158:161], v[178:181], v[12:15]
	v_mfma_f32_16x16x32_bf16 v[24:27], v[150:153], v[186:189], v[24:27]
	v_mfma_f32_16x16x32_bf16 v[8:11], v[158:161], v[186:189], v[8:11]
	s_setprio 0
	s_setprio 1
	v_mfma_f32_16x16x32_bf16 v[20:23], v[150:153], v[194:197], v[20:23]
	v_mfma_f32_16x16x32_bf16 v[4:7], v[158:161], v[194:197], v[4:7]
	v_mfma_f32_16x16x32_bf16 v[16:19], v[150:153], v[202:205], v[16:19]
	v_mfma_f32_16x16x32_bf16 v[0:3], v[158:161], v[202:205], v[0:3]
	s_setprio 0
	s_setprio 1
	v_mfma_f32_16x16x32_bf16 v[28:31], v[154:157], v[182:185], v[28:31]
	v_mfma_f32_16x16x32_bf16 v[12:15], v[174:177], v[182:185], v[12:15]
	v_mfma_f32_16x16x32_bf16 v[24:27], v[154:157], v[190:193], v[24:27]
	v_mfma_f32_16x16x32_bf16 v[8:11], v[174:177], v[190:193], v[8:11]
	s_setprio 0
	s_setprio 1
	v_mfma_f32_16x16x32_bf16 v[20:23], v[154:157], v[198:201], v[20:23]
	v_mfma_f32_16x16x32_bf16 v[4:7], v[174:177], v[198:201], v[4:7]
	v_mfma_f32_16x16x32_bf16 v[16:19], v[154:157], v[206:209], v[16:19]
	v_mfma_f32_16x16x32_bf16 v[0:3], v[174:177], v[206:209], v[0:3]
	s_setprio 0
	s_barrier
	s_add_i32 s49, 0, 0x18000
	s_add_i32 s58, 0, 0x1c000
	v_add_u32_e32 v146, s49, v212
	v_add_u32_e32 v174, s58, v212
	ds_read_b128 v[128:131], v146
	ds_read_b128 v[132:135], v146 offset:1024
	ds_read_b128 v[142:145], v146 offset:2048
	ds_read_b128 v[146:149], v146 offset:3072
	ds_read_b128 v[150:153], v174
	ds_read_b128 v[154:157], v174 offset:1024
	ds_read_b128 v[158:161], v174 offset:2048
	ds_read_b128 v[174:177], v174 offset:3072
	s_add_u32 s4, s38, 0xb0000
	s_addc_u32 s5, s39, 0
	s_mov_b32 m0, s41
	v_lshl_add_u64 v[234:235], s[4:5], 0, v[164:165]
	ds_read_b128 v[178:181], v216 offset:32768
	ds_read_b128 v[182:185], v216 offset:33792
	ds_read_b128 v[186:189], v216 offset:34816
	ds_read_b128 v[190:193], v216 offset:35840
	ds_read_b128 v[194:197], v216 offset:36864
	ds_read_b128 v[198:201], v216 offset:37888
	ds_read_b128 v[202:205], v216 offset:38912
	ds_read_b128 v[206:209], v216 offset:39936
	global_load_lds_dwordx4 v[234:235], off
	v_lshl_add_u64 v[234:235], s[4:5], 0, v[136:137]
	s_mov_b32 m0, s42
	s_nop 0
	global_load_lds_dwordx4 v[234:235], off
	s_waitcnt vmcnt(8)
	s_waitcnt lgkmcnt(0)
	s_barrier
	s_setprio 1
	s_waitcnt lgkmcnt(0)
	v_mfma_f32_16x16x32_bf16 v[60:63], v[128:131], v[178:181], v[60:63]
	v_mfma_f32_16x16x32_bf16 v[92:95], v[142:145], v[178:181], v[92:95]
	v_mfma_f32_16x16x32_bf16 v[56:59], v[128:131], v[186:189], v[56:59]
	v_mfma_f32_16x16x32_bf16 v[84:87], v[142:145], v[186:189], v[84:87]
	s_setprio 0
	s_setprio 1
	v_mfma_f32_16x16x32_bf16 v[48:51], v[128:131], v[194:197], v[48:51]
	v_mfma_f32_16x16x32_bf16 v[80:83], v[142:145], v[194:197], v[80:83]
	v_mfma_f32_16x16x32_bf16 v[40:43], v[128:131], v[202:205], v[40:43]
	v_mfma_f32_16x16x32_bf16 v[72:75], v[142:145], v[202:205], v[72:75]
	s_setprio 0
	s_setprio 1
	v_mfma_f32_16x16x32_bf16 v[60:63], v[132:135], v[182:185], v[60:63]
	v_mfma_f32_16x16x32_bf16 v[92:95], v[146:149], v[182:185], v[92:95]
	v_mfma_f32_16x16x32_bf16 v[56:59], v[132:135], v[190:193], v[56:59]
	v_mfma_f32_16x16x32_bf16 v[84:87], v[146:149], v[190:193], v[84:87]
	s_setprio 0
	s_setprio 1
	v_mfma_f32_16x16x32_bf16 v[48:51], v[132:135], v[198:201], v[48:51]
	v_mfma_f32_16x16x32_bf16 v[80:83], v[146:149], v[198:201], v[80:83]
	v_mfma_f32_16x16x32_bf16 v[40:43], v[132:135], v[206:209], v[40:43]
	v_mfma_f32_16x16x32_bf16 v[72:75], v[146:149], v[206:209], v[72:75]
	s_setprio 0
	s_setprio 1
	v_mfma_f32_16x16x32_bf16 v[120:123], v[150:153], v[178:181], v[120:123]
	v_mfma_f32_16x16x32_bf16 v[124:127], v[158:161], v[178:181], v[124:127]
	v_mfma_f32_16x16x32_bf16 v[112:115], v[150:153], v[186:189], v[112:115]
	v_mfma_f32_16x16x32_bf16 v[116:119], v[158:161], v[186:189], v[116:119]
	s_setprio 0
	s_setprio 1
	v_mfma_f32_16x16x32_bf16 v[108:111], v[150:153], v[194:197], v[108:111]
	v_mfma_f32_16x16x32_bf16 v[104:107], v[158:161], v[194:197], v[104:107]
	v_mfma_f32_16x16x32_bf16 v[100:103], v[150:153], v[202:205], v[100:103]
	v_mfma_f32_16x16x32_bf16 v[96:99], v[158:161], v[202:205], v[96:99]
	s_setprio 0
	s_setprio 1
	v_mfma_f32_16x16x32_bf16 v[120:123], v[154:157], v[182:185], v[120:123]
	v_mfma_f32_16x16x32_bf16 v[124:127], v[174:177], v[182:185], v[124:127]
	v_mfma_f32_16x16x32_bf16 v[112:115], v[154:157], v[190:193], v[112:115]
	v_mfma_f32_16x16x32_bf16 v[116:119], v[174:177], v[190:193], v[116:119]
	s_setprio 0
	s_setprio 1
	v_mfma_f32_16x16x32_bf16 v[108:111], v[154:157], v[198:201], v[108:111]
	v_mfma_f32_16x16x32_bf16 v[104:107], v[174:177], v[198:201], v[104:107]
	v_mfma_f32_16x16x32_bf16 v[100:103], v[154:157], v[206:209], v[100:103]
	v_mfma_f32_16x16x32_bf16 v[96:99], v[174:177], v[206:209], v[96:99]
	s_setprio 0
	s_barrier
; #define PG8_STAGE(bufoff, gbase, voff) do { _Pragma("unroll") for (int _i = 0; _i < 2; ++_i) \
;         __builtin_amdgcn_global_load_lds((const unsigned*)((const char*)(gbase) + (voff)[_i]), (PG8_LAS unsigned*)(lds + (bufoff) + ldsw + _i * 8192), 16, 0, 0); } while (0)
; #define PG8_LDA(dst, b, h) do { _Pragma("unroll") for (int m = 0; m < 4; ++m) _Pragma("unroll") for (int k = 0; k < 2; ++k) dst[m][k] = *(const PG8_LAS bf16x8*)(lds + PG8_SA(b, h) + aoff + m * 2048 + k * 1024); } while (0)
; #define PG8_MMA(ai, bj, At, Bt) do { __builtin_amdgcn_s_setprio(1); _Pragma("unroll") for (int m = 0; m < 4; ++m) _Pragma("unroll") for (int n = 0; n < 2; ++n) _Pragma("unroll") for (int k = 0; k < 2; ++k) \
;         acc[ai][bj][m][n] = __builtin_amdgcn_mfma_f32_16x16x32_bf16(Bt[n][k], At[m][k], acc[ai][bj][m][n], 0, 0, 0); __builtin_amdgcn_s_setprio(0); } while (0)
; #define PG8_WAIT_V(n) asm volatile("s_waitcnt vmcnt(" #n ")" ::: "memory")
; #define PG8_WAIT_L(n) asm volatile("s_waitcnt lgkmcnt(" #n ")" ::: "memory")
; #define PG8_BAR __builtin_amdgcn_s_barrier()
; #define PG8_SCHED __builtin_amdgcn_sched_barrier(0)
; template <class Epi, class Sched, bool ALIGN_EPI, bool SP2, int KC>
; __device__ __forceinline__ void gemm_phase(PG8_LAS unsigned char* lds, const Gemm g, const Sched& S, const Epi& E, const int tid) {
;     ...
;             PG8_LDA(At, 1, 1); PG8_STAGE(PG8_SB(1, 0), b3, voffB); PG8_STAGE(PG8_SB(1, 1), b3 + hstep, voffB); PG8_STAGE(PG8_SA(1, 0), a3, voffA);
;             PG8_WAIT_V(8); PG8_WAIT_L(0); PG8_BAR; PG8_MMA(1, 0, At, B0); PG8_MMA(1, 1, At, B1); PG8_BAR; PG8_SCHED;
	s_add_i32 s4, s49, s6
	v_lshl_add_u64 v[162:163], v[162:163], 0, s[86:87]
	s_mov_b32 m0, s4
	ds_read_b128 v[178:181], v216 offset:49152
	ds_read_b128 v[182:185], v216 offset:50176
	ds_read_b128 v[186:189], v216 offset:51200
	ds_read_b128 v[190:193], v216 offset:52224
	ds_read_b128 v[194:197], v216 offset:53248
	ds_read_b128 v[198:201], v216 offset:54272
	ds_read_b128 v[202:205], v216 offset:55296
	ds_read_b128 v[206:209], v216 offset:56320
	global_load_lds_dwordx4 v[162:163], off
	s_add_i32 m0, s4, 0x2000
	s_add_u32 s4, s36, 0xb0080
	v_lshl_add_u64 v[162:163], v[210:211], 0, s[86:87]
	s_addc_u32 s5, s37, 0
	s_add_i32 s36, s58, s6
	global_load_lds_dwordx4 v[162:163], off
	v_lshl_add_u64 v[162:163], s[4:5], 0, v[164:165]
	s_mov_b32 m0, s36
	s_nop 0
	global_load_lds_dwordx4 v[162:163], off
	v_lshl_add_u64 v[162:163], s[4:5], 0, v[136:137]
	s_add_i32 m0, s36, 0x2000
	s_nop 0
	global_load_lds_dwordx4 v[162:163], off
	v_lshl_add_u64 v[162:163], v[220:221], 0, s[86:87]
	s_mov_b32 m0, s43
	s_nop 0
	global_load_lds_dwordx4 v[162:163], off
	v_lshl_add_u64 v[162:163], v[222:223], 0, s[86:87]
	s_mov_b32 m0, s44
	s_nop 0
	global_load_lds_dwordx4 v[162:163], off
	s_waitcnt vmcnt(8)
	s_waitcnt lgkmcnt(0)
	s_barrier
	s_setprio 1
	s_waitcnt lgkmcnt(0)
	v_mfma_f32_16x16x32_bf16 v[88:91], v[128:131], v[178:181], v[88:91]
	v_mfma_f32_16x16x32_bf16 v[52:55], v[142:145], v[178:181], v[52:55]
	v_mfma_f32_16x16x32_bf16 v[76:79], v[128:131], v[186:189], v[76:79]
	v_mfma_f32_16x16x32_bf16 v[44:47], v[142:145], v[186:189], v[44:47]
	s_setprio 0
	s_setprio 1
	v_mfma_f32_16x16x32_bf16 v[68:71], v[128:131], v[194:197], v[68:71]
	v_mfma_f32_16x16x32_bf16 v[36:39], v[142:145], v[194:197], v[36:39]
	v_mfma_f32_16x16x32_bf16 v[64:67], v[128:131], v[202:205], v[64:67]
	v_mfma_f32_16x16x32_bf16 v[32:35], v[142:145], v[202:205], v[32:35]
	s_setprio 0
	s_setprio 1
	v_mfma_f32_16x16x32_bf16 v[88:91], v[132:135], v[182:185], v[88:91]
	v_mfma_f32_16x16x32_bf16 v[52:55], v[146:149], v[182:185], v[52:55]
	v_mfma_f32_16x16x32_bf16 v[76:79], v[132:135], v[190:193], v[76:79]
	v_mfma_f32_16x16x32_bf16 v[44:47], v[146:149], v[190:193], v[44:47]
	s_setprio 0
	s_setprio 1
	v_mfma_f32_16x16x32_bf16 v[68:71], v[132:135], v[198:201], v[68:71]
	v_mfma_f32_16x16x32_bf16 v[36:39], v[146:149], v[198:201], v[36:39]
	v_mfma_f32_16x16x32_bf16 v[64:67], v[132:135], v[206:209], v[64:67]
	v_mfma_f32_16x16x32_bf16 v[32:35], v[146:149], v[206:209], v[32:35]
	s_setprio 0
	s_setprio 1
	v_mfma_f32_16x16x32_bf16 v[28:31], v[150:153], v[178:181], v[28:31]
	v_mfma_f32_16x16x32_bf16 v[12:15], v[158:161], v[178:181], v[12:15]
	v_mfma_f32_16x16x32_bf16 v[24:27], v[150:153], v[186:189], v[24:27]
	v_mfma_f32_16x16x32_bf16 v[8:11], v[158:161], v[186:189], v[8:11]
	s_setprio 0
	s_setprio 1
	v_mfma_f32_16x16x32_bf16 v[20:23], v[150:153], v[194:197], v[20:23]
	v_mfma_f32_16x16x32_bf16 v[4:7], v[158:161], v[194:197], v[4:7]
	v_mfma_f32_16x16x32_bf16 v[16:19], v[150:153], v[202:205], v[16:19]
	v_mfma_f32_16x16x32_bf16 v[0:3], v[158:161], v[202:205], v[0:3]
	s_setprio 0
	s_setprio 1
	v_mfma_f32_16x16x32_bf16 v[28:31], v[154:157], v[182:185], v[28:31]
	v_mfma_f32_16x16x32_bf16 v[12:15], v[174:177], v[182:185], v[12:15]
	v_mfma_f32_16x16x32_bf16 v[24:27], v[154:157], v[190:193], v[24:27]
	v_mfma_f32_16x16x32_bf16 v[8:11], v[174:177], v[190:193], v[8:11]
	s_setprio 0
	s_setprio 1
	v_mfma_f32_16x16x32_bf16 v[20:23], v[154:157], v[198:201], v[20:23]
	v_mfma_f32_16x16x32_bf16 v[4:7], v[174:177], v[198:201], v[4:7]
	v_mfma_f32_16x16x32_bf16 v[16:19], v[154:157], v[206:209], v[16:19]
	v_mfma_f32_16x16x32_bf16 v[0:3], v[174:177], v[206:209], v[0:3]
	s_setprio 0
	s_barrier
	s_add_i32 s48, s48, 2
	s_add_u32 s31, s31, 0x100
	s_addc_u32 s35, s35, 0
	s_cmp_gt_u32 s48, 41
	s_mov_b64 s[4:5], s[16:17]
	s_cbranch_scc0 .LBB0_560
	s_and_b64 vcc, exec, s[24:25]
	s_cbranch_vccz .LBB0_563
	s_barrier

; #define PG8_STAGE(bufoff, gbase, voff) do { _Pragma("unroll") for (int _i = 0; _i < 2; ++_i) \
;         __builtin_amdgcn_global_load_lds((const unsigned*)((const char*)(gbase) + (voff)[_i]), (PG8_LAS unsigned*)(lds + (bufoff) + ldsw + _i * 8192), 16, 0, 0); } while (0)
; #define PG8_LDA(dst, b, h) do { _Pragma("unroll") for (int m = 0; m < 4; ++m) _Pragma("unroll") for (int k = 0; k < 2; ++k) dst[m][k] = *(const PG8_LAS bf16x8*)(lds + PG8_SA(b, h) + aoff + m * 2048 + k * 1024); } while (0)
; #define PG8_LDB(dst, b, h) do { _Pragma("unroll") for (int n = 0; n < 2; ++n) _Pragma("unroll") for (int k = 0; k < 2; ++k) dst[n][k] = *(const PG8_LAS bf16x8*)(lds + PG8_SB(b, h) + boff + n * 2048 + k * 1024); } while (0)
; #define PG8_MMA(ai, bj, At, Bt) do { __builtin_amdgcn_s_setprio(1); _Pragma("unroll") for (int m = 0; m < 4; ++m) _Pragma("unroll") for (int n = 0; n < 2; ++n) _Pragma("unroll") for (int k = 0; k < 2; ++k) \
;         acc[ai][bj][m][n] = __builtin_amdgcn_mfma_f32_16x16x32_bf16(Bt[n][k], At[m][k], acc[ai][bj][m][n], 0, 0, 0); __builtin_amdgcn_s_setprio(0); } while (0)
; #define PG8_WAIT_V(n) asm volatile("s_waitcnt vmcnt(" #n ")" ::: "memory")
; #define PG8_WAIT_L(n) asm volatile("s_waitcnt lgkmcnt(" #n ")" ::: "memory")
; #define PG8_BAR __builtin_amdgcn_s_barrier()
; template <class Epi, class Sched, bool ALIGN_EPI, bool SP2, int KC>
; __device__ __forceinline__ void gemm_phase(PG8_LAS unsigned char* lds, const Gemm g, const Sched& S, const Epi& E, const int tid) {
;     ...
;             const char* a1 = cA + (size_t)(t + 1) * kstep;
;             const char* a2 = last ? nA : cA + (size_t)(t + 2) * kstep; const char* b2 = last ? nB : cB + (size_t)(t + 2) * kstep;
;             const char* a3 = a2 + kstep; const char* b3 = b2 + kstep;
;             if (last && has_next) S.a_ready(nxt);
;             if constexpr (SP2) {
;             PG8_LDB(B0, 0, 0); PG8_LDB(B1, 0, 1); PG8_SCHED; PG8_LDA(At, 0, 0); PG8_STAGE(PG8_SA(1, 1), a1 + hstep, voffA);
;             PG8_WAIT_V(8); PG8_WAIT_L(0); PG8_BAR; PG8_MMA(0, 0, At, B0); PG8_MMA(0, 1, At, B1); PG8_BAR; PG8_SCHED;
;             PG8_LDA(At, 0, 1); PG8_STAGE(PG8_SB(0, 0), b2, voffB); PG8_STAGE(PG8_SB(0, 1), b2 + hstep, voffB); PG8_STAGE(PG8_SA(0, 0), a2, voffA);
;             PG8_WAIT_V(8); PG8_WAIT_L(0); PG8_BAR; PG8_MMA(1, 0, At, B0); PG8_MMA(1, 1, At, B1); PG8_BAR; PG8_SCHED;
.LBB0_730:
	s_add_u32 s22, s4, 0xfffc0080
	s_addc_u32 s23, s5, -1
	s_add_i32 s41, 0, 0x10000
	s_cmp_eq_u32 s40, 12
	s_cselect_b32 s25, s17, s23
	s_cselect_b32 s24, s36, s22
	s_cselect_b32 s23, s15, s39
	s_cselect_b32 s22, s37, s38
	s_add_i32 s44, 0, 0x14000
	v_add_u32_e32 v140, s41, v223
	v_add_u32_e32 v156, s44, v223
	ds_read_b128 v[128:131], v140
	ds_read_b128 v[132:135], v140 offset:1024
	ds_read_b128 v[136:139], v140 offset:2048
	ds_read_b128 v[140:143], v140 offset:3072
	ds_read_b128 v[144:147], v156
	ds_read_b128 v[148:151], v156 offset:1024
	ds_read_b128 v[152:155], v156 offset:2048
	ds_read_b128 v[156:159], v156 offset:3072
	v_lshl_add_u64 v[214:215], s[4:5], 0, v[182:183]
	s_add_i32 m0, s7, 0xc000
	ds_read_b128 v[160:163], v234
	s_waitcnt vmcnt(0)
	ds_read_b128 v[186:189], v234 offset:1024
	ds_read_b128 v[190:193], v234 offset:2048
	ds_read_b128 v[194:197], v234 offset:3072
	ds_read_b128 v[198:201], v234 offset:4096
	ds_read_b128 v[202:205], v234 offset:5120
	ds_read_b128 v[206:209], v234 offset:6144
	ds_read_b128 v[210:213], v234 offset:7168
	global_load_lds_dwordx4 v[214:215], off
	v_lshl_add_u64 v[214:215], s[4:5], 0, v[184:185]
	s_add_i32 m0, s7, 0xe000
	s_nop 0
	global_load_lds_dwordx4 v[214:215], off
	s_waitcnt vmcnt(8)
	s_waitcnt lgkmcnt(0)
	s_barrier
	s_setprio 1
	s_waitcnt lgkmcnt(0)
	v_mfma_f32_16x16x32_bf16 v[124:127], v[128:131], v[160:163], v[124:127]
	v_mfma_f32_16x16x32_bf16 v[120:123], v[136:139], v[160:163], v[120:123]
	v_mfma_f32_16x16x32_bf16 v[116:119], v[128:131], v[190:193], v[116:119]
	v_mfma_f32_16x16x32_bf16 v[112:115], v[136:139], v[190:193], v[112:115]
	s_setprio 0
	s_setprio 1
	v_mfma_f32_16x16x32_bf16 v[108:111], v[128:131], v[198:201], v[108:111]
	v_mfma_f32_16x16x32_bf16 v[104:107], v[136:139], v[198:201], v[104:107]
	v_mfma_f32_16x16x32_bf16 v[100:103], v[128:131], v[206:209], v[100:103]
	v_mfma_f32_16x16x32_bf16 v[96:99], v[136:139], v[206:209], v[96:99]
	s_setprio 0
	s_setprio 1
	v_mfma_f32_16x16x32_bf16 v[124:127], v[132:135], v[186:189], v[124:127]
	v_mfma_f32_16x16x32_bf16 v[120:123], v[140:143], v[186:189], v[120:123]
	v_mfma_f32_16x16x32_bf16 v[116:119], v[132:135], v[194:197], v[116:119]
	v_mfma_f32_16x16x32_bf16 v[112:115], v[140:143], v[194:197], v[112:115]
	s_setprio 0
	s_setprio 1
	v_mfma_f32_16x16x32_bf16 v[108:111], v[132:135], v[202:205], v[108:111]
	v_mfma_f32_16x16x32_bf16 v[104:107], v[140:143], v[202:205], v[104:107]
	v_mfma_f32_16x16x32_bf16 v[100:103], v[132:135], v[210:213], v[100:103]
	v_mfma_f32_16x16x32_bf16 v[96:99], v[140:143], v[210:213], v[96:99]
	s_setprio 0
	s_setprio 1
	v_mfma_f32_16x16x32_bf16 v[68:71], v[144:147], v[160:163], v[68:71]
	v_mfma_f32_16x16x32_bf16 v[56:59], v[152:155], v[160:163], v[56:59]
	v_mfma_f32_16x16x32_bf16 v[52:55], v[144:147], v[190:193], v[52:55]
	v_mfma_f32_16x16x32_bf16 v[48:51], v[152:155], v[190:193], v[48:51]
	s_setprio 0
	s_setprio 1
	v_mfma_f32_16x16x32_bf16 v[44:47], v[144:147], v[198:201], v[44:47]
	v_mfma_f32_16x16x32_bf16 v[40:43], v[152:155], v[198:201], v[40:43]
	v_mfma_f32_16x16x32_bf16 v[36:39], v[144:147], v[206:209], v[36:39]
	v_mfma_f32_16x16x32_bf16 v[32:35], v[152:155], v[206:209], v[32:35]
	s_setprio 0
	s_setprio 1
	v_mfma_f32_16x16x32_bf16 v[68:71], v[148:151], v[186:189], v[68:71]
	v_mfma_f32_16x16x32_bf16 v[56:59], v[156:159], v[186:189], v[56:59]
	v_mfma_f32_16x16x32_bf16 v[52:55], v[148:151], v[194:197], v[52:55]
	v_mfma_f32_16x16x32_bf16 v[48:51], v[156:159], v[194:197], v[48:51]
	s_setprio 0
	s_setprio 1
	v_mfma_f32_16x16x32_bf16 v[44:47], v[148:151], v[202:205], v[44:47]
	v_mfma_f32_16x16x32_bf16 v[40:43], v[156:159], v[202:205], v[40:43]
	v_mfma_f32_16x16x32_bf16 v[36:39], v[148:151], v[210:213], v[36:39]
	v_mfma_f32_16x16x32_bf16 v[32:35], v[156:159], v[210:213], v[32:35]
	s_setprio 0
	s_barrier
	s_add_i32 s41, s41, s6
	v_lshl_add_u64 v[214:215], s[22:23], 0, v[178:179]
	s_mov_b32 m0, s41
	ds_read_b128 v[160:163], v234 offset:16384
	ds_read_b128 v[186:189], v234 offset:17408
	ds_read_b128 v[190:193], v234 offset:18432
	ds_read_b128 v[194:197], v234 offset:19456
	ds_read_b128 v[198:201], v234 offset:20480
	ds_read_b128 v[202:205], v234 offset:21504
	ds_read_b128 v[206:209], v234 offset:22528
	ds_read_b128 v[210:213], v234 offset:23552
	global_load_lds_dwordx4 v[214:215], off
	s_add_i32 m0, s41, 0x2000
	s_add_u32 s42, s22, 0x40000
	v_lshl_add_u64 v[216:217], s[22:23], 0, v[174:175]
	s_addc_u32 s43, s23, 0
	s_add_i32 s41, s44, s6
	global_load_lds_dwordx4 v[216:217], off
	v_lshl_add_u64 v[218:219], s[42:43], 0, v[178:179]
	s_mov_b32 m0, s41
	v_lshl_add_u64 v[220:221], s[24:25], 0, v[176:177]
	global_load_lds_dwordx4 v[218:219], off
	v_lshl_add_u64 v[218:219], s[42:43], 0, v[174:175]
	s_add_i32 m0, s41, 0x2000
	s_nop 0
	global_load_lds_dwordx4 v[218:219], off
	v_lshl_add_u64 v[218:219], s[24:25], 0, v[180:181]
	s_mov_b32 m0, s7
	s_nop 0
	global_load_lds_dwordx4 v[218:219], off
	s_mov_b32 m0, s26
	s_nop 0
	global_load_lds_dwordx4 v[220:221], off
	s_waitcnt vmcnt(8)
	s_waitcnt lgkmcnt(0)
	s_barrier
; #define PG8_STAGE(bufoff, gbase, voff) do { _Pragma("unroll") for (int _i = 0; _i < 2; ++_i) \
;         __builtin_amdgcn_global_load_lds((const unsigned*)((const char*)(gbase) + (voff)[_i]), (PG8_LAS unsigned*)(lds + (bufoff) + ldsw + _i * 8192), 16, 0, 0); } while (0)
; #define PG8_LDA(dst, b, h) do { _Pragma("unroll") for (int m = 0; m < 4; ++m) _Pragma("unroll") for (int k = 0; k < 2; ++k) dst[m][k] = *(const PG8_LAS bf16x8*)(lds + PG8_SA(b, h) + aoff + m * 2048 + k * 1024); } while (0)
; #define PG8_LDB(dst, b, h) do { _Pragma("unroll") for (int n = 0; n < 2; ++n) _Pragma("unroll") for (int k = 0; k < 2; ++k) dst[n][k] = *(const PG8_LAS bf16x8*)(lds + PG8_SB(b, h) + boff + n * 2048 + k * 1024); } while (0)
; #define PG8_MMA(ai, bj, At, Bt) do { __builtin_amdgcn_s_setprio(1); _Pragma("unroll") for (int m = 0; m < 4; ++m) _Pragma("unroll") for (int n = 0; n < 2; ++n) _Pragma("unroll") for (int k = 0; k < 2; ++k) \
;         acc[ai][bj][m][n] = __builtin_amdgcn_mfma_f32_16x16x32_bf16(Bt[n][k], At[m][k], acc[ai][bj][m][n], 0, 0, 0); __builtin_amdgcn_s_setprio(0); } while (0)
; #define PG8_WAIT_V(n) asm volatile("s_waitcnt vmcnt(" #n ")" ::: "memory")
; #define PG8_WAIT_L(n) asm volatile("s_waitcnt lgkmcnt(" #n ")" ::: "memory")
; #define PG8_BAR __builtin_amdgcn_s_barrier()
; #define PG8_SCHED __builtin_amdgcn_sched_barrier(0)
; template <class Epi, class Sched, bool ALIGN_EPI, bool SP2, int KC>
; __device__ __forceinline__ void gemm_phase(PG8_LAS unsigned char* lds, const Gemm g, const Sched& S, const Epi& E, const int tid) {
;     ...
;             PG8_WAIT_V(8); PG8_WAIT_L(0); PG8_BAR; PG8_MMA(1, 0, At, B0); PG8_MMA(1, 1, At, B1); PG8_BAR; PG8_SCHED;
;             PG8_LDB(B0, 1, 0); PG8_LDB(B1, 1, 1); PG8_SCHED; PG8_LDA(At, 1, 0); PG8_STAGE(PG8_SA(0, 1), a2 + hstep, voffA);
;             PG8_WAIT_V(8); PG8_WAIT_L(0); PG8_BAR; PG8_MMA(0, 0, At, B0); PG8_MMA(0, 1, At, B1); PG8_BAR; PG8_SCHED;
	s_setprio 1
	s_waitcnt lgkmcnt(0)
	v_mfma_f32_16x16x32_bf16 v[92:95], v[128:131], v[160:163], v[92:95]
	v_mfma_f32_16x16x32_bf16 v[88:91], v[136:139], v[160:163], v[88:91]
	v_mfma_f32_16x16x32_bf16 v[84:87], v[128:131], v[190:193], v[84:87]
	v_mfma_f32_16x16x32_bf16 v[80:83], v[136:139], v[190:193], v[80:83]
	s_setprio 0
	s_setprio 1
	v_mfma_f32_16x16x32_bf16 v[76:79], v[128:131], v[198:201], v[76:79]
	v_mfma_f32_16x16x32_bf16 v[72:75], v[136:139], v[198:201], v[72:75]
	v_mfma_f32_16x16x32_bf16 v[64:67], v[128:131], v[206:209], v[64:67]
	v_mfma_f32_16x16x32_bf16 v[60:63], v[136:139], v[206:209], v[60:63]
	s_setprio 0
	s_setprio 1
	v_mfma_f32_16x16x32_bf16 v[92:95], v[132:135], v[186:189], v[92:95]
	v_mfma_f32_16x16x32_bf16 v[88:91], v[140:143], v[186:189], v[88:91]
	v_mfma_f32_16x16x32_bf16 v[84:87], v[132:135], v[194:197], v[84:87]
	v_mfma_f32_16x16x32_bf16 v[80:83], v[140:143], v[194:197], v[80:83]
	s_setprio 0
	s_setprio 1
	v_mfma_f32_16x16x32_bf16 v[76:79], v[132:135], v[202:205], v[76:79]
	v_mfma_f32_16x16x32_bf16 v[72:75], v[140:143], v[202:205], v[72:75]
	v_mfma_f32_16x16x32_bf16 v[64:67], v[132:135], v[210:213], v[64:67]
	v_mfma_f32_16x16x32_bf16 v[60:63], v[140:143], v[210:213], v[60:63]
	s_setprio 0
	s_setprio 1
	v_mfma_f32_16x16x32_bf16 v[28:31], v[144:147], v[160:163], v[28:31]
	v_mfma_f32_16x16x32_bf16 v[24:27], v[152:155], v[160:163], v[24:27]
	v_mfma_f32_16x16x32_bf16 v[20:23], v[144:147], v[190:193], v[20:23]
	v_mfma_f32_16x16x32_bf16 v[16:19], v[152:155], v[190:193], v[16:19]
	s_setprio 0
	s_setprio 1
	v_mfma_f32_16x16x32_bf16 v[12:15], v[144:147], v[198:201], v[12:15]
	v_mfma_f32_16x16x32_bf16 v[8:11], v[152:155], v[198:201], v[8:11]
	v_mfma_f32_16x16x32_bf16 v[4:7], v[144:147], v[206:209], v[4:7]
	v_mfma_f32_16x16x32_bf16 v[0:3], v[152:155], v[206:209], v[0:3]
	s_setprio 0
	s_setprio 1
	v_mfma_f32_16x16x32_bf16 v[28:31], v[148:151], v[186:189], v[28:31]
	v_mfma_f32_16x16x32_bf16 v[24:27], v[156:159], v[186:189], v[24:27]
	v_mfma_f32_16x16x32_bf16 v[20:23], v[148:151], v[194:197], v[20:23]
	v_mfma_f32_16x16x32_bf16 v[16:19], v[156:159], v[194:197], v[16:19]
	s_setprio 0
	s_setprio 1
	v_mfma_f32_16x16x32_bf16 v[12:15], v[148:151], v[202:205], v[12:15]
	v_mfma_f32_16x16x32_bf16 v[8:11], v[156:159], v[202:205], v[8:11]
	v_mfma_f32_16x16x32_bf16 v[4:7], v[148:151], v[210:213], v[4:7]
	v_mfma_f32_16x16x32_bf16 v[0:3], v[156:159], v[210:213], v[0:3]
	s_setprio 0
	s_barrier
	s_add_i32 s41, 0, 0x18000
	s_add_i32 s42, 0, 0x1c000
	v_add_u32_e32 v140, s41, v223
	v_add_u32_e32 v156, s42, v223
	ds_read_b128 v[128:131], v140
	ds_read_b128 v[132:135], v140 offset:1024
	ds_read_b128 v[136:139], v140 offset:2048
	ds_read_b128 v[140:143], v140 offset:3072
	ds_read_b128 v[144:147], v156
	ds_read_b128 v[148:151], v156 offset:1024
	ds_read_b128 v[152:155], v156 offset:2048
	ds_read_b128 v[156:159], v156 offset:3072
	s_add_u32 s24, s24, 0x40000
	s_addc_u32 s25, s25, 0
	s_mov_b32 m0, s27
	v_lshl_add_u64 v[236:237], s[24:25], 0, v[180:181]
	ds_read_b128 v[160:163], v234 offset:32768
	ds_read_b128 v[186:189], v234 offset:33792
	ds_read_b128 v[190:193], v234 offset:34816
	ds_read_b128 v[194:197], v234 offset:35840
	ds_read_b128 v[198:201], v234 offset:36864
	ds_read_b128 v[202:205], v234 offset:37888
	ds_read_b128 v[206:209], v234 offset:38912
	ds_read_b128 v[210:213], v234 offset:39936
	global_load_lds_dwordx4 v[236:237], off
	v_lshl_add_u64 v[236:237], s[24:25], 0, v[176:177]
	s_mov_b32 m0, s28
	s_nop 0
	global_load_lds_dwordx4 v[236:237], off
	s_waitcnt vmcnt(8)
	s_waitcnt lgkmcnt(0)
	s_barrier
	s_setprio 1
	s_waitcnt lgkmcnt(0)
	v_mfma_f32_16x16x32_bf16 v[124:127], v[128:131], v[160:163], v[124:127]
	v_mfma_f32_16x16x32_bf16 v[120:123], v[136:139], v[160:163], v[120:123]
	v_mfma_f32_16x16x32_bf16 v[116:119], v[128:131], v[190:193], v[116:119]
	v_mfma_f32_16x16x32_bf16 v[112:115], v[136:139], v[190:193], v[112:115]
	s_setprio 0
	s_setprio 1
	v_mfma_f32_16x16x32_bf16 v[108:111], v[128:131], v[198:201], v[108:111]
	v_mfma_f32_16x16x32_bf16 v[104:107], v[136:139], v[198:201], v[104:107]
	v_mfma_f32_16x16x32_bf16 v[100:103], v[128:131], v[206:209], v[100:103]
	v_mfma_f32_16x16x32_bf16 v[96:99], v[136:139], v[206:209], v[96:99]
	s_setprio 0
	s_setprio 1
	v_mfma_f32_16x16x32_bf16 v[124:127], v[132:135], v[186:189], v[124:127]
	v_mfma_f32_16x16x32_bf16 v[120:123], v[140:143], v[186:189], v[120:123]
	v_mfma_f32_16x16x32_bf16 v[116:119], v[132:135], v[194:197], v[116:119]
	v_mfma_f32_16x16x32_bf16 v[112:115], v[140:143], v[194:197], v[112:115]
	s_setprio 0
	s_setprio 1
	v_mfma_f32_16x16x32_bf16 v[108:111], v[132:135], v[202:205], v[108:111]
	v_mfma_f32_16x16x32_bf16 v[104:107], v[140:143], v[202:205], v[104:107]
	v_mfma_f32_16x16x32_bf16 v[100:103], v[132:135], v[210:213], v[100:103]
	v_mfma_f32_16x16x32_bf16 v[96:99], v[140:143], v[210:213], v[96:99]
	s_setprio 0
	s_setprio 1
	v_mfma_f32_16x16x32_bf16 v[68:71], v[144:147], v[160:163], v[68:71]
	v_mfma_f32_16x16x32_bf16 v[56:59], v[152:155], v[160:163], v[56:59]
	v_mfma_f32_16x16x32_bf16 v[52:55], v[144:147], v[190:193], v[52:55]
	v_mfma_f32_16x16x32_bf16 v[48:51], v[152:155], v[190:193], v[48:51]
	s_setprio 0
	s_setprio 1
	v_mfma_f32_16x16x32_bf16 v[44:47], v[144:147], v[198:201], v[44:47]
	v_mfma_f32_16x16x32_bf16 v[40:43], v[152:155], v[198:201], v[40:43]
	v_mfma_f32_16x16x32_bf16 v[36:39], v[144:147], v[206:209], v[36:39]
	v_mfma_f32_16x16x32_bf16 v[32:35], v[152:155], v[206:209], v[32:35]
	s_setprio 0
	s_setprio 1
	v_mfma_f32_16x16x32_bf16 v[68:71], v[148:151], v[186:189], v[68:71]
	v_mfma_f32_16x16x32_bf16 v[56:59], v[156:159], v[186:189], v[56:59]
	v_mfma_f32_16x16x32_bf16 v[52:55], v[148:151], v[194:197], v[52:55]
	v_mfma_f32_16x16x32_bf16 v[48:51], v[156:159], v[194:197], v[48:51]
	s_setprio 0
	s_setprio 1
	v_mfma_f32_16x16x32_bf16 v[44:47], v[148:151], v[202:205], v[44:47]
	v_mfma_f32_16x16x32_bf16 v[40:43], v[156:159], v[202:205], v[40:43]
	v_mfma_f32_16x16x32_bf16 v[36:39], v[148:151], v[210:213], v[36:39]
	v_mfma_f32_16x16x32_bf16 v[32:35], v[156:159], v[210:213], v[32:35]
	s_setprio 0
	s_barrier
; #define PG8_STAGE(bufoff, gbase, voff) do { _Pragma("unroll") for (int _i = 0; _i < 2; ++_i) \
;         __builtin_amdgcn_global_load_lds((const unsigned*)((const char*)(gbase) + (voff)[_i]), (PG8_LAS unsigned*)(lds + (bufoff) + ldsw + _i * 8192), 16, 0, 0); } while (0)
; #define PG8_LDA(dst, b, h) do { _Pragma("unroll") for (int m = 0; m < 4; ++m) _Pragma("unroll") for (int k = 0; k < 2; ++k) dst[m][k] = *(const PG8_LAS bf16x8*)(lds + PG8_SA(b, h) + aoff + m * 2048 + k * 1024); } while (0)
; #define PG8_MMA(ai, bj, At, Bt) do { __builtin_amdgcn_s_setprio(1); _Pragma("unroll") for (int m = 0; m < 4; ++m) _Pragma("unroll") for (int n = 0; n < 2; ++n) _Pragma("unroll") for (int k = 0; k < 2; ++k) \
;         acc[ai][bj][m][n] = __builtin_amdgcn_mfma_f32_16x16x32_bf16(Bt[n][k], At[m][k], acc[ai][bj][m][n], 0, 0, 0); __builtin_amdgcn_s_setprio(0); } while (0)
; #define PG8_WAIT_V(n) asm volatile("s_waitcnt vmcnt(" #n ")" ::: "memory")
; #define PG8_WAIT_L(n) asm volatile("s_waitcnt lgkmcnt(" #n ")" ::: "memory")
; #define PG8_BAR __builtin_amdgcn_s_barrier()
; #define PG8_SCHED __builtin_amdgcn_sched_barrier(0)
; template <class Epi, class Sched, bool ALIGN_EPI, bool SP2, int KC>
; __device__ __forceinline__ void gemm_phase(PG8_LAS unsigned char* lds, const Gemm g, const Sched& S, const Epi& E, const int tid) {
;     ...
;             PG8_LDA(At, 1, 1); PG8_STAGE(PG8_SB(1, 0), b3, voffB); PG8_STAGE(PG8_SB(1, 1), b3 + hstep, voffB); PG8_STAGE(PG8_SA(1, 0), a3, voffA);
;             PG8_WAIT_V(8); PG8_WAIT_L(0); PG8_BAR; PG8_MMA(1, 0, At, B0); PG8_MMA(1, 1, At, B1); PG8_BAR; PG8_SCHED;
	s_add_i32 s24, s41, s6
	v_lshl_add_u64 v[214:215], v[214:215], 0, s[86:87]
	s_mov_b32 m0, s24
	ds_read_b128 v[160:163], v234 offset:49152
	ds_read_b128 v[186:189], v234 offset:50176
	ds_read_b128 v[190:193], v234 offset:51200
	ds_read_b128 v[194:197], v234 offset:52224
	ds_read_b128 v[198:201], v234 offset:53248
	ds_read_b128 v[202:205], v234 offset:54272
	ds_read_b128 v[206:209], v234 offset:55296
	ds_read_b128 v[210:213], v234 offset:56320
	global_load_lds_dwordx4 v[214:215], off
	s_add_i32 m0, s24, 0x2000
	s_add_u32 s22, s22, 0x40080
	v_lshl_add_u64 v[214:215], v[216:217], 0, s[86:87]
	s_addc_u32 s23, s23, 0
	s_add_i32 s24, s42, s6
	global_load_lds_dwordx4 v[214:215], off
	v_lshl_add_u64 v[214:215], s[22:23], 0, v[178:179]
	s_mov_b32 m0, s24
	s_nop 0
	global_load_lds_dwordx4 v[214:215], off
	v_lshl_add_u64 v[214:215], s[22:23], 0, v[174:175]
	s_add_i32 m0, s24, 0x2000
	s_nop 0
	global_load_lds_dwordx4 v[214:215], off
	v_lshl_add_u64 v[214:215], v[218:219], 0, s[86:87]
	s_mov_b32 m0, s29
	s_nop 0
	global_load_lds_dwordx4 v[214:215], off
	v_lshl_add_u64 v[214:215], v[220:221], 0, s[86:87]
	s_mov_b32 m0, s30
	s_nop 0
	global_load_lds_dwordx4 v[214:215], off
	s_waitcnt vmcnt(8)
	s_waitcnt lgkmcnt(0)
	s_barrier
	s_setprio 1
	s_waitcnt lgkmcnt(0)
	v_mfma_f32_16x16x32_bf16 v[92:95], v[128:131], v[160:163], v[92:95]
	v_mfma_f32_16x16x32_bf16 v[88:91], v[136:139], v[160:163], v[88:91]
	v_mfma_f32_16x16x32_bf16 v[84:87], v[128:131], v[190:193], v[84:87]
	v_mfma_f32_16x16x32_bf16 v[80:83], v[136:139], v[190:193], v[80:83]
	s_setprio 0
	s_setprio 1
	v_mfma_f32_16x16x32_bf16 v[76:79], v[128:131], v[198:201], v[76:79]
	v_mfma_f32_16x16x32_bf16 v[72:75], v[136:139], v[198:201], v[72:75]
	v_mfma_f32_16x16x32_bf16 v[64:67], v[128:131], v[206:209], v[64:67]
	v_mfma_f32_16x16x32_bf16 v[60:63], v[136:139], v[206:209], v[60:63]
	s_setprio 0
	s_setprio 1
	v_mfma_f32_16x16x32_bf16 v[92:95], v[132:135], v[186:189], v[92:95]
	v_mfma_f32_16x16x32_bf16 v[88:91], v[140:143], v[186:189], v[88:91]
	v_mfma_f32_16x16x32_bf16 v[84:87], v[132:135], v[194:197], v[84:87]
	v_mfma_f32_16x16x32_bf16 v[80:83], v[140:143], v[194:197], v[80:83]
	s_setprio 0
	s_setprio 1
	v_mfma_f32_16x16x32_bf16 v[76:79], v[132:135], v[202:205], v[76:79]
	v_mfma_f32_16x16x32_bf16 v[72:75], v[140:143], v[202:205], v[72:75]
	v_mfma_f32_16x16x32_bf16 v[64:67], v[132:135], v[210:213], v[64:67]
	v_mfma_f32_16x16x32_bf16 v[60:63], v[140:143], v[210:213], v[60:63]
	s_setprio 0
	s_setprio 1
	v_mfma_f32_16x16x32_bf16 v[28:31], v[144:147], v[160:163], v[28:31]
	v_mfma_f32_16x16x32_bf16 v[24:27], v[152:155], v[160:163], v[24:27]
	v_mfma_f32_16x16x32_bf16 v[20:23], v[144:147], v[190:193], v[20:23]
	v_mfma_f32_16x16x32_bf16 v[16:19], v[152:155], v[190:193], v[16:19]
	s_setprio 0
	s_setprio 1
	v_mfma_f32_16x16x32_bf16 v[12:15], v[144:147], v[198:201], v[12:15]
	v_mfma_f32_16x16x32_bf16 v[8:11], v[152:155], v[198:201], v[8:11]
	v_mfma_f32_16x16x32_bf16 v[4:7], v[144:147], v[206:209], v[4:7]
	v_mfma_f32_16x16x32_bf16 v[0:3], v[152:155], v[206:209], v[0:3]
	s_setprio 0
	s_setprio 1
	v_mfma_f32_16x16x32_bf16 v[28:31], v[148:151], v[186:189], v[28:31]
	v_mfma_f32_16x16x32_bf16 v[24:27], v[156:159], v[186:189], v[24:27]
	v_mfma_f32_16x16x32_bf16 v[20:23], v[148:151], v[194:197], v[20:23]
	v_mfma_f32_16x16x32_bf16 v[16:19], v[156:159], v[194:197], v[16:19]
	s_setprio 0
	s_setprio 1
	v_mfma_f32_16x16x32_bf16 v[12:15], v[148:151], v[202:205], v[12:15]
	v_mfma_f32_16x16x32_bf16 v[8:11], v[156:159], v[202:205], v[8:11]
	v_mfma_f32_16x16x32_bf16 v[4:7], v[148:151], v[210:213], v[4:7]
	v_mfma_f32_16x16x32_bf16 v[0:3], v[156:159], v[210:213], v[0:3]
	s_setprio 0
	s_barrier
	s_add_i32 s40, s40, 2
	s_add_u32 s4, s4, 0x100
	s_addc_u32 s5, s5, 0
	s_add_u32 s38, s38, 0x100
	s_addc_u32 s39, s39, 0
	s_cmp_gt_u32 s40, 13
	s_cbranch_scc0 .LBB0_730
	s_and_b64 vcc, exec, s[12:13]
	s_cbranch_vccz .LBB0_733
	s_barrier
